# v24 + load segment's lgkmcnt(0) wait moved behind the pre-MMA barrier (LDS read tail overlaps the barrier latency)
# speedup vs baseline: 1.0066x; 1.0018x over previous
; #define PG8_WAIT_V(n) asm volatile("s_waitcnt vmcnt(" #n ")" ::: "memory")
; #define PG8_BAR __builtin_amdgcn_s_barrier()
; template <class Epi, bool ALIGN_EPI, bool SP2, class Hook>
; __device__ __forceinline__ void gemm_phase(LAS unsigned char* lds, const Gemm g, const StaticOrder& S, const Epi& E, Acc& acc, const bool fresh, const Hook& H, const int wave_id) {
;     ...
;         if (reset) {
; #pragma unroll
;             for (int a = 0; a < 2; ++a)
; #pragma unroll
;                 for (int b = 0; b < 2; ++b)
; #pragma unroll
;                     for (int m = 0; m < 4; ++m)
; #pragma unroll
;                         for (int n = 0; n < 2; ++n) acc[a][b][m][n] = (f32x4){0.f, 0.f, 0.f, 0.f};
;         }
;         cur = nxt; cA = nA; cB = nB; ++ui;
;         if constexpr (ALIGN_EPI) { if (wr == 1) PG8_BAR; }
;         if constexpr (SP2 && Epi::NSTORE > 0) {
;             const Src a1 = cA + kstep, a2 = cA + 2 * kstep, b2 = cB + 2 * kstep, a3 = a2 + kstep, b3 = b2 + kstep;
;             if constexpr (Epi::NSTORE == 16) PG8_TRIP_SP2(PG8_WAIT_V(24)); else PG8_TRIP_SP2(PG8_WAIT_V(16));
;             t0 = 2;
;         }
.LBB0_382:
	ds_read_b128 v[2:5], v150
	ds_read_b128 v[6:9], v150 offset:1024
	ds_read_b128 v[10:13], v150 offset:2048
	ds_read_b128 v[14:17], v150 offset:3072
	ds_read_b128 v[18:21], v151
	ds_read_b128 v[22:25], v151 offset:1024
	ds_read_b128 v[26:29], v151 offset:2048
	ds_read_b128 v[30:33], v151 offset:3072
	s_or_b32 s9, s68, 0x100
	s_or_b32 s8, s68, 0x180
	s_or_b32 s10, s69, 0x100
	s_or_b32 s11, s68, 0x40080
	s_mov_b32 m0, s45
	ds_read_b128 v[34:37], v149
	ds_read_b128 v[38:41], v149 offset:1024
	ds_read_b128 v[42:45], v149 offset:2048
	ds_read_b128 v[46:49], v149 offset:3072
	ds_read_b128 v[50:53], v149 offset:4096
	ds_read_b128 v[54:57], v149 offset:5120
	ds_read_b128 v[58:61], v149 offset:6144
	ds_read_b128 v[62:65], v149 offset:7168
	buffer_load_dwordx4 v144, s[0:3], s11 offen lds
	s_mov_b32 m0, s46
	s_nop 0
	buffer_load_dwordx4 v146, s[0:3], s11 offen lds
	s_waitcnt vmcnt(24)
	s_setprio 1
	s_barrier
	s_waitcnt lgkmcnt(0)
	v_mfma_f32_16x16x32_bf16 v[86:89], v[10:13], v[50:53], 0
	v_mfma_f32_16x16x32_bf16 v[92:95], v[14:17], v[54:57], v[86:89]
	v_mfma_f32_16x16x32_bf16 v[86:89], v[2:5], v[58:61], 0
	v_mfma_f32_16x16x32_bf16 v[66:69], v[2:5], v[34:37], 0
	v_mfma_f32_16x16x32_bf16 v[70:73], v[10:13], v[34:37], 0
	v_mfma_f32_16x16x32_bf16 v[74:77], v[2:5], v[42:45], 0
	v_mfma_f32_16x16x32_bf16 v[78:81], v[10:13], v[42:45], 0
	v_mfma_f32_16x16x32_bf16 v[82:85], v[2:5], v[50:53], 0
	v_mfma_f32_16x16x32_bf16 v[96:99], v[6:9], v[62:65], v[86:89]
	v_mfma_f32_16x16x32_bf16 v[86:89], v[10:13], v[58:61], 0
	v_mfma_f32_16x16x32_bf16 v[66:69], v[6:9], v[38:41], v[66:69]
	v_mfma_f32_16x16x32_bf16 v[70:73], v[14:17], v[38:41], v[70:73]
	v_mfma_f32_16x16x32_bf16 v[74:77], v[6:9], v[46:49], v[74:77]
	v_mfma_f32_16x16x32_bf16 v[78:81], v[14:17], v[46:49], v[78:81]
	v_mfma_f32_16x16x32_bf16 v[82:85], v[6:9], v[54:57], v[82:85]
	v_mfma_f32_16x16x32_bf16 v[104:107], v[14:17], v[62:65], v[86:89]
	v_mfma_f32_16x16x32_bf16 v[86:89], v[18:21], v[34:37], 0
	v_mfma_f32_16x16x32_bf16 v[34:37], v[26:29], v[34:37], 0
	v_mfma_f32_16x16x32_bf16 v[116:119], v[30:33], v[38:41], v[34:37]
	v_mfma_f32_16x16x32_bf16 v[34:37], v[18:21], v[42:45], 0
	v_mfma_f32_16x16x32_bf16 v[132:135], v[22:25], v[46:49], v[34:37]
	v_mfma_f32_16x16x32_bf16 v[34:37], v[26:29], v[42:45], 0
	v_mfma_f32_16x16x32_bf16 v[108:111], v[22:25], v[38:41], v[86:89]
	v_mfma_f32_16x16x32_bf16 v[40:43], v[30:33], v[46:49], v[34:37]
	v_mfma_f32_16x16x32_bf16 v[34:37], v[18:21], v[50:53], 0
	v_mfma_f32_16x16x32_bf16 v[44:47], v[22:25], v[54:57], v[34:37]
	v_mfma_f32_16x16x32_bf16 v[34:37], v[26:29], v[50:53], 0
	v_mfma_f32_16x16x32_bf16 v[48:51], v[30:33], v[54:57], v[34:37]
	v_mfma_f32_16x16x32_bf16 v[34:37], v[18:21], v[58:61], 0
	v_mfma_f32_16x16x32_bf16 v[52:55], v[22:25], v[62:65], v[34:37]
	v_mfma_f32_16x16x32_bf16 v[34:37], v[26:29], v[58:61], 0
	v_mfma_f32_16x16x32_bf16 v[60:63], v[30:33], v[62:65], v[34:37]
	s_barrier
	s_setprio 0
	s_mov_b32 m0, s92
	s_nop 3
	ds_read_b128 v[34:37], v149 offset:16384
	ds_read_b128 v[56:59], v149 offset:17408
	ds_read_b128 v[86:89], v149 offset:18432
	ds_read_b128 v[100:103], v149 offset:19456
	ds_read_b128 v[112:115], v149 offset:20480
	ds_read_b128 v[120:123], v149 offset:21504
	ds_read_b128 v[124:127], v149 offset:22528
	ds_read_b128 v[128:131], v149 offset:23552
	buffer_load_dwordx4 v145, s[4:7], s10 offen lds
	s_mov_b32 m0, s93
	s_nop 0
	buffer_load_dwordx4 v147, s[4:7], s10 offen lds
	s_or_b32 s10, s69, 0x40100
	s_mov_b32 m0, s94
	s_nop 0
	buffer_load_dwordx4 v145, s[4:7], s10 offen lds
	s_mov_b32 m0, s95
	s_nop 0
	buffer_load_dwordx4 v147, s[4:7], s10 offen lds
	s_mov_b32 m0, s44
	s_nop 0
	buffer_load_dwordx4 v144, s[0:3], s9 offen lds
	s_mov_b32 m0, s36
	s_nop 0
	buffer_load_dwordx4 v146, s[0:3], s9 offen lds
	s_waitcnt vmcnt(24)
	s_setprio 1
	s_barrier
	s_waitcnt lgkmcnt(0)
	v_mfma_f32_16x16x32_bf16 v[136:139], v[2:5], v[34:37], 0
	v_mfma_f32_16x16x32_bf16 v[154:157], v[2:5], v[86:89], 0
	v_mfma_f32_16x16x32_bf16 v[162:165], v[2:5], v[112:115], 0
	v_mfma_f32_16x16x32_bf16 v[2:5], v[2:5], v[124:127], 0
	v_mfma_f32_16x16x32_bf16 v[136:139], v[6:9], v[56:59], v[136:139]
	v_mfma_f32_16x16x32_bf16 v[140:143], v[10:13], v[34:37], 0
	v_mfma_f32_16x16x32_bf16 v[154:157], v[6:9], v[100:103], v[154:157]
	v_mfma_f32_16x16x32_bf16 v[158:161], v[10:13], v[86:89], 0
	v_mfma_f32_16x16x32_bf16 v[162:165], v[6:9], v[120:123], v[162:165]
	v_mfma_f32_16x16x32_bf16 v[166:169], v[10:13], v[112:115], 0
	v_mfma_f32_16x16x32_bf16 v[2:5], v[6:9], v[128:131], v[2:5]
	v_mfma_f32_16x16x32_bf16 v[6:9], v[10:13], v[124:127], 0
	v_mfma_f32_16x16x32_bf16 v[140:143], v[14:17], v[56:59], v[140:143]
	v_mfma_f32_16x16x32_bf16 v[158:161], v[14:17], v[100:103], v[158:161]
	v_mfma_f32_16x16x32_bf16 v[166:169], v[14:17], v[120:123], v[166:169]
	v_mfma_f32_16x16x32_bf16 v[170:173], v[14:17], v[128:131], v[6:9]
	v_mfma_f32_16x16x32_bf16 v[6:9], v[18:21], v[34:37], 0
	v_mfma_f32_16x16x32_bf16 v[174:177], v[22:25], v[56:59], v[6:9]
	v_mfma_f32_16x16x32_bf16 v[6:9], v[26:29], v[34:37], 0
	v_mfma_f32_16x16x32_bf16 v[178:181], v[30:33], v[56:59], v[6:9]
	v_mfma_f32_16x16x32_bf16 v[6:9], v[18:21], v[86:89], 0
	v_mfma_f32_16x16x32_bf16 v[182:185], v[22:25], v[100:103], v[6:9]
	v_mfma_f32_16x16x32_bf16 v[6:9], v[26:29], v[86:89], 0
	v_mfma_f32_16x16x32_bf16 v[186:189], v[30:33], v[100:103], v[6:9]
	v_mfma_f32_16x16x32_bf16 v[6:9], v[18:21], v[112:115], 0
	v_mfma_f32_16x16x32_bf16 v[190:193], v[22:25], v[120:123], v[6:9]
	v_mfma_f32_16x16x32_bf16 v[6:9], v[26:29], v[112:115], 0
	v_mfma_f32_16x16x32_bf16 v[212:215], v[30:33], v[120:123], v[6:9]
	v_mfma_f32_16x16x32_bf16 v[6:9], v[18:21], v[124:127], 0
	v_mfma_f32_16x16x32_bf16 v[20:23], v[22:25], v[128:131], v[6:9]
	v_mfma_f32_16x16x32_bf16 v[6:9], v[26:29], v[124:127], 0
	v_mfma_f32_16x16x32_bf16 v[216:219], v[30:33], v[128:131], v[6:9]
	s_barrier
; #define PG8_WAIT_V(n) asm volatile("s_waitcnt vmcnt(" #n ")" ::: "memory")
; #define PG8_BAR __builtin_amdgcn_s_barrier()
; template <class Epi, bool ALIGN_EPI, bool SP2, class Hook>
; __device__ __forceinline__ void gemm_phase(LAS unsigned char* lds, const Gemm g, const StaticOrder& S, const Epi& E, Acc& acc, const bool fresh, const Hook& H, const int wave_id) {
;     ...
;         cur = nxt; cA = nA; cB = nB; ++ui;
;         if constexpr (ALIGN_EPI) { if (wr == 1) PG8_BAR; }
;         if constexpr (SP2 && Epi::NSTORE > 0) {
;             const Src a1 = cA + kstep, a2 = cA + 2 * kstep, b2 = cB + 2 * kstep, a3 = a2 + kstep, b3 = b2 + kstep;
;             if constexpr (Epi::NSTORE == 16) PG8_TRIP_SP2(PG8_WAIT_V(24)); else PG8_TRIP_SP2(PG8_WAIT_V(16));
;             t0 = 2;
;         }
	s_setprio 0
	s_nop 4
	ds_read_b128 v[6:9], v152
	ds_read_b128 v[24:27], v152 offset:1024
	ds_read_b128 v[228:231], v152 offset:2048
	ds_read_b128 v[232:235], v152 offset:3072
	ds_read_b128 v[236:239], v153
	ds_read_b128 v[240:243], v153 offset:1024
	ds_read_b128 v[244:247], v153 offset:2048
	ds_read_b128 v[150:153], v153 offset:3072
	s_or_b32 s9, s68, 0x40100
	s_mov_b32 m0, s37
	ds_read_b128 v[10:13], v149 offset:32768
	ds_read_b128 v[14:17], v149 offset:33792
	ds_read_b128 v[32:35], v149 offset:34816
	ds_read_b128 v[194:197], v149 offset:35840
	ds_read_b128 v[208:211], v149 offset:36864
	ds_read_b128 v[200:203], v149 offset:37888
	ds_read_b128 v[204:207], v149 offset:38912
	ds_read_b128 v[220:223], v149 offset:39936
	buffer_load_dwordx4 v144, s[0:3], s9 offen lds
	s_mov_b32 m0, s38
	s_nop 0
	buffer_load_dwordx4 v146, s[0:3], s9 offen lds
	s_waitcnt vmcnt(8)
	s_setprio 1
	s_barrier
	s_waitcnt lgkmcnt(0)
	v_mfma_f32_16x16x32_bf16 v[28:31], v[6:9], v[10:13], v[66:69]
	v_mfma_f32_16x16x32_bf16 v[120:123], v[24:27], v[14:17], v[28:31]
	v_mfma_f32_16x16x32_bf16 v[28:31], v[228:231], v[10:13], v[70:73]
	v_mfma_f32_16x16x32_bf16 v[112:115], v[232:235], v[14:17], v[28:31]
	v_mfma_f32_16x16x32_bf16 v[28:31], v[6:9], v[32:35], v[74:77]
	v_mfma_f32_16x16x32_bf16 v[100:103], v[24:27], v[194:197], v[28:31]
	v_mfma_f32_16x16x32_bf16 v[28:31], v[228:231], v[32:35], v[78:81]
	v_mfma_f32_16x16x32_bf16 v[88:91], v[232:235], v[194:197], v[28:31]
	v_mfma_f32_16x16x32_bf16 v[28:31], v[6:9], v[208:211], v[82:85]
	v_mfma_f32_16x16x32_bf16 v[68:71], v[24:27], v[200:203], v[28:31]
	v_mfma_f32_16x16x32_bf16 v[28:31], v[228:231], v[208:211], v[92:95]
	v_mfma_f32_16x16x32_bf16 v[56:59], v[232:235], v[200:203], v[28:31]
	v_mfma_f32_16x16x32_bf16 v[28:31], v[6:9], v[204:207], v[96:99]
	v_mfma_f32_16x16x32_bf16 v[36:39], v[24:27], v[220:223], v[28:31]
	v_mfma_f32_16x16x32_bf16 v[28:31], v[228:231], v[204:207], v[104:107]
	v_mfma_f32_16x16x32_bf16 v[28:31], v[232:235], v[220:223], v[28:31]
	v_mfma_f32_16x16x32_bf16 v[64:67], v[236:239], v[10:13], v[108:111]
	v_mfma_f32_16x16x32_bf16 v[10:13], v[244:247], v[10:13], v[116:119]
	v_mfma_f32_16x16x32_bf16 v[124:127], v[150:153], v[14:17], v[10:13]
	v_mfma_f32_16x16x32_bf16 v[10:13], v[236:239], v[32:35], v[132:135]
	v_mfma_f32_16x16x32_bf16 v[116:119], v[240:243], v[194:197], v[10:13]
	v_mfma_f32_16x16x32_bf16 v[10:13], v[244:247], v[32:35], v[40:43]
	v_mfma_f32_16x16x32_bf16 v[108:111], v[150:153], v[194:197], v[10:13]
	v_mfma_f32_16x16x32_bf16 v[10:13], v[236:239], v[208:211], v[44:47]
	v_mfma_f32_16x16x32_bf16 v[92:95], v[240:243], v[200:203], v[10:13]
	v_mfma_f32_16x16x32_bf16 v[10:13], v[244:247], v[208:211], v[48:51]
	v_mfma_f32_16x16x32_bf16 v[80:83], v[150:153], v[200:203], v[10:13]
	v_mfma_f32_16x16x32_bf16 v[10:13], v[236:239], v[204:207], v[52:55]
	v_mfma_f32_16x16x32_bf16 v[128:131], v[240:243], v[14:17], v[64:67]
	v_mfma_f32_16x16x32_bf16 v[64:67], v[240:243], v[220:223], v[10:13]
	v_mfma_f32_16x16x32_bf16 v[10:13], v[244:247], v[204:207], v[60:63]
	v_mfma_f32_16x16x32_bf16 v[48:51], v[150:153], v[220:223], v[10:13]
	s_barrier
	s_setprio 0
	s_mov_b32 m0, s39
	s_or_b32 s9, s69, 0x180
	ds_read_b128 v[44:47], v149 offset:49152
	ds_read_b128 v[52:55], v149 offset:50176
	ds_read_b128 v[76:79], v149 offset:51200
	ds_read_b128 v[132:135], v149 offset:52224
	ds_read_b128 v[194:197], v149 offset:53248
	ds_read_b128 v[200:203], v149 offset:54272
	ds_read_b128 v[204:207], v149 offset:55296
	ds_read_b128 v[208:211], v149 offset:56320
	buffer_load_dwordx4 v145, s[4:7], s9 offen lds
	s_mov_b32 m0, s40
	s_nop 0
	buffer_load_dwordx4 v147, s[4:7], s9 offen lds
	s_or_b32 s9, s69, 0x40180
	s_mov_b32 m0, s43
	s_nop 0
	buffer_load_dwordx4 v145, s[4:7], s9 offen lds
	s_mov_b32 m0, s42
	s_nop 0
	buffer_load_dwordx4 v147, s[4:7], s9 offen lds
	s_mov_b32 m0, s41
	s_nop 0
	buffer_load_dwordx4 v144, s[0:3], s8 offen lds
	s_mov_b32 m0, s33
	s_nop 0
	buffer_load_dwordx4 v146, s[0:3], s8 offen lds
	s_waitcnt vmcnt(8)
	s_setprio 1
	s_barrier
	s_waitcnt lgkmcnt(0)
	v_mfma_f32_16x16x32_bf16 v[10:13], v[6:9], v[44:47], v[136:139]
	v_mfma_f32_16x16x32_bf16 v[72:75], v[24:27], v[52:55], v[10:13]
	v_mfma_f32_16x16x32_bf16 v[10:13], v[228:231], v[44:47], v[140:143]
	v_mfma_f32_16x16x32_bf16 v[60:63], v[232:235], v[52:55], v[10:13]
	v_mfma_f32_16x16x32_bf16 v[10:13], v[6:9], v[76:79], v[154:157]
	v_mfma_f32_16x16x32_bf16 v[40:43], v[24:27], v[132:135], v[10:13]
	v_mfma_f32_16x16x32_bf16 v[10:13], v[228:231], v[76:79], v[158:161]
	v_mfma_f32_16x16x32_bf16 v[32:35], v[232:235], v[132:135], v[10:13]
	v_mfma_f32_16x16x32_bf16 v[10:13], v[6:9], v[194:197], v[162:165]
	v_mfma_f32_16x16x32_bf16 v[16:19], v[24:27], v[200:203], v[10:13]
	v_mfma_f32_16x16x32_bf16 v[10:13], v[228:231], v[194:197], v[166:169]
	v_mfma_f32_16x16x32_bf16 v[2:5], v[6:9], v[204:207], v[2:5]
	v_mfma_f32_16x16x32_bf16 v[12:15], v[232:235], v[200:203], v[10:13]
	v_mfma_f32_16x16x32_bf16 v[8:11], v[24:27], v[208:211], v[2:5]
	v_mfma_f32_16x16x32_bf16 v[2:5], v[228:231], v[204:207], v[170:173]
	v_mfma_f32_16x16x32_bf16 v[4:7], v[232:235], v[208:211], v[2:5]
	v_mfma_f32_16x16x32_bf16 v[24:27], v[236:239], v[44:47], v[174:177]
	v_mfma_f32_16x16x32_bf16 v[96:99], v[240:243], v[52:55], v[24:27]
	v_mfma_f32_16x16x32_bf16 v[24:27], v[244:247], v[44:47], v[178:181]
	v_mfma_f32_16x16x32_bf16 v[104:107], v[150:153], v[52:55], v[24:27]
	v_mfma_f32_16x16x32_bf16 v[24:27], v[236:239], v[76:79], v[182:185]
	v_mfma_f32_16x16x32_bf16 v[84:87], v[240:243], v[132:135], v[24:27]
	v_mfma_f32_16x16x32_bf16 v[24:27], v[244:247], v[76:79], v[186:189]
	v_mfma_f32_16x16x32_bf16 v[76:79], v[150:153], v[132:135], v[24:27]
	v_mfma_f32_16x16x32_bf16 v[24:27], v[236:239], v[194:197], v[190:193]
	v_mfma_f32_16x16x32_bf16 v[52:55], v[240:243], v[200:203], v[24:27]
	v_mfma_f32_16x16x32_bf16 v[24:27], v[244:247], v[194:197], v[212:215]
	v_mfma_f32_16x16x32_bf16 v[20:23], v[236:239], v[204:207], v[20:23]
	v_mfma_f32_16x16x32_bf16 v[44:47], v[150:153], v[200:203], v[24:27]
	v_mfma_f32_16x16x32_bf16 v[24:27], v[240:243], v[208:211], v[20:23]
	v_mfma_f32_16x16x32_bf16 v[20:23], v[244:247], v[204:207], v[216:219]
	v_mfma_f32_16x16x32_bf16 v[20:23], v[150:153], v[208:211], v[20:23]
	s_barrier
	s_setprio 0
	s_mov_b64 s[8:9], 0
	v_mov_b64_e32 v[234:235], v[198:199]
	v_mov_b64_e32 v[236:237], v[226:227]
	v_mov_b32_e32 v198, v0
	v_mov_b32_e32 v226, v225
	v_mov_b64_e32 v[244:245], 0x100
	v_mov_b64_e32 v[246:247], 0xff

; __device__ __forceinline__ const bf16_t* selA(const Gemm& g, int s) { return sel3(g.A0, g.A1, g.A2, s); }
; __device__ __forceinline__ const bf16_t* selB(const Gemm& g, int s) { return sel3(g.B0, g.B1, g.B2, s); }
; __device__ __forceinline__ Src make_src(const bf16_t* p, size_t off) { Src s_; s_.r = __builtin_amdgcn_make_buffer_rsrc((void*)p, (short)0, 0x7fffffff, 0x00020000); s_.o = (unsigned)off; return s_; }
; #define PG8_WAIT_V(n) asm volatile("s_waitcnt vmcnt(" #n ")" ::: "memory")
; template <class Epi, bool ALIGN_EPI, bool SP2, class Hook>
; __device__ __forceinline__ void gemm_phase(LAS unsigned char* lds, const Gemm g, const StaticOrder& S, const Epi& E, Acc& acc, const bool fresh, const Hook& H, const int wave_id) {
;     ...
;         const bool has_next = S.next(ui + 1, nxt);
;         const Src nA = has_next ? make_src(selA(g, nxt.seg), (size_t)nxt.pm * tstepA) : cA, nB = has_next ? make_src(selB(g, nxt.seg), (size_t)nxt.pn * tstep) : cB;
;         for (int t = t0; t < nt; t += 2) {
;             const bool last = (t == nt - 2);
;             const Src a1 = cA + (size_t)(t + 1) * kstep;
;             const Src a2 = last ? nA : cA + (size_t)(t + 2) * kstep, b2 = last ? nB : cB + (size_t)(t + 2) * kstep;
;             const Src a3 = a2 + kstep, b3 = b2 + kstep;
;             if (last && has_next) H(nxt);
;             if constexpr (SP2) {
;             PG8_TRIP_SP2(PG8_WAIT_V(8));
.LBB0_391:
	v_add_u32_e32 v150, 0x10000, v148
	v_add_u32_e32 v151, 0x14000, v148
	ds_read_b128 v[132:135], v150
	ds_read_b128 v[136:139], v150 offset:1024
	ds_read_b128 v[140:143], v150 offset:2048
	ds_read_b128 v[152:155], v150 offset:3072
	ds_read_b128 v[156:159], v151
	ds_read_b128 v[160:163], v151 offset:1024
	ds_read_b128 v[164:167], v151 offset:2048
	ds_read_b128 v[168:171], v151 offset:3072
	s_add_i32 s12, s56, 0xfffc0080
	s_cmp_eq_u32 s29, 12
	s_cselect_b32 s60, s68, s12
	s_cselect_b32 s13, s5, s77
	s_cselect_b32 s12, s4, s76
	s_cselect_b32 s15, s7, s55
	s_cselect_b32 s14, s6, s54
	s_cselect_b32 s58, s69, s57
	s_cselect_b32 s16, s0, s8
	s_cselect_b32 s17, s1, s9
	s_cselect_b32 s18, s2, s10
	s_cselect_b32 s19, s3, s11
	s_or_b32 s59, s60, 0x80
	s_mov_b32 m0, s45
	ds_read_b128 v[172:175], v149
	ds_read_b128 v[176:179], v149 offset:1024
	ds_read_b128 v[180:183], v149 offset:2048
	ds_read_b128 v[184:187], v149 offset:3072
	ds_read_b128 v[188:191], v149 offset:4096
	ds_read_b128 v[212:215], v149 offset:5120
	ds_read_b128 v[216:219], v149 offset:6144
	ds_read_b128 v[228:231], v149 offset:7168
	buffer_load_dwordx4 v144, s[8:11], s56 offen lds
	s_mov_b32 m0, s46
	s_nop 0
	buffer_load_dwordx4 v146, s[8:11], s56 offen lds
	s_waitcnt vmcnt(8)
	s_setprio 1
	s_barrier
	s_waitcnt lgkmcnt(0)
	v_mfma_f32_16x16x32_bf16 v[120:123], v[132:135], v[172:175], v[120:123]
	v_mfma_f32_16x16x32_bf16 v[112:115], v[140:143], v[172:175], v[112:115]
	v_mfma_f32_16x16x32_bf16 v[100:103], v[132:135], v[180:183], v[100:103]
	v_mfma_f32_16x16x32_bf16 v[88:91], v[140:143], v[180:183], v[88:91]
	v_mfma_f32_16x16x32_bf16 v[68:71], v[132:135], v[188:191], v[68:71]
	v_mfma_f32_16x16x32_bf16 v[56:59], v[140:143], v[188:191], v[56:59]
	v_mfma_f32_16x16x32_bf16 v[36:39], v[132:135], v[216:219], v[36:39]
	v_mfma_f32_16x16x32_bf16 v[28:31], v[140:143], v[216:219], v[28:31]
	v_mfma_f32_16x16x32_bf16 v[120:123], v[136:139], v[176:179], v[120:123]
	v_mfma_f32_16x16x32_bf16 v[112:115], v[152:155], v[176:179], v[112:115]
	v_mfma_f32_16x16x32_bf16 v[100:103], v[136:139], v[184:187], v[100:103]
	v_mfma_f32_16x16x32_bf16 v[88:91], v[152:155], v[184:187], v[88:91]
	v_mfma_f32_16x16x32_bf16 v[68:71], v[136:139], v[212:215], v[68:71]
	v_mfma_f32_16x16x32_bf16 v[56:59], v[152:155], v[212:215], v[56:59]
	v_mfma_f32_16x16x32_bf16 v[36:39], v[136:139], v[228:231], v[36:39]
	v_mfma_f32_16x16x32_bf16 v[28:31], v[152:155], v[228:231], v[28:31]
	v_mfma_f32_16x16x32_bf16 v[128:131], v[156:159], v[172:175], v[128:131]
	v_mfma_f32_16x16x32_bf16 v[124:127], v[164:167], v[172:175], v[124:127]
	v_mfma_f32_16x16x32_bf16 v[116:119], v[156:159], v[180:183], v[116:119]
	v_mfma_f32_16x16x32_bf16 v[108:111], v[164:167], v[180:183], v[108:111]
	v_mfma_f32_16x16x32_bf16 v[92:95], v[156:159], v[188:191], v[92:95]
	v_mfma_f32_16x16x32_bf16 v[80:83], v[164:167], v[188:191], v[80:83]
	v_mfma_f32_16x16x32_bf16 v[64:67], v[156:159], v[216:219], v[64:67]
	v_mfma_f32_16x16x32_bf16 v[48:51], v[164:167], v[216:219], v[48:51]
	v_mfma_f32_16x16x32_bf16 v[128:131], v[160:163], v[176:179], v[128:131]
	v_mfma_f32_16x16x32_bf16 v[124:127], v[168:171], v[176:179], v[124:127]
	v_mfma_f32_16x16x32_bf16 v[116:119], v[160:163], v[184:187], v[116:119]
	v_mfma_f32_16x16x32_bf16 v[108:111], v[168:171], v[184:187], v[108:111]
	v_mfma_f32_16x16x32_bf16 v[92:95], v[160:163], v[212:215], v[92:95]
	v_mfma_f32_16x16x32_bf16 v[80:83], v[168:171], v[212:215], v[80:83]
	v_mfma_f32_16x16x32_bf16 v[64:67], v[160:163], v[228:231], v[64:67]
	v_mfma_f32_16x16x32_bf16 v[48:51], v[168:171], v[228:231], v[48:51]
	s_barrier
	s_setprio 0
	s_mov_b32 m0, s92
	ds_read_b128 v[172:175], v149 offset:16384
	ds_read_b128 v[176:179], v149 offset:17408
	ds_read_b128 v[180:183], v149 offset:18432
	ds_read_b128 v[184:187], v149 offset:19456
	ds_read_b128 v[188:191], v149 offset:20480
	ds_read_b128 v[212:215], v149 offset:21504
	ds_read_b128 v[216:219], v149 offset:22528
	ds_read_b128 v[228:231], v149 offset:23552
	buffer_load_dwordx4 v145, s[12:15], s58 offen lds
	s_mov_b32 m0, s93
	s_add_i32 s61, s58, 0x40000
	buffer_load_dwordx4 v147, s[12:15], s58 offen lds
	s_mov_b32 m0, s94
	s_nop 0
	buffer_load_dwordx4 v145, s[12:15], s61 offen lds
	s_mov_b32 m0, s95
	s_nop 0
	buffer_load_dwordx4 v147, s[12:15], s61 offen lds
	s_mov_b32 m0, s44
	s_nop 0
	buffer_load_dwordx4 v144, s[16:19], s60 offen lds
	s_mov_b32 m0, s36
	s_nop 0
	buffer_load_dwordx4 v146, s[16:19], s60 offen lds
	s_waitcnt vmcnt(8)
	s_setprio 1
	s_barrier
	s_waitcnt lgkmcnt(0)
	v_mfma_f32_16x16x32_bf16 v[72:75], v[132:135], v[172:175], v[72:75]
	v_mfma_f32_16x16x32_bf16 v[60:63], v[140:143], v[172:175], v[60:63]
	v_mfma_f32_16x16x32_bf16 v[40:43], v[132:135], v[180:183], v[40:43]
	v_mfma_f32_16x16x32_bf16 v[32:35], v[140:143], v[180:183], v[32:35]
	v_mfma_f32_16x16x32_bf16 v[16:19], v[132:135], v[188:191], v[16:19]
	v_mfma_f32_16x16x32_bf16 v[12:15], v[140:143], v[188:191], v[12:15]
	v_mfma_f32_16x16x32_bf16 v[8:11], v[132:135], v[216:219], v[8:11]
	v_mfma_f32_16x16x32_bf16 v[2:5], v[140:143], v[216:219], v[4:7]
	v_mfma_f32_16x16x32_bf16 v[72:75], v[136:139], v[176:179], v[72:75]
	v_mfma_f32_16x16x32_bf16 v[60:63], v[152:155], v[176:179], v[60:63]
	v_mfma_f32_16x16x32_bf16 v[40:43], v[136:139], v[184:187], v[40:43]
	v_mfma_f32_16x16x32_bf16 v[32:35], v[152:155], v[184:187], v[32:35]
	v_mfma_f32_16x16x32_bf16 v[16:19], v[136:139], v[212:215], v[16:19]
	v_mfma_f32_16x16x32_bf16 v[12:15], v[152:155], v[212:215], v[12:15]
	v_mfma_f32_16x16x32_bf16 v[8:11], v[136:139], v[228:231], v[8:11]
	v_mfma_f32_16x16x32_bf16 v[2:5], v[152:155], v[228:231], v[2:5]
	v_mfma_f32_16x16x32_bf16 v[96:99], v[156:159], v[172:175], v[96:99]
	v_mfma_f32_16x16x32_bf16 v[104:107], v[164:167], v[172:175], v[104:107]
	v_mfma_f32_16x16x32_bf16 v[84:87], v[156:159], v[180:183], v[84:87]
	v_mfma_f32_16x16x32_bf16 v[76:79], v[164:167], v[180:183], v[76:79]
	v_mfma_f32_16x16x32_bf16 v[52:55], v[156:159], v[188:191], v[52:55]
	v_mfma_f32_16x16x32_bf16 v[44:47], v[164:167], v[188:191], v[44:47]
	v_mfma_f32_16x16x32_bf16 v[24:27], v[156:159], v[216:219], v[24:27]
	v_mfma_f32_16x16x32_bf16 v[20:23], v[164:167], v[216:219], v[20:23]
	v_mfma_f32_16x16x32_bf16 v[96:99], v[160:163], v[176:179], v[96:99]
	v_mfma_f32_16x16x32_bf16 v[104:107], v[168:171], v[176:179], v[104:107]
	v_mfma_f32_16x16x32_bf16 v[84:87], v[160:163], v[184:187], v[84:87]
	v_mfma_f32_16x16x32_bf16 v[76:79], v[168:171], v[184:187], v[76:79]
	v_mfma_f32_16x16x32_bf16 v[52:55], v[160:163], v[212:215], v[52:55]
	v_mfma_f32_16x16x32_bf16 v[44:47], v[168:171], v[212:215], v[44:47]
	v_mfma_f32_16x16x32_bf16 v[24:27], v[160:163], v[228:231], v[24:27]
	v_mfma_f32_16x16x32_bf16 v[20:23], v[168:171], v[228:231], v[20:23]
	s_barrier
; #define PG8_STAGE(bufoff, gbase, voff) do { const Src _g = (gbase); _Pragma("unroll") for (int _i = 0; _i < 2; ++_i) \
;         __builtin_amdgcn_raw_ptr_buffer_load_lds(_g.r, (LAS unsigned*)(lds + (bufoff) + ldsw + _i * 8192), 16, (voff)[_i], _g.o, 0, 0); } while (0)
; #define PG8_WAIT_V(n) asm volatile("s_waitcnt vmcnt(" #n ")" ::: "memory")
; template <class Epi, bool ALIGN_EPI, bool SP2, class Hook>
; __device__ __forceinline__ void gemm_phase(LAS unsigned char* lds, const Gemm g, const StaticOrder& S, const Epi& E, Acc& acc, const bool fresh, const Hook& H, const int wave_id) {
;     ...
;         for (int t = t0; t < nt; t += 2) {
;             const bool last = (t == nt - 2);
;             const Src a1 = cA + (size_t)(t + 1) * kstep;
;             const Src a2 = last ? nA : cA + (size_t)(t + 2) * kstep, b2 = last ? nB : cB + (size_t)(t + 2) * kstep;
;             const Src a3 = a2 + kstep, b3 = b2 + kstep;
;             if (last && has_next) H(nxt);
;             if constexpr (SP2) {
;             PG8_TRIP_SP2(PG8_WAIT_V(8));
;             } else {
;             PG8_LDB(B0, 0, 0); PG8_SCHED; PG8_LDA(At, 0, 0); PG8_STAGE(PG8_SA(1, 1), a1 + hstepA, voffA);
;             PG8_WAIT_L(8); PG8_BAR; PG8_WAIT_L(0); PG8_MMA(0, 0, At, B0); PG8_BAR; PG8_SCHED;
;             PG8_LDB(B1, 0, 1); PG8_STAGE(PG8_SB(0, 0), b2, voffB);
;             PG8_BAR; PG8_WAIT_L(0); PG8_MMA(0, 1, At, B1); PG8_BAR;
;             PG8_LDA(At, 0, 1); PG8_STAGE(PG8_SA(0, 0), a2, voffA);
;             PG8_BAR; PG8_WAIT_L(0); PG8_MMA(1, 0, At, B0); PG8_BAR; PG8_SCHED;
;             PG8_STAGE(PG8_SB(0, 1), b2 + hstep, voffB);
;             PG8_WAIT_V(6); PG8_BAR; PG8_MMA(1, 1, At, B1); PG8_BAR;
;             PG8_LDB(B0, 1, 0); PG8_SCHED; PG8_LDA(At, 1, 0); PG8_STAGE(PG8_SA(0, 1), a2 + hstepA, voffA);
;             PG8_WAIT_L(8); PG8_BAR; PG8_WAIT_L(0); PG8_MMA(0, 0, At, B0); PG8_BAR; PG8_SCHED;
;             PG8_LDB(B1, 1, 1); PG8_STAGE(PG8_SB(1, 0), b3, voffB);
;             PG8_BAR; PG8_WAIT_L(0); PG8_MMA(0, 1, At, B1); PG8_BAR;
;             PG8_LDA(At, 1, 1); PG8_STAGE(PG8_SA(1, 0), a3, voffA);
;             PG8_BAR; PG8_WAIT_L(0); PG8_MMA(1, 0, At, B0); PG8_BAR; PG8_SCHED;
;             PG8_STAGE(PG8_SB(1, 1), b3 + hstep, voffB);
;             PG8_WAIT_V(6); PG8_BAR; PG8_MMA(1, 1, At, B1); PG8_BAR;
;             }
;         }
;         if constexpr (ALIGN_EPI) { if (wr == 0) PG8_BAR; }
	s_setprio 0
	v_add_u32_e32 v152, 0x18000, v148
	v_add_u32_e32 v153, 0x1c000, v148
	ds_read_b128 v[132:135], v152
	ds_read_b128 v[136:139], v152 offset:1024
	ds_read_b128 v[140:143], v152 offset:2048
	ds_read_b128 v[154:157], v152 offset:3072
	ds_read_b128 v[158:161], v153
	ds_read_b128 v[162:165], v153 offset:1024
	ds_read_b128 v[166:169], v153 offset:2048
	ds_read_b128 v[170:173], v153 offset:3072
	s_add_i32 s60, s60, 0x40000
	s_mov_b32 m0, s37
	ds_read_b128 v[174:177], v149 offset:32768
	ds_read_b128 v[178:181], v149 offset:33792
	ds_read_b128 v[182:185], v149 offset:34816
	ds_read_b128 v[186:189], v149 offset:35840
	ds_read_b128 v[190:193], v149 offset:36864
	ds_read_b128 v[212:215], v149 offset:37888
	ds_read_b128 v[216:219], v149 offset:38912
	ds_read_b128 v[228:231], v149 offset:39936
	buffer_load_dwordx4 v144, s[16:19], s60 offen lds
	s_mov_b32 m0, s38
	s_nop 0
	buffer_load_dwordx4 v146, s[16:19], s60 offen lds
	s_waitcnt vmcnt(8)
	s_setprio 1
	s_barrier
	s_waitcnt lgkmcnt(0)
	v_mfma_f32_16x16x32_bf16 v[120:123], v[132:135], v[174:177], v[120:123]
	v_mfma_f32_16x16x32_bf16 v[112:115], v[140:143], v[174:177], v[112:115]
	v_mfma_f32_16x16x32_bf16 v[100:103], v[132:135], v[182:185], v[100:103]
	v_mfma_f32_16x16x32_bf16 v[88:91], v[140:143], v[182:185], v[88:91]
	v_mfma_f32_16x16x32_bf16 v[68:71], v[132:135], v[190:193], v[68:71]
	v_mfma_f32_16x16x32_bf16 v[56:59], v[140:143], v[190:193], v[56:59]
	v_mfma_f32_16x16x32_bf16 v[36:39], v[132:135], v[216:219], v[36:39]
	v_mfma_f32_16x16x32_bf16 v[28:31], v[140:143], v[216:219], v[28:31]
	v_mfma_f32_16x16x32_bf16 v[120:123], v[136:139], v[178:181], v[120:123]
	v_mfma_f32_16x16x32_bf16 v[112:115], v[154:157], v[178:181], v[112:115]
	v_mfma_f32_16x16x32_bf16 v[100:103], v[136:139], v[186:189], v[100:103]
	v_mfma_f32_16x16x32_bf16 v[88:91], v[154:157], v[186:189], v[88:91]
	v_mfma_f32_16x16x32_bf16 v[68:71], v[136:139], v[212:215], v[68:71]
	v_mfma_f32_16x16x32_bf16 v[56:59], v[154:157], v[212:215], v[56:59]
	v_mfma_f32_16x16x32_bf16 v[36:39], v[136:139], v[228:231], v[36:39]
	v_mfma_f32_16x16x32_bf16 v[28:31], v[154:157], v[228:231], v[28:31]
	v_mfma_f32_16x16x32_bf16 v[128:131], v[158:161], v[174:177], v[128:131]
	v_mfma_f32_16x16x32_bf16 v[124:127], v[166:169], v[174:177], v[124:127]
	v_mfma_f32_16x16x32_bf16 v[116:119], v[158:161], v[182:185], v[116:119]
	v_mfma_f32_16x16x32_bf16 v[108:111], v[166:169], v[182:185], v[108:111]
	v_mfma_f32_16x16x32_bf16 v[92:95], v[158:161], v[190:193], v[92:95]
	v_mfma_f32_16x16x32_bf16 v[80:83], v[166:169], v[190:193], v[80:83]
	v_mfma_f32_16x16x32_bf16 v[64:67], v[158:161], v[216:219], v[64:67]
	v_mfma_f32_16x16x32_bf16 v[48:51], v[166:169], v[216:219], v[48:51]
	v_mfma_f32_16x16x32_bf16 v[128:131], v[162:165], v[178:181], v[128:131]
	v_mfma_f32_16x16x32_bf16 v[124:127], v[170:173], v[178:181], v[124:127]
	v_mfma_f32_16x16x32_bf16 v[116:119], v[162:165], v[186:189], v[116:119]
	v_mfma_f32_16x16x32_bf16 v[108:111], v[170:173], v[186:189], v[108:111]
	v_mfma_f32_16x16x32_bf16 v[92:95], v[162:165], v[212:215], v[92:95]
	v_mfma_f32_16x16x32_bf16 v[80:83], v[170:173], v[212:215], v[80:83]
	v_mfma_f32_16x16x32_bf16 v[64:67], v[162:165], v[228:231], v[64:67]
	v_mfma_f32_16x16x32_bf16 v[48:51], v[170:173], v[228:231], v[48:51]
	s_barrier
	s_setprio 0
	s_mov_b32 m0, s39
	s_or_b32 s60, s58, 0x80
	ds_read_b128 v[174:177], v149 offset:49152
	ds_read_b128 v[178:181], v149 offset:50176
	ds_read_b128 v[182:185], v149 offset:51200
	ds_read_b128 v[186:189], v149 offset:52224
	ds_read_b128 v[190:193], v149 offset:53248
	ds_read_b128 v[212:215], v149 offset:54272
	ds_read_b128 v[216:219], v149 offset:55296
	ds_read_b128 v[228:231], v149 offset:56320
	buffer_load_dwordx4 v145, s[12:15], s60 offen lds
	s_mov_b32 m0, s40
	s_add_i32 s58, s58, 0x40080
	buffer_load_dwordx4 v147, s[12:15], s60 offen lds
	s_mov_b32 m0, s43
	s_nop 0
	buffer_load_dwordx4 v145, s[12:15], s58 offen lds
	s_mov_b32 m0, s42
	s_nop 0
	buffer_load_dwordx4 v147, s[12:15], s58 offen lds
	s_mov_b32 m0, s41
	s_nop 0
	buffer_load_dwordx4 v144, s[16:19], s59 offen lds
	s_mov_b32 m0, s33
	s_nop 0
	buffer_load_dwordx4 v146, s[16:19], s59 offen lds
	s_waitcnt vmcnt(8)
	s_setprio 1
	s_barrier
	s_waitcnt lgkmcnt(0)
	v_mfma_f32_16x16x32_bf16 v[72:75], v[132:135], v[174:177], v[72:75]
	v_mfma_f32_16x16x32_bf16 v[60:63], v[140:143], v[174:177], v[60:63]
	v_mfma_f32_16x16x32_bf16 v[40:43], v[132:135], v[182:185], v[40:43]
	v_mfma_f32_16x16x32_bf16 v[32:35], v[140:143], v[182:185], v[32:35]
	v_mfma_f32_16x16x32_bf16 v[16:19], v[132:135], v[190:193], v[16:19]
	v_mfma_f32_16x16x32_bf16 v[12:15], v[140:143], v[190:193], v[12:15]
	v_mfma_f32_16x16x32_bf16 v[6:9], v[132:135], v[216:219], v[8:11]
	v_mfma_f32_16x16x32_bf16 v[2:5], v[140:143], v[216:219], v[2:5]
	v_mfma_f32_16x16x32_bf16 v[72:75], v[136:139], v[178:181], v[72:75]
	v_mfma_f32_16x16x32_bf16 v[60:63], v[154:157], v[178:181], v[60:63]
	v_mfma_f32_16x16x32_bf16 v[40:43], v[136:139], v[186:189], v[40:43]
	v_mfma_f32_16x16x32_bf16 v[32:35], v[154:157], v[186:189], v[32:35]
	v_mfma_f32_16x16x32_bf16 v[16:19], v[136:139], v[212:215], v[16:19]
	v_mfma_f32_16x16x32_bf16 v[12:15], v[154:157], v[212:215], v[12:15]
	v_mfma_f32_16x16x32_bf16 v[8:11], v[136:139], v[228:231], v[6:9]
	v_mfma_f32_16x16x32_bf16 v[4:7], v[154:157], v[228:231], v[2:5]
	v_mfma_f32_16x16x32_bf16 v[96:99], v[158:161], v[174:177], v[96:99]
	v_mfma_f32_16x16x32_bf16 v[104:107], v[166:169], v[174:177], v[104:107]
	v_mfma_f32_16x16x32_bf16 v[84:87], v[158:161], v[182:185], v[84:87]
	v_mfma_f32_16x16x32_bf16 v[76:79], v[166:169], v[182:185], v[76:79]
	v_mfma_f32_16x16x32_bf16 v[52:55], v[158:161], v[190:193], v[52:55]
	v_mfma_f32_16x16x32_bf16 v[44:47], v[166:169], v[190:193], v[44:47]
	v_mfma_f32_16x16x32_bf16 v[24:27], v[158:161], v[216:219], v[24:27]
	v_mfma_f32_16x16x32_bf16 v[20:23], v[166:169], v[216:219], v[20:23]
	v_mfma_f32_16x16x32_bf16 v[96:99], v[162:165], v[178:181], v[96:99]
	v_mfma_f32_16x16x32_bf16 v[104:107], v[170:173], v[178:181], v[104:107]
	v_mfma_f32_16x16x32_bf16 v[84:87], v[162:165], v[186:189], v[84:87]
	v_mfma_f32_16x16x32_bf16 v[76:79], v[170:173], v[186:189], v[76:79]
	v_mfma_f32_16x16x32_bf16 v[52:55], v[162:165], v[212:215], v[52:55]
	v_mfma_f32_16x16x32_bf16 v[44:47], v[170:173], v[212:215], v[44:47]
	v_mfma_f32_16x16x32_bf16 v[24:27], v[162:165], v[228:231], v[24:27]
	v_mfma_f32_16x16x32_bf16 v[20:23], v[170:173], v[228:231], v[20:23]
	s_barrier
	s_setprio 0
	s_add_i32 s29, s29, 2
	s_addk_i32 s56, 0x100
	s_addk_i32 s57, 0x100
	s_cmp_gt_u32 s29, 13
	s_cbranch_scc0 .LBB0_391
	v_readlane_b32 s8, v251, 45
	v_readlane_b32 s9, v251, 46
	s_and_b64 vcc, exec, s[8:9]
	s_cbranch_vccz .LBB0_394
	s_barrier

; template <class Epi, bool ALIGN_EPI, bool SP2, class Hook>
; __device__ __forceinline__ void gemm_phase(LAS unsigned char* lds, const Gemm g, const StaticOrder& S, const Epi& E, Acc& acc, const bool fresh, const Hook& H, const int wave_id) {
;     ...
;         for (int t = t0; t < nt; t += 2) {
;             const bool last = (t == nt - 2);
;             const Src a1 = cA + (size_t)(t + 1) * kstep;
;             const Src a2 = last ? nA : cA + (size_t)(t + 2) * kstep, b2 = last ? nB : cB + (size_t)(t + 2) * kstep;
;             const Src a3 = a2 + kstep, b3 = b2 + kstep;
;             if (last && has_next) H(nxt);
.LBB0_702:
	v_add_u32_e32 v70, 0x10000, v216
	v_add_u32_e32 v118, 0x14000, v216
	ds_read_b128 v[34:37], v70
	ds_read_b128 v[46:49], v70 offset:1024
	ds_read_b128 v[58:61], v70 offset:2048
	ds_read_b128 v[70:73], v70 offset:3072
	ds_read_b128 v[82:85], v118
	ds_read_b128 v[94:97], v118 offset:1024
	ds_read_b128 v[106:109], v118 offset:2048
	ds_read_b128 v[118:121], v118 offset:3072
	s_add_i32 s12, s55, 0xfffe0080
	s_cmp_eq_u32 s57, 4
	s_cselect_b32 s60, s53, s12
	s_cselect_b32 s13, s29, s77
	s_cselect_b32 s12, s28, s76
	s_cselect_b32 s15, s31, s35
	s_cselect_b32 s14, s30, s34
	s_cselect_b32 s58, s54, s56
	s_cselect_b32 s16, s2, s8
	s_cselect_b32 s17, s3, s9
	s_cselect_b32 s18, s26, s10
	s_cselect_b32 s19, s27, s11
	s_or_b32 s59, s60, 0x80
	s_mov_b32 m0, s45
	s_waitcnt vmcnt(14)
	ds_read_b128 v[130:133], v217
	ds_read_b128 v[142:145], v217 offset:1024
	ds_read_b128 v[154:157], v217 offset:2048
	ds_read_b128 v[166:169], v217 offset:3072
	ds_read_b128 v[174:177], v217 offset:4096
	ds_read_b128 v[182:185], v217 offset:5120
	ds_read_b128 v[186:189], v217 offset:6144
	ds_read_b128 v[190:193], v217 offset:7168
	buffer_load_dwordx4 v0, s[8:11], s55 offen lds
	s_mov_b32 m0, s46
	s_nop 0
	buffer_load_dwordx4 v214, s[8:11], s55 offen lds
	s_waitcnt vmcnt(8)
	s_setprio 1
	s_barrier
	s_waitcnt lgkmcnt(0)
	v_mfma_f32_16x16x32_bf16 v[178:181], v[34:37], v[130:133], v[178:181]
	v_mfma_f32_16x16x32_bf16 v[170:173], v[58:61], v[130:133], v[170:173]
	v_mfma_f32_16x16x32_bf16 v[150:153], v[34:37], v[154:157], v[150:153]
	v_mfma_f32_16x16x32_bf16 v[146:149], v[58:61], v[154:157], v[146:149]
	v_mfma_f32_16x16x32_bf16 v[126:129], v[34:37], v[174:177], v[126:129]
	v_mfma_f32_16x16x32_bf16 v[122:125], v[58:61], v[174:177], v[122:125]
	v_mfma_f32_16x16x32_bf16 v[102:105], v[34:37], v[186:189], v[102:105]
	v_mfma_f32_16x16x32_bf16 v[98:101], v[58:61], v[186:189], v[98:101]
	v_mfma_f32_16x16x32_bf16 v[178:181], v[46:49], v[142:145], v[178:181]
	v_mfma_f32_16x16x32_bf16 v[170:173], v[70:73], v[142:145], v[170:173]
	v_mfma_f32_16x16x32_bf16 v[150:153], v[46:49], v[166:169], v[150:153]
	v_mfma_f32_16x16x32_bf16 v[146:149], v[70:73], v[166:169], v[146:149]
	v_mfma_f32_16x16x32_bf16 v[126:129], v[46:49], v[182:185], v[126:129]
	v_mfma_f32_16x16x32_bf16 v[122:125], v[70:73], v[182:185], v[122:125]
	v_mfma_f32_16x16x32_bf16 v[102:105], v[46:49], v[190:193], v[102:105]
	v_mfma_f32_16x16x32_bf16 v[98:101], v[70:73], v[190:193], v[98:101]
	v_mfma_f32_16x16x32_bf16 v[162:165], v[82:85], v[130:133], v[162:165]
	v_mfma_f32_16x16x32_bf16 v[138:141], v[82:85], v[154:157], v[138:141]
	v_mfma_f32_16x16x32_bf16 v[134:137], v[106:109], v[154:157], v[134:137]
	v_mfma_f32_16x16x32_bf16 v[114:117], v[82:85], v[174:177], v[114:117]
	v_mfma_f32_16x16x32_bf16 v[110:113], v[106:109], v[174:177], v[110:113]
	v_mfma_f32_16x16x32_bf16 v[90:93], v[82:85], v[186:189], v[90:93]
	v_mfma_f32_16x16x32_bf16 v[86:89], v[106:109], v[186:189], v[86:89]
	v_mfma_f32_16x16x32_bf16 v[162:165], v[94:97], v[142:145], v[162:165]
	v_mfma_f32_16x16x32_bf16 v[130:133], v[106:109], v[130:133], v[158:161]
	v_mfma_f32_16x16x32_bf16 v[138:141], v[94:97], v[166:169], v[138:141]
	v_mfma_f32_16x16x32_bf16 v[134:137], v[118:121], v[166:169], v[134:137]
	v_mfma_f32_16x16x32_bf16 v[114:117], v[94:97], v[182:185], v[114:117]
	v_mfma_f32_16x16x32_bf16 v[110:113], v[118:121], v[182:185], v[110:113]
	v_mfma_f32_16x16x32_bf16 v[90:93], v[94:97], v[190:193], v[90:93]
	v_mfma_f32_16x16x32_bf16 v[86:89], v[118:121], v[190:193], v[86:89]
	v_mfma_f32_16x16x32_bf16 v[130:133], v[118:121], v[142:145], v[130:133]
	s_barrier
	s_setprio 0
	s_mov_b32 m0, s92
	ds_read_b128 v[142:145], v217 offset:16384
	ds_read_b128 v[154:157], v217 offset:17408
	ds_read_b128 v[158:161], v217 offset:18432
	ds_read_b128 v[166:169], v217 offset:19456
	ds_read_b128 v[174:177], v217 offset:20480
	ds_read_b128 v[182:185], v217 offset:21504
	ds_read_b128 v[186:189], v217 offset:22528
	ds_read_b128 v[190:193], v217 offset:23552
	buffer_load_dwordx4 v199, s[12:15], s58 offen lds
	s_mov_b32 m0, s93
	s_add_i32 s61, s58, 0x20000
	buffer_load_dwordx4 v215, s[12:15], s58 offen lds
	s_mov_b32 m0, s94
	s_nop 0
	buffer_load_dwordx4 v199, s[12:15], s61 offen lds
	s_mov_b32 m0, s95
	s_nop 0
	buffer_load_dwordx4 v215, s[12:15], s61 offen lds
	s_mov_b32 m0, s44
	s_nop 0
	buffer_load_dwordx4 v0, s[16:19], s60 offen lds
	s_mov_b32 m0, s36
	s_nop 0
	buffer_load_dwordx4 v214, s[16:19], s60 offen lds
	s_waitcnt vmcnt(8)
	s_setprio 1
	s_barrier
	s_waitcnt lgkmcnt(0)
	v_mfma_f32_16x16x32_bf16 v[78:81], v[34:37], v[142:145], v[78:81]
	v_mfma_f32_16x16x32_bf16 v[74:77], v[58:61], v[142:145], v[74:77]
	v_mfma_f32_16x16x32_bf16 v[54:57], v[34:37], v[158:161], v[54:57]
	v_mfma_f32_16x16x32_bf16 v[50:53], v[58:61], v[158:161], v[50:53]
	v_mfma_f32_16x16x32_bf16 v[30:33], v[34:37], v[174:177], v[30:33]
	v_mfma_f32_16x16x32_bf16 v[26:29], v[58:61], v[174:177], v[26:29]
	v_mfma_f32_16x16x32_bf16 v[14:17], v[34:37], v[186:189], v[14:17]
	v_mfma_f32_16x16x32_bf16 v[10:13], v[58:61], v[186:189], v[10:13]
	v_mfma_f32_16x16x32_bf16 v[78:81], v[46:49], v[154:157], v[78:81]
	v_mfma_f32_16x16x32_bf16 v[74:77], v[70:73], v[154:157], v[74:77]
	v_mfma_f32_16x16x32_bf16 v[54:57], v[46:49], v[166:169], v[54:57]
	v_mfma_f32_16x16x32_bf16 v[50:53], v[70:73], v[166:169], v[50:53]
	v_mfma_f32_16x16x32_bf16 v[30:33], v[46:49], v[182:185], v[30:33]
	v_mfma_f32_16x16x32_bf16 v[26:29], v[70:73], v[182:185], v[26:29]
	v_mfma_f32_16x16x32_bf16 v[14:17], v[46:49], v[190:193], v[14:17]
	v_mfma_f32_16x16x32_bf16 v[10:13], v[70:73], v[190:193], v[10:13]
	v_mfma_f32_16x16x32_bf16 v[42:45], v[82:85], v[158:161], v[42:45]
	v_mfma_f32_16x16x32_bf16 v[38:41], v[106:109], v[158:161], v[38:41]
	v_mfma_f32_16x16x32_bf16 v[22:25], v[82:85], v[174:177], v[22:25]
	v_mfma_f32_16x16x32_bf16 v[18:21], v[106:109], v[174:177], v[18:21]
	v_mfma_f32_16x16x32_bf16 v[6:9], v[82:85], v[186:189], v[6:9]
	v_mfma_f32_16x16x32_bf16 v[2:5], v[106:109], v[186:189], v[2:5]
	v_mfma_f32_16x16x32_bf16 v[34:37], v[82:85], v[142:145], v[66:69]
	v_mfma_f32_16x16x32_bf16 v[46:49], v[106:109], v[142:145], v[62:65]
	v_mfma_f32_16x16x32_bf16 v[42:45], v[94:97], v[166:169], v[42:45]
	v_mfma_f32_16x16x32_bf16 v[38:41], v[118:121], v[166:169], v[38:41]
	v_mfma_f32_16x16x32_bf16 v[22:25], v[94:97], v[182:185], v[22:25]
	v_mfma_f32_16x16x32_bf16 v[18:21], v[118:121], v[182:185], v[18:21]
	v_mfma_f32_16x16x32_bf16 v[6:9], v[94:97], v[190:193], v[6:9]
	v_mfma_f32_16x16x32_bf16 v[2:5], v[118:121], v[190:193], v[2:5]
	v_mfma_f32_16x16x32_bf16 v[34:37], v[94:97], v[154:157], v[34:37]
	v_mfma_f32_16x16x32_bf16 v[46:49], v[118:121], v[154:157], v[46:49]
	s_barrier
; #define PG8_WAIT_V(n) asm volatile("s_waitcnt vmcnt(" #n ")" ::: "memory")
; template <class Epi, bool ALIGN_EPI, bool SP2, class Hook>
; __device__ __forceinline__ void gemm_phase(LAS unsigned char* lds, const Gemm g, const StaticOrder& S, const Epi& E, Acc& acc, const bool fresh, const Hook& H, const int wave_id) {
;     ...
;         for (int t = t0; t < nt; t += 2) {
;             const bool last = (t == nt - 2);
;             const Src a1 = cA + (size_t)(t + 1) * kstep;
;             const Src a2 = last ? nA : cA + (size_t)(t + 2) * kstep, b2 = last ? nB : cB + (size_t)(t + 2) * kstep;
;             const Src a3 = a2 + kstep, b3 = b2 + kstep;
;             if (last && has_next) H(nxt);
;             if constexpr (SP2) {
;             PG8_TRIP_SP2(PG8_WAIT_V(8));
	s_setprio 0
	v_add_u32_e32 v70, 0x18000, v216
	v_add_u32_e32 v118, 0x1c000, v216
	ds_read_b128 v[58:61], v70
	ds_read_b128 v[62:65], v70 offset:1024
	ds_read_b128 v[66:69], v70 offset:2048
	ds_read_b128 v[70:73], v70 offset:3072
	ds_read_b128 v[82:85], v118
	ds_read_b128 v[94:97], v118 offset:1024
	ds_read_b128 v[106:109], v118 offset:2048
	ds_read_b128 v[118:121], v118 offset:3072
	s_add_i32 s60, s60, 0x20000
	s_mov_b32 m0, s37
	ds_read_b128 v[142:145], v217 offset:32768
	ds_read_b128 v[154:157], v217 offset:33792
	ds_read_b128 v[166:169], v217 offset:34816
	ds_read_b128 v[174:177], v217 offset:35840
	ds_read_b128 v[182:185], v217 offset:36864
	ds_read_b128 v[186:189], v217 offset:37888
	ds_read_b128 v[190:193], v217 offset:38912
	ds_read_b128 v[194:197], v217 offset:39936
	buffer_load_dwordx4 v0, s[16:19], s60 offen lds
	s_mov_b32 m0, s38
	s_nop 0
	buffer_load_dwordx4 v214, s[16:19], s60 offen lds
	s_waitcnt vmcnt(8)
	s_setprio 1
	s_barrier
	s_waitcnt lgkmcnt(0)
	v_mfma_f32_16x16x32_bf16 v[158:161], v[58:61], v[142:145], v[178:181]
	v_mfma_f32_16x16x32_bf16 v[178:181], v[62:65], v[154:157], v[158:161]
	v_mfma_f32_16x16x32_bf16 v[158:161], v[66:69], v[142:145], v[170:173]
	v_mfma_f32_16x16x32_bf16 v[150:153], v[58:61], v[166:169], v[150:153]
	v_mfma_f32_16x16x32_bf16 v[146:149], v[66:69], v[166:169], v[146:149]
	v_mfma_f32_16x16x32_bf16 v[126:129], v[58:61], v[182:185], v[126:129]
	v_mfma_f32_16x16x32_bf16 v[122:125], v[66:69], v[182:185], v[122:125]
	v_mfma_f32_16x16x32_bf16 v[102:105], v[58:61], v[190:193], v[102:105]
	v_mfma_f32_16x16x32_bf16 v[98:101], v[66:69], v[190:193], v[98:101]
	v_mfma_f32_16x16x32_bf16 v[170:173], v[70:73], v[154:157], v[158:161]
	v_mfma_f32_16x16x32_bf16 v[150:153], v[62:65], v[174:177], v[150:153]
	v_mfma_f32_16x16x32_bf16 v[146:149], v[70:73], v[174:177], v[146:149]
	v_mfma_f32_16x16x32_bf16 v[126:129], v[62:65], v[186:189], v[126:129]
	v_mfma_f32_16x16x32_bf16 v[122:125], v[70:73], v[186:189], v[122:125]
	v_mfma_f32_16x16x32_bf16 v[102:105], v[62:65], v[194:197], v[102:105]
	v_mfma_f32_16x16x32_bf16 v[98:101], v[70:73], v[194:197], v[98:101]
	v_mfma_f32_16x16x32_bf16 v[158:161], v[82:85], v[142:145], v[162:165]
	v_mfma_f32_16x16x32_bf16 v[130:133], v[106:109], v[142:145], v[130:133]
	v_mfma_f32_16x16x32_bf16 v[162:165], v[94:97], v[154:157], v[158:161]
	v_mfma_f32_16x16x32_bf16 v[158:161], v[118:121], v[154:157], v[130:133]
	v_mfma_f32_16x16x32_bf16 v[130:133], v[82:85], v[166:169], v[138:141]
	v_mfma_f32_16x16x32_bf16 v[138:141], v[94:97], v[174:177], v[130:133]
	v_mfma_f32_16x16x32_bf16 v[130:133], v[106:109], v[166:169], v[134:137]
	v_mfma_f32_16x16x32_bf16 v[114:117], v[82:85], v[182:185], v[114:117]
	v_mfma_f32_16x16x32_bf16 v[110:113], v[106:109], v[182:185], v[110:113]
	v_mfma_f32_16x16x32_bf16 v[90:93], v[82:85], v[190:193], v[90:93]
	v_mfma_f32_16x16x32_bf16 v[86:89], v[106:109], v[190:193], v[86:89]
	v_mfma_f32_16x16x32_bf16 v[134:137], v[118:121], v[174:177], v[130:133]
	v_mfma_f32_16x16x32_bf16 v[114:117], v[94:97], v[186:189], v[114:117]
	v_mfma_f32_16x16x32_bf16 v[110:113], v[118:121], v[186:189], v[110:113]
	v_mfma_f32_16x16x32_bf16 v[90:93], v[94:97], v[194:197], v[90:93]
	v_mfma_f32_16x16x32_bf16 v[86:89], v[118:121], v[194:197], v[86:89]
	s_barrier
	s_setprio 0
	s_mov_b32 m0, s39
	s_or_b32 s60, s58, 0x80
	ds_read_b128 v[130:133], v217 offset:49152
	ds_read_b128 v[142:145], v217 offset:50176
	ds_read_b128 v[154:157], v217 offset:51200
	ds_read_b128 v[166:169], v217 offset:52224
	ds_read_b128 v[174:177], v217 offset:53248
	ds_read_b128 v[182:185], v217 offset:54272
	ds_read_b128 v[186:189], v217 offset:55296
	ds_read_b128 v[190:193], v217 offset:56320
	buffer_load_dwordx4 v199, s[12:15], s60 offen lds
	s_mov_b32 m0, s40
	s_add_i32 s58, s58, 0x20080
	buffer_load_dwordx4 v215, s[12:15], s60 offen lds
	s_mov_b32 m0, s43
	s_nop 0
	buffer_load_dwordx4 v199, s[12:15], s58 offen lds
	s_mov_b32 m0, s42
	s_nop 0
	buffer_load_dwordx4 v215, s[12:15], s58 offen lds
	s_mov_b32 m0, s41
	s_nop 0
	buffer_load_dwordx4 v0, s[16:19], s59 offen lds
	s_mov_b32 m0, s33
	s_nop 0
	buffer_load_dwordx4 v214, s[16:19], s59 offen lds
	s_waitcnt vmcnt(8)
	s_setprio 1
	s_barrier
	s_waitcnt lgkmcnt(0)
	v_mfma_f32_16x16x32_bf16 v[78:81], v[58:61], v[130:133], v[78:81]
	v_mfma_f32_16x16x32_bf16 v[74:77], v[66:69], v[130:133], v[74:77]
	v_mfma_f32_16x16x32_bf16 v[54:57], v[58:61], v[154:157], v[54:57]
	v_mfma_f32_16x16x32_bf16 v[50:53], v[66:69], v[154:157], v[50:53]
	v_mfma_f32_16x16x32_bf16 v[30:33], v[58:61], v[174:177], v[30:33]
	v_mfma_f32_16x16x32_bf16 v[26:29], v[66:69], v[174:177], v[26:29]
	v_mfma_f32_16x16x32_bf16 v[14:17], v[58:61], v[186:189], v[14:17]
	v_mfma_f32_16x16x32_bf16 v[10:13], v[66:69], v[186:189], v[10:13]
	v_mfma_f32_16x16x32_bf16 v[78:81], v[62:65], v[142:145], v[78:81]
	v_mfma_f32_16x16x32_bf16 v[74:77], v[70:73], v[142:145], v[74:77]
	v_mfma_f32_16x16x32_bf16 v[54:57], v[62:65], v[166:169], v[54:57]
	v_mfma_f32_16x16x32_bf16 v[50:53], v[70:73], v[166:169], v[50:53]
	v_mfma_f32_16x16x32_bf16 v[30:33], v[62:65], v[182:185], v[30:33]
	v_mfma_f32_16x16x32_bf16 v[26:29], v[70:73], v[182:185], v[26:29]
	v_mfma_f32_16x16x32_bf16 v[14:17], v[62:65], v[190:193], v[14:17]
	v_mfma_f32_16x16x32_bf16 v[10:13], v[70:73], v[190:193], v[10:13]
	v_mfma_f32_16x16x32_bf16 v[34:37], v[82:85], v[130:133], v[34:37]
	v_mfma_f32_16x16x32_bf16 v[66:69], v[94:97], v[142:145], v[34:37]
	v_mfma_f32_16x16x32_bf16 v[34:37], v[106:109], v[130:133], v[46:49]
	v_mfma_f32_16x16x32_bf16 v[62:65], v[118:121], v[142:145], v[34:37]
	v_mfma_f32_16x16x32_bf16 v[34:37], v[82:85], v[154:157], v[42:45]
	v_mfma_f32_16x16x32_bf16 v[42:45], v[94:97], v[166:169], v[34:37]
	v_mfma_f32_16x16x32_bf16 v[34:37], v[106:109], v[154:157], v[38:41]
	v_mfma_f32_16x16x32_bf16 v[22:25], v[82:85], v[174:177], v[22:25]
	v_mfma_f32_16x16x32_bf16 v[18:21], v[106:109], v[174:177], v[18:21]
	v_mfma_f32_16x16x32_bf16 v[6:9], v[82:85], v[186:189], v[6:9]
	v_mfma_f32_16x16x32_bf16 v[2:5], v[106:109], v[186:189], v[2:5]
	v_mfma_f32_16x16x32_bf16 v[38:41], v[118:121], v[166:169], v[34:37]
	v_mfma_f32_16x16x32_bf16 v[22:25], v[94:97], v[182:185], v[22:25]
	v_mfma_f32_16x16x32_bf16 v[18:21], v[118:121], v[182:185], v[18:21]
	v_mfma_f32_16x16x32_bf16 v[6:9], v[94:97], v[190:193], v[6:9]
	v_mfma_f32_16x16x32_bf16 v[2:5], v[118:121], v[190:193], v[2:5]
	s_barrier
	s_setprio 0
	s_add_i32 s57, s57, 2
	s_addk_i32 s55, 0x100
	s_addk_i32 s56, 0x100
	s_cmp_gt_u32 s57, 5
	s_cbranch_scc0 .LBB0_702
	v_readlane_b32 s8, v251, 45
	v_readlane_b32 s9, v251, 46
	s_and_b64 vcc, exec, s[8:9]
	s_cbranch_vccz .LBB0_705
	s_barrier

; template <class Epi, bool ALIGN_EPI, bool SP2, class Hook>
; __device__ __forceinline__ void gemm_phase(LAS unsigned char* lds, const Gemm g, const StaticOrder& S, const Epi& E, Acc& acc, const bool fresh, const Hook& H, const int wave_id) {
;     ...
;         for (int t = t0; t < nt; t += 2) {
;             const bool last = (t == nt - 2);
;             const Src a1 = cA + (size_t)(t + 1) * kstep;
;             const Src a2 = last ? nA : cA + (size_t)(t + 2) * kstep, b2 = last ? nB : cB + (size_t)(t + 2) * kstep;
;             const Src a3 = a2 + kstep, b3 = b2 + kstep;
;             if (last && has_next) H(nxt);
.LBB0_779:
	v_add_u32_e32 v0, 0x10000, v230
	s_waitcnt vmcnt(0)
	ds_read_b128 v[130:133], v0
	ds_read_b128 v[134:137], v0 offset:1024
	ds_read_b128 v[138:141], v0 offset:2048
	ds_read_b128 v[142:145], v0 offset:3072
	v_add_u32_e32 v0, 0x14000, v230
	ds_read_b128 v[146:149], v0
	ds_read_b128 v[150:153], v0 offset:1024
	ds_read_b128 v[154:157], v0 offset:2048
	ds_read_b128 v[158:161], v0 offset:3072
	s_add_i32 s12, s2, 0xfffe0080
	s_cmp_eq_u32 s63, 4
	s_cselect_b32 s66, s60, s12
	s_cselect_b32 s13, s53, s77
	s_cselect_b32 s12, s52, s76
	s_cselect_b32 s15, s55, s7
	s_cselect_b32 s14, s54, s6
	s_cselect_b32 s64, s61, s3
	s_cselect_b32 s16, s34, s8
	s_cselect_b32 s17, s35, s9
	s_cselect_b32 s18, s50, s10
	s_cselect_b32 s19, s51, s11
	s_or_b32 s65, s66, 0x80
	s_mov_b32 m0, s45
	ds_read_b128 v[162:165], v231
	ds_read_b128 v[166:169], v231 offset:1024
	ds_read_b128 v[170:173], v231 offset:2048
	ds_read_b128 v[174:177], v231 offset:3072
	ds_read_b128 v[178:181], v231 offset:4096
	ds_read_b128 v[182:185], v231 offset:5120
	ds_read_b128 v[186:189], v231 offset:6144
	ds_read_b128 v[190:193], v231 offset:7168
	buffer_load_dwordx4 v199, s[8:11], s2 offen lds
	s_mov_b32 m0, s46
	s_nop 0
	buffer_load_dwordx4 v228, s[8:11], s2 offen lds
	s_waitcnt vmcnt(8)
	s_setprio 1
	s_barrier
	s_waitcnt lgkmcnt(0)
	v_mfma_f32_16x16x32_bf16 v[126:129], v[130:133], v[162:165], v[126:129]
	v_mfma_f32_16x16x32_bf16 v[122:125], v[138:141], v[162:165], v[122:125]
	v_mfma_f32_16x16x32_bf16 v[118:121], v[130:133], v[170:173], v[118:121]
	v_mfma_f32_16x16x32_bf16 v[114:117], v[138:141], v[170:173], v[114:117]
	v_mfma_f32_16x16x32_bf16 v[110:113], v[130:133], v[178:181], v[110:113]
	v_mfma_f32_16x16x32_bf16 v[106:109], v[138:141], v[178:181], v[106:109]
	v_mfma_f32_16x16x32_bf16 v[102:105], v[130:133], v[186:189], v[102:105]
	v_mfma_f32_16x16x32_bf16 v[98:101], v[138:141], v[186:189], v[98:101]
	v_mfma_f32_16x16x32_bf16 v[126:129], v[134:137], v[166:169], v[126:129]
	v_mfma_f32_16x16x32_bf16 v[122:125], v[142:145], v[166:169], v[122:125]
	v_mfma_f32_16x16x32_bf16 v[118:121], v[134:137], v[174:177], v[118:121]
	v_mfma_f32_16x16x32_bf16 v[114:117], v[142:145], v[174:177], v[114:117]
	v_mfma_f32_16x16x32_bf16 v[110:113], v[134:137], v[182:185], v[110:113]
	v_mfma_f32_16x16x32_bf16 v[106:109], v[142:145], v[182:185], v[106:109]
	v_mfma_f32_16x16x32_bf16 v[102:105], v[134:137], v[190:193], v[102:105]
	v_mfma_f32_16x16x32_bf16 v[98:101], v[142:145], v[190:193], v[98:101]
	v_mfma_f32_16x16x32_bf16 v[94:97], v[146:149], v[162:165], v[94:97]
	v_mfma_f32_16x16x32_bf16 v[90:93], v[154:157], v[162:165], v[90:93]
	v_mfma_f32_16x16x32_bf16 v[86:89], v[146:149], v[170:173], v[86:89]
	v_mfma_f32_16x16x32_bf16 v[82:85], v[154:157], v[170:173], v[82:85]
	v_mfma_f32_16x16x32_bf16 v[78:81], v[146:149], v[178:181], v[78:81]
	v_mfma_f32_16x16x32_bf16 v[74:77], v[154:157], v[178:181], v[74:77]
	v_mfma_f32_16x16x32_bf16 v[70:73], v[146:149], v[186:189], v[70:73]
	v_mfma_f32_16x16x32_bf16 v[66:69], v[154:157], v[186:189], v[66:69]
	v_mfma_f32_16x16x32_bf16 v[94:97], v[150:153], v[166:169], v[94:97]
	v_mfma_f32_16x16x32_bf16 v[90:93], v[158:161], v[166:169], v[90:93]
	v_mfma_f32_16x16x32_bf16 v[86:89], v[150:153], v[174:177], v[86:89]
	v_mfma_f32_16x16x32_bf16 v[82:85], v[158:161], v[174:177], v[82:85]
	v_mfma_f32_16x16x32_bf16 v[78:81], v[150:153], v[182:185], v[78:81]
	v_mfma_f32_16x16x32_bf16 v[74:77], v[158:161], v[182:185], v[74:77]
	v_mfma_f32_16x16x32_bf16 v[70:73], v[150:153], v[190:193], v[70:73]
	v_mfma_f32_16x16x32_bf16 v[66:69], v[158:161], v[190:193], v[66:69]
	s_barrier
	s_setprio 0
	s_mov_b32 m0, s92
	ds_read_b128 v[162:165], v231 offset:16384
	ds_read_b128 v[166:169], v231 offset:17408
	ds_read_b128 v[170:173], v231 offset:18432
	ds_read_b128 v[174:177], v231 offset:19456
	ds_read_b128 v[178:181], v231 offset:20480
	ds_read_b128 v[182:185], v231 offset:21504
	ds_read_b128 v[186:189], v231 offset:22528
	ds_read_b128 v[190:193], v231 offset:23552
	buffer_load_dwordx4 v227, s[12:15], s64 offen lds
	s_mov_b32 m0, s93
	s_add_i32 s67, s64, 0x20000
	buffer_load_dwordx4 v229, s[12:15], s64 offen lds
	s_mov_b32 m0, s94
	s_nop 0
	buffer_load_dwordx4 v227, s[12:15], s67 offen lds
	s_mov_b32 m0, s95
	s_nop 0
	buffer_load_dwordx4 v229, s[12:15], s67 offen lds
	s_mov_b32 m0, s44
	s_nop 0
	buffer_load_dwordx4 v199, s[16:19], s66 offen lds
	s_mov_b32 m0, s36
	s_nop 0
	buffer_load_dwordx4 v228, s[16:19], s66 offen lds
	s_waitcnt vmcnt(8)
	s_setprio 1
	s_barrier
	s_waitcnt lgkmcnt(0)
	v_mfma_f32_16x16x32_bf16 v[62:65], v[130:133], v[162:165], v[62:65]
	v_mfma_f32_16x16x32_bf16 v[58:61], v[138:141], v[162:165], v[58:61]
	v_mfma_f32_16x16x32_bf16 v[54:57], v[130:133], v[170:173], v[54:57]
	v_mfma_f32_16x16x32_bf16 v[50:53], v[138:141], v[170:173], v[50:53]
	v_mfma_f32_16x16x32_bf16 v[46:49], v[130:133], v[178:181], v[46:49]
	v_mfma_f32_16x16x32_bf16 v[42:45], v[138:141], v[178:181], v[42:45]
	v_mfma_f32_16x16x32_bf16 v[38:41], v[130:133], v[186:189], v[38:41]
	v_mfma_f32_16x16x32_bf16 v[34:37], v[138:141], v[186:189], v[34:37]
	v_mfma_f32_16x16x32_bf16 v[62:65], v[134:137], v[166:169], v[62:65]
	v_mfma_f32_16x16x32_bf16 v[58:61], v[142:145], v[166:169], v[58:61]
	v_mfma_f32_16x16x32_bf16 v[54:57], v[134:137], v[174:177], v[54:57]
	v_mfma_f32_16x16x32_bf16 v[50:53], v[142:145], v[174:177], v[50:53]
	v_mfma_f32_16x16x32_bf16 v[46:49], v[134:137], v[182:185], v[46:49]
	v_mfma_f32_16x16x32_bf16 v[42:45], v[142:145], v[182:185], v[42:45]
	v_mfma_f32_16x16x32_bf16 v[38:41], v[134:137], v[190:193], v[38:41]
	v_mfma_f32_16x16x32_bf16 v[34:37], v[142:145], v[190:193], v[34:37]
	v_mfma_f32_16x16x32_bf16 v[30:33], v[146:149], v[162:165], v[30:33]
	v_mfma_f32_16x16x32_bf16 v[26:29], v[154:157], v[162:165], v[26:29]
	v_mfma_f32_16x16x32_bf16 v[22:25], v[146:149], v[170:173], v[22:25]
	v_mfma_f32_16x16x32_bf16 v[18:21], v[154:157], v[170:173], v[18:21]
	v_mfma_f32_16x16x32_bf16 v[14:17], v[146:149], v[178:181], v[14:17]
	v_mfma_f32_16x16x32_bf16 v[10:13], v[154:157], v[178:181], v[10:13]
	v_mfma_f32_16x16x32_bf16 v[6:9], v[146:149], v[186:189], v[6:9]
	v_mfma_f32_16x16x32_bf16 v[2:5], v[154:157], v[186:189], v[2:5]
	v_mfma_f32_16x16x32_bf16 v[30:33], v[150:153], v[166:169], v[30:33]
	v_mfma_f32_16x16x32_bf16 v[26:29], v[158:161], v[166:169], v[26:29]
	v_mfma_f32_16x16x32_bf16 v[22:25], v[150:153], v[174:177], v[22:25]
	v_mfma_f32_16x16x32_bf16 v[18:21], v[158:161], v[174:177], v[18:21]
	v_mfma_f32_16x16x32_bf16 v[14:17], v[150:153], v[182:185], v[14:17]
	v_mfma_f32_16x16x32_bf16 v[10:13], v[158:161], v[182:185], v[10:13]
	v_mfma_f32_16x16x32_bf16 v[6:9], v[150:153], v[190:193], v[6:9]
	v_mfma_f32_16x16x32_bf16 v[2:5], v[158:161], v[190:193], v[2:5]
	s_barrier
; #define PG8_WAIT_V(n) asm volatile("s_waitcnt vmcnt(" #n ")" ::: "memory")
; template <class Epi, bool ALIGN_EPI, bool SP2, class Hook>
; __device__ __forceinline__ void gemm_phase(LAS unsigned char* lds, const Gemm g, const StaticOrder& S, const Epi& E, Acc& acc, const bool fresh, const Hook& H, const int wave_id) {
;     ...
;         for (int t = t0; t < nt; t += 2) {
;             const bool last = (t == nt - 2);
;             const Src a1 = cA + (size_t)(t + 1) * kstep;
;             const Src a2 = last ? nA : cA + (size_t)(t + 2) * kstep, b2 = last ? nB : cB + (size_t)(t + 2) * kstep;
;             const Src a3 = a2 + kstep, b3 = b2 + kstep;
;             if (last && has_next) H(nxt);
;             if constexpr (SP2) {
;             PG8_TRIP_SP2(PG8_WAIT_V(8));
	s_setprio 0
	v_add_u32_e32 v0, 0x18000, v230
	ds_read_b128 v[130:133], v0
	ds_read_b128 v[134:137], v0 offset:1024
	ds_read_b128 v[138:141], v0 offset:2048
	ds_read_b128 v[142:145], v0 offset:3072
	v_add_u32_e32 v0, 0x1c000, v230
	ds_read_b128 v[146:149], v0
	ds_read_b128 v[150:153], v0 offset:1024
	ds_read_b128 v[154:157], v0 offset:2048
	ds_read_b128 v[158:161], v0 offset:3072
	s_add_i32 s66, s66, 0x20000
	s_mov_b32 m0, s37
	ds_read_b128 v[162:165], v231 offset:32768
	ds_read_b128 v[166:169], v231 offset:33792
	ds_read_b128 v[170:173], v231 offset:34816
	ds_read_b128 v[174:177], v231 offset:35840
	ds_read_b128 v[178:181], v231 offset:36864
	ds_read_b128 v[182:185], v231 offset:37888
	ds_read_b128 v[186:189], v231 offset:38912
	ds_read_b128 v[190:193], v231 offset:39936
	buffer_load_dwordx4 v199, s[16:19], s66 offen lds
	s_mov_b32 m0, s38
	s_nop 0
	buffer_load_dwordx4 v228, s[16:19], s66 offen lds
	s_waitcnt vmcnt(8)
	s_setprio 1
	s_barrier
	s_waitcnt lgkmcnt(0)
	v_mfma_f32_16x16x32_bf16 v[126:129], v[130:133], v[162:165], v[126:129]
	v_mfma_f32_16x16x32_bf16 v[122:125], v[138:141], v[162:165], v[122:125]
	v_mfma_f32_16x16x32_bf16 v[118:121], v[130:133], v[170:173], v[118:121]
	v_mfma_f32_16x16x32_bf16 v[114:117], v[138:141], v[170:173], v[114:117]
	v_mfma_f32_16x16x32_bf16 v[110:113], v[130:133], v[178:181], v[110:113]
	v_mfma_f32_16x16x32_bf16 v[106:109], v[138:141], v[178:181], v[106:109]
	v_mfma_f32_16x16x32_bf16 v[102:105], v[130:133], v[186:189], v[102:105]
	v_mfma_f32_16x16x32_bf16 v[98:101], v[138:141], v[186:189], v[98:101]
	v_mfma_f32_16x16x32_bf16 v[126:129], v[134:137], v[166:169], v[126:129]
	v_mfma_f32_16x16x32_bf16 v[122:125], v[142:145], v[166:169], v[122:125]
	v_mfma_f32_16x16x32_bf16 v[118:121], v[134:137], v[174:177], v[118:121]
	v_mfma_f32_16x16x32_bf16 v[114:117], v[142:145], v[174:177], v[114:117]
	v_mfma_f32_16x16x32_bf16 v[110:113], v[134:137], v[182:185], v[110:113]
	v_mfma_f32_16x16x32_bf16 v[106:109], v[142:145], v[182:185], v[106:109]
	v_mfma_f32_16x16x32_bf16 v[102:105], v[134:137], v[190:193], v[102:105]
	v_mfma_f32_16x16x32_bf16 v[98:101], v[142:145], v[190:193], v[98:101]
	v_mfma_f32_16x16x32_bf16 v[94:97], v[146:149], v[162:165], v[94:97]
	v_mfma_f32_16x16x32_bf16 v[90:93], v[154:157], v[162:165], v[90:93]
	v_mfma_f32_16x16x32_bf16 v[86:89], v[146:149], v[170:173], v[86:89]
	v_mfma_f32_16x16x32_bf16 v[82:85], v[154:157], v[170:173], v[82:85]
	v_mfma_f32_16x16x32_bf16 v[78:81], v[146:149], v[178:181], v[78:81]
	v_mfma_f32_16x16x32_bf16 v[74:77], v[154:157], v[178:181], v[74:77]
	v_mfma_f32_16x16x32_bf16 v[70:73], v[146:149], v[186:189], v[70:73]
	v_mfma_f32_16x16x32_bf16 v[66:69], v[154:157], v[186:189], v[66:69]
	v_mfma_f32_16x16x32_bf16 v[94:97], v[150:153], v[166:169], v[94:97]
	v_mfma_f32_16x16x32_bf16 v[90:93], v[158:161], v[166:169], v[90:93]
	v_mfma_f32_16x16x32_bf16 v[86:89], v[150:153], v[174:177], v[86:89]
	v_mfma_f32_16x16x32_bf16 v[82:85], v[158:161], v[174:177], v[82:85]
	v_mfma_f32_16x16x32_bf16 v[78:81], v[150:153], v[182:185], v[78:81]
	v_mfma_f32_16x16x32_bf16 v[74:77], v[158:161], v[182:185], v[74:77]
	v_mfma_f32_16x16x32_bf16 v[70:73], v[150:153], v[190:193], v[70:73]
	v_mfma_f32_16x16x32_bf16 v[66:69], v[158:161], v[190:193], v[66:69]
	s_barrier
	s_setprio 0
	s_mov_b32 m0, s39
	s_or_b32 s66, s64, 0x80
	ds_read_b128 v[162:165], v231 offset:49152
	ds_read_b128 v[166:169], v231 offset:50176
	ds_read_b128 v[170:173], v231 offset:51200
	ds_read_b128 v[174:177], v231 offset:52224
	ds_read_b128 v[178:181], v231 offset:53248
	ds_read_b128 v[182:185], v231 offset:54272
	ds_read_b128 v[186:189], v231 offset:55296
	ds_read_b128 v[190:193], v231 offset:56320
	buffer_load_dwordx4 v227, s[12:15], s66 offen lds
	s_mov_b32 m0, s40
	s_add_i32 s64, s64, 0x20080
	buffer_load_dwordx4 v229, s[12:15], s66 offen lds
	s_mov_b32 m0, s43
	s_nop 0
	buffer_load_dwordx4 v227, s[12:15], s64 offen lds
	s_mov_b32 m0, s42
	s_nop 0
	buffer_load_dwordx4 v229, s[12:15], s64 offen lds
	s_mov_b32 m0, s41
	s_nop 0
	buffer_load_dwordx4 v199, s[16:19], s65 offen lds
	s_mov_b32 m0, s33
	s_nop 0
	buffer_load_dwordx4 v228, s[16:19], s65 offen lds
	s_waitcnt vmcnt(8)
	s_setprio 1
	s_barrier
	s_waitcnt lgkmcnt(0)
	v_mfma_f32_16x16x32_bf16 v[62:65], v[130:133], v[162:165], v[62:65]
	v_mfma_f32_16x16x32_bf16 v[58:61], v[138:141], v[162:165], v[58:61]
	v_mfma_f32_16x16x32_bf16 v[54:57], v[130:133], v[170:173], v[54:57]
	v_mfma_f32_16x16x32_bf16 v[50:53], v[138:141], v[170:173], v[50:53]
	v_mfma_f32_16x16x32_bf16 v[46:49], v[130:133], v[178:181], v[46:49]
	v_mfma_f32_16x16x32_bf16 v[42:45], v[138:141], v[178:181], v[42:45]
	v_mfma_f32_16x16x32_bf16 v[38:41], v[130:133], v[186:189], v[38:41]
	v_mfma_f32_16x16x32_bf16 v[34:37], v[138:141], v[186:189], v[34:37]
	v_mfma_f32_16x16x32_bf16 v[62:65], v[134:137], v[166:169], v[62:65]
	v_mfma_f32_16x16x32_bf16 v[58:61], v[142:145], v[166:169], v[58:61]
	v_mfma_f32_16x16x32_bf16 v[54:57], v[134:137], v[174:177], v[54:57]
	v_mfma_f32_16x16x32_bf16 v[50:53], v[142:145], v[174:177], v[50:53]
	v_mfma_f32_16x16x32_bf16 v[46:49], v[134:137], v[182:185], v[46:49]
	v_mfma_f32_16x16x32_bf16 v[42:45], v[142:145], v[182:185], v[42:45]
	v_mfma_f32_16x16x32_bf16 v[38:41], v[134:137], v[190:193], v[38:41]
	v_mfma_f32_16x16x32_bf16 v[34:37], v[142:145], v[190:193], v[34:37]
	v_mfma_f32_16x16x32_bf16 v[30:33], v[146:149], v[162:165], v[30:33]
	v_mfma_f32_16x16x32_bf16 v[26:29], v[154:157], v[162:165], v[26:29]
	v_mfma_f32_16x16x32_bf16 v[22:25], v[146:149], v[170:173], v[22:25]
	v_mfma_f32_16x16x32_bf16 v[18:21], v[154:157], v[170:173], v[18:21]
	v_mfma_f32_16x16x32_bf16 v[14:17], v[146:149], v[178:181], v[14:17]
	v_mfma_f32_16x16x32_bf16 v[10:13], v[154:157], v[178:181], v[10:13]
	v_mfma_f32_16x16x32_bf16 v[6:9], v[146:149], v[186:189], v[6:9]
	v_mfma_f32_16x16x32_bf16 v[2:5], v[154:157], v[186:189], v[2:5]
	v_mfma_f32_16x16x32_bf16 v[30:33], v[150:153], v[166:169], v[30:33]
	v_mfma_f32_16x16x32_bf16 v[26:29], v[158:161], v[166:169], v[26:29]
	v_mfma_f32_16x16x32_bf16 v[22:25], v[150:153], v[174:177], v[22:25]
	v_mfma_f32_16x16x32_bf16 v[18:21], v[158:161], v[174:177], v[18:21]
	v_mfma_f32_16x16x32_bf16 v[14:17], v[150:153], v[182:185], v[14:17]
	v_mfma_f32_16x16x32_bf16 v[10:13], v[158:161], v[182:185], v[10:13]
	v_mfma_f32_16x16x32_bf16 v[6:9], v[150:153], v[190:193], v[6:9]
	v_mfma_f32_16x16x32_bf16 v[2:5], v[158:161], v[190:193], v[2:5]
	s_barrier
	s_setprio 0
	s_add_i32 s63, s63, 2
	s_addk_i32 s2, 0x100
	s_addk_i32 s3, 0x100
	s_cmp_gt_u32 s63, 5
	s_cbranch_scc0 .LBB0_779
	v_readlane_b32 s2, v251, 45
	v_readlane_b32 s3, v251, 46
	s_and_b64 vcc, exec, s[2:3]
	s_cbranch_vccz .LBB0_782
	s_barrier

; template <class Epi, bool ALIGN_EPI, bool SP2, class Hook>
; __device__ __forceinline__ void gemm_phase(LAS unsigned char* lds, const Gemm g, const StaticOrder& S, const Epi& E, Acc& acc, const bool fresh, const Hook& H, const int wave_id) {
;     ...
;         for (int t = t0; t < nt; t += 2) {
;             const bool last = (t == nt - 2);
;             const Src a1 = cA + (size_t)(t + 1) * kstep;
;             const Src a2 = last ? nA : cA + (size_t)(t + 2) * kstep, b2 = last ? nB : cB + (size_t)(t + 2) * kstep;
;             const Src a3 = a2 + kstep, b3 = b2 + kstep;
;             if (last && has_next) H(nxt);
.LBB0_903:
	v_add_u32_e32 v70, 0x10000, v216
	v_add_u32_e32 v118, 0x14000, v216
	ds_read_b128 v[34:37], v70
	ds_read_b128 v[46:49], v70 offset:1024
	ds_read_b128 v[58:61], v70 offset:2048
	ds_read_b128 v[70:73], v70 offset:3072
	ds_read_b128 v[82:85], v118
	ds_read_b128 v[94:97], v118 offset:1024
	ds_read_b128 v[106:109], v118 offset:2048
	ds_read_b128 v[118:121], v118 offset:3072
	s_add_i32 s12, s55, 0xfffe0080
	s_cmp_eq_u32 s57, 4
	s_cselect_b32 s60, s53, s12
	s_cselect_b32 s13, s29, s77
	s_cselect_b32 s12, s28, s76
	s_cselect_b32 s15, s31, s35
	s_cselect_b32 s14, s30, s34
	s_cselect_b32 s58, s54, s56
	s_cselect_b32 s16, s2, s8
	s_cselect_b32 s17, s3, s9
	s_cselect_b32 s18, s26, s10
	s_cselect_b32 s19, s27, s11
	s_or_b32 s59, s60, 0x80
	s_mov_b32 m0, s45
	ds_read_b128 v[130:133], v217
	ds_read_b128 v[142:145], v217 offset:1024
	ds_read_b128 v[154:157], v217 offset:2048
	ds_read_b128 v[166:169], v217 offset:3072
	ds_read_b128 v[174:177], v217 offset:4096
	ds_read_b128 v[182:185], v217 offset:5120
	ds_read_b128 v[186:189], v217 offset:6144
	ds_read_b128 v[190:193], v217 offset:7168
	buffer_load_dwordx4 v0, s[8:11], s55 offen lds
	s_mov_b32 m0, s46
	s_nop 0
	buffer_load_dwordx4 v214, s[8:11], s55 offen lds
	s_waitcnt vmcnt(8)
	s_setprio 1
	s_barrier
	s_waitcnt lgkmcnt(0)
	v_mfma_f32_16x16x32_bf16 v[178:181], v[34:37], v[130:133], v[178:181]
	v_mfma_f32_16x16x32_bf16 v[170:173], v[58:61], v[130:133], v[170:173]
	v_mfma_f32_16x16x32_bf16 v[150:153], v[34:37], v[154:157], v[150:153]
	v_mfma_f32_16x16x32_bf16 v[146:149], v[58:61], v[154:157], v[146:149]
	v_mfma_f32_16x16x32_bf16 v[126:129], v[34:37], v[174:177], v[126:129]
	v_mfma_f32_16x16x32_bf16 v[122:125], v[58:61], v[174:177], v[122:125]
	v_mfma_f32_16x16x32_bf16 v[102:105], v[34:37], v[186:189], v[102:105]
	v_mfma_f32_16x16x32_bf16 v[98:101], v[58:61], v[186:189], v[98:101]
	v_mfma_f32_16x16x32_bf16 v[178:181], v[46:49], v[142:145], v[178:181]
	v_mfma_f32_16x16x32_bf16 v[170:173], v[70:73], v[142:145], v[170:173]
	v_mfma_f32_16x16x32_bf16 v[150:153], v[46:49], v[166:169], v[150:153]
	v_mfma_f32_16x16x32_bf16 v[146:149], v[70:73], v[166:169], v[146:149]
	v_mfma_f32_16x16x32_bf16 v[126:129], v[46:49], v[182:185], v[126:129]
	v_mfma_f32_16x16x32_bf16 v[122:125], v[70:73], v[182:185], v[122:125]
	v_mfma_f32_16x16x32_bf16 v[102:105], v[46:49], v[190:193], v[102:105]
	v_mfma_f32_16x16x32_bf16 v[98:101], v[70:73], v[190:193], v[98:101]
	v_mfma_f32_16x16x32_bf16 v[162:165], v[82:85], v[130:133], v[162:165]
	v_mfma_f32_16x16x32_bf16 v[138:141], v[82:85], v[154:157], v[138:141]
	v_mfma_f32_16x16x32_bf16 v[134:137], v[106:109], v[154:157], v[134:137]
	v_mfma_f32_16x16x32_bf16 v[114:117], v[82:85], v[174:177], v[114:117]
	v_mfma_f32_16x16x32_bf16 v[110:113], v[106:109], v[174:177], v[110:113]
	v_mfma_f32_16x16x32_bf16 v[90:93], v[82:85], v[186:189], v[90:93]
	v_mfma_f32_16x16x32_bf16 v[86:89], v[106:109], v[186:189], v[86:89]
	v_mfma_f32_16x16x32_bf16 v[162:165], v[94:97], v[142:145], v[162:165]
	v_mfma_f32_16x16x32_bf16 v[130:133], v[106:109], v[130:133], v[158:161]
	v_mfma_f32_16x16x32_bf16 v[138:141], v[94:97], v[166:169], v[138:141]
	v_mfma_f32_16x16x32_bf16 v[134:137], v[118:121], v[166:169], v[134:137]
	v_mfma_f32_16x16x32_bf16 v[114:117], v[94:97], v[182:185], v[114:117]
	v_mfma_f32_16x16x32_bf16 v[110:113], v[118:121], v[182:185], v[110:113]
	v_mfma_f32_16x16x32_bf16 v[90:93], v[94:97], v[190:193], v[90:93]
	v_mfma_f32_16x16x32_bf16 v[86:89], v[118:121], v[190:193], v[86:89]
	v_mfma_f32_16x16x32_bf16 v[130:133], v[118:121], v[142:145], v[130:133]
	s_barrier
	s_setprio 0
	s_mov_b32 m0, s92
	ds_read_b128 v[142:145], v217 offset:16384
	ds_read_b128 v[154:157], v217 offset:17408
	ds_read_b128 v[158:161], v217 offset:18432
	ds_read_b128 v[166:169], v217 offset:19456
	ds_read_b128 v[174:177], v217 offset:20480
	ds_read_b128 v[182:185], v217 offset:21504
	ds_read_b128 v[186:189], v217 offset:22528
	ds_read_b128 v[190:193], v217 offset:23552
	buffer_load_dwordx4 v199, s[12:15], s58 offen lds
	s_mov_b32 m0, s93
	s_add_i32 s61, s58, 0x20000
	buffer_load_dwordx4 v215, s[12:15], s58 offen lds
	s_mov_b32 m0, s94
	s_nop 0
	buffer_load_dwordx4 v199, s[12:15], s61 offen lds
	s_mov_b32 m0, s95
	s_nop 0
	buffer_load_dwordx4 v215, s[12:15], s61 offen lds
	s_mov_b32 m0, s44
	s_nop 0
	buffer_load_dwordx4 v0, s[16:19], s60 offen lds
	s_mov_b32 m0, s36
	s_nop 0
	buffer_load_dwordx4 v214, s[16:19], s60 offen lds
	s_waitcnt vmcnt(8)
	s_setprio 1
	s_barrier
	s_waitcnt lgkmcnt(0)
	v_mfma_f32_16x16x32_bf16 v[78:81], v[34:37], v[142:145], v[78:81]
	v_mfma_f32_16x16x32_bf16 v[74:77], v[58:61], v[142:145], v[74:77]
	v_mfma_f32_16x16x32_bf16 v[54:57], v[34:37], v[158:161], v[54:57]
	v_mfma_f32_16x16x32_bf16 v[50:53], v[58:61], v[158:161], v[50:53]
	v_mfma_f32_16x16x32_bf16 v[30:33], v[34:37], v[174:177], v[30:33]
	v_mfma_f32_16x16x32_bf16 v[26:29], v[58:61], v[174:177], v[26:29]
	v_mfma_f32_16x16x32_bf16 v[14:17], v[34:37], v[186:189], v[14:17]
	v_mfma_f32_16x16x32_bf16 v[10:13], v[58:61], v[186:189], v[10:13]
	v_mfma_f32_16x16x32_bf16 v[78:81], v[46:49], v[154:157], v[78:81]
	v_mfma_f32_16x16x32_bf16 v[74:77], v[70:73], v[154:157], v[74:77]
	v_mfma_f32_16x16x32_bf16 v[54:57], v[46:49], v[166:169], v[54:57]
	v_mfma_f32_16x16x32_bf16 v[50:53], v[70:73], v[166:169], v[50:53]
	v_mfma_f32_16x16x32_bf16 v[30:33], v[46:49], v[182:185], v[30:33]
	v_mfma_f32_16x16x32_bf16 v[26:29], v[70:73], v[182:185], v[26:29]
	v_mfma_f32_16x16x32_bf16 v[14:17], v[46:49], v[190:193], v[14:17]
	v_mfma_f32_16x16x32_bf16 v[10:13], v[70:73], v[190:193], v[10:13]
	v_mfma_f32_16x16x32_bf16 v[42:45], v[82:85], v[158:161], v[42:45]
	v_mfma_f32_16x16x32_bf16 v[38:41], v[106:109], v[158:161], v[38:41]
	v_mfma_f32_16x16x32_bf16 v[22:25], v[82:85], v[174:177], v[22:25]
	v_mfma_f32_16x16x32_bf16 v[18:21], v[106:109], v[174:177], v[18:21]
	v_mfma_f32_16x16x32_bf16 v[6:9], v[82:85], v[186:189], v[6:9]
	v_mfma_f32_16x16x32_bf16 v[2:5], v[106:109], v[186:189], v[2:5]
	v_mfma_f32_16x16x32_bf16 v[34:37], v[82:85], v[142:145], v[66:69]
	v_mfma_f32_16x16x32_bf16 v[46:49], v[106:109], v[142:145], v[62:65]
	v_mfma_f32_16x16x32_bf16 v[42:45], v[94:97], v[166:169], v[42:45]
	v_mfma_f32_16x16x32_bf16 v[38:41], v[118:121], v[166:169], v[38:41]
	v_mfma_f32_16x16x32_bf16 v[22:25], v[94:97], v[182:185], v[22:25]
	v_mfma_f32_16x16x32_bf16 v[18:21], v[118:121], v[182:185], v[18:21]
	v_mfma_f32_16x16x32_bf16 v[6:9], v[94:97], v[190:193], v[6:9]
	v_mfma_f32_16x16x32_bf16 v[2:5], v[118:121], v[190:193], v[2:5]
	v_mfma_f32_16x16x32_bf16 v[34:37], v[94:97], v[154:157], v[34:37]
	v_mfma_f32_16x16x32_bf16 v[46:49], v[118:121], v[154:157], v[46:49]
	s_barrier
; #define PG8_WAIT_V(n) asm volatile("s_waitcnt vmcnt(" #n ")" ::: "memory")
; template <class Epi, bool ALIGN_EPI, bool SP2, class Hook>
; __device__ __forceinline__ void gemm_phase(LAS unsigned char* lds, const Gemm g, const StaticOrder& S, const Epi& E, Acc& acc, const bool fresh, const Hook& H, const int wave_id) {
;     ...
;         for (int t = t0; t < nt; t += 2) {
;             const bool last = (t == nt - 2);
;             const Src a1 = cA + (size_t)(t + 1) * kstep;
;             const Src a2 = last ? nA : cA + (size_t)(t + 2) * kstep, b2 = last ? nB : cB + (size_t)(t + 2) * kstep;
;             const Src a3 = a2 + kstep, b3 = b2 + kstep;
;             if (last && has_next) H(nxt);
;             if constexpr (SP2) {
;             PG8_TRIP_SP2(PG8_WAIT_V(8));
	s_setprio 0
	v_add_u32_e32 v70, 0x18000, v216
	v_add_u32_e32 v118, 0x1c000, v216
	ds_read_b128 v[58:61], v70
	ds_read_b128 v[62:65], v70 offset:1024
	ds_read_b128 v[66:69], v70 offset:2048
	ds_read_b128 v[70:73], v70 offset:3072
	ds_read_b128 v[82:85], v118
	ds_read_b128 v[94:97], v118 offset:1024
	ds_read_b128 v[106:109], v118 offset:2048
	ds_read_b128 v[118:121], v118 offset:3072
	s_add_i32 s60, s60, 0x20000
	s_mov_b32 m0, s37
	ds_read_b128 v[142:145], v217 offset:32768
	ds_read_b128 v[154:157], v217 offset:33792
	ds_read_b128 v[166:169], v217 offset:34816
	ds_read_b128 v[174:177], v217 offset:35840
	ds_read_b128 v[182:185], v217 offset:36864
	ds_read_b128 v[186:189], v217 offset:37888
	ds_read_b128 v[190:193], v217 offset:38912
	ds_read_b128 v[194:197], v217 offset:39936
	buffer_load_dwordx4 v0, s[16:19], s60 offen lds
	s_mov_b32 m0, s38
	s_nop 0
	buffer_load_dwordx4 v214, s[16:19], s60 offen lds
	s_waitcnt vmcnt(8)
	s_setprio 1
	s_barrier
	s_waitcnt lgkmcnt(0)
	v_mfma_f32_16x16x32_bf16 v[158:161], v[58:61], v[142:145], v[178:181]
	v_mfma_f32_16x16x32_bf16 v[178:181], v[62:65], v[154:157], v[158:161]
	v_mfma_f32_16x16x32_bf16 v[158:161], v[66:69], v[142:145], v[170:173]
	v_mfma_f32_16x16x32_bf16 v[150:153], v[58:61], v[166:169], v[150:153]
	v_mfma_f32_16x16x32_bf16 v[146:149], v[66:69], v[166:169], v[146:149]
	v_mfma_f32_16x16x32_bf16 v[126:129], v[58:61], v[182:185], v[126:129]
	v_mfma_f32_16x16x32_bf16 v[122:125], v[66:69], v[182:185], v[122:125]
	v_mfma_f32_16x16x32_bf16 v[102:105], v[58:61], v[190:193], v[102:105]
	v_mfma_f32_16x16x32_bf16 v[98:101], v[66:69], v[190:193], v[98:101]
	v_mfma_f32_16x16x32_bf16 v[170:173], v[70:73], v[154:157], v[158:161]
	v_mfma_f32_16x16x32_bf16 v[150:153], v[62:65], v[174:177], v[150:153]
	v_mfma_f32_16x16x32_bf16 v[146:149], v[70:73], v[174:177], v[146:149]
	v_mfma_f32_16x16x32_bf16 v[126:129], v[62:65], v[186:189], v[126:129]
	v_mfma_f32_16x16x32_bf16 v[122:125], v[70:73], v[186:189], v[122:125]
	v_mfma_f32_16x16x32_bf16 v[102:105], v[62:65], v[194:197], v[102:105]
	v_mfma_f32_16x16x32_bf16 v[98:101], v[70:73], v[194:197], v[98:101]
	v_mfma_f32_16x16x32_bf16 v[158:161], v[82:85], v[142:145], v[162:165]
	v_mfma_f32_16x16x32_bf16 v[130:133], v[106:109], v[142:145], v[130:133]
	v_mfma_f32_16x16x32_bf16 v[162:165], v[94:97], v[154:157], v[158:161]
	v_mfma_f32_16x16x32_bf16 v[158:161], v[118:121], v[154:157], v[130:133]
	v_mfma_f32_16x16x32_bf16 v[130:133], v[82:85], v[166:169], v[138:141]
	v_mfma_f32_16x16x32_bf16 v[138:141], v[94:97], v[174:177], v[130:133]
	v_mfma_f32_16x16x32_bf16 v[130:133], v[106:109], v[166:169], v[134:137]
	v_mfma_f32_16x16x32_bf16 v[114:117], v[82:85], v[182:185], v[114:117]
	v_mfma_f32_16x16x32_bf16 v[110:113], v[106:109], v[182:185], v[110:113]
	v_mfma_f32_16x16x32_bf16 v[90:93], v[82:85], v[190:193], v[90:93]
	v_mfma_f32_16x16x32_bf16 v[86:89], v[106:109], v[190:193], v[86:89]
	v_mfma_f32_16x16x32_bf16 v[134:137], v[118:121], v[174:177], v[130:133]
	v_mfma_f32_16x16x32_bf16 v[114:117], v[94:97], v[186:189], v[114:117]
	v_mfma_f32_16x16x32_bf16 v[110:113], v[118:121], v[186:189], v[110:113]
	v_mfma_f32_16x16x32_bf16 v[90:93], v[94:97], v[194:197], v[90:93]
	v_mfma_f32_16x16x32_bf16 v[86:89], v[118:121], v[194:197], v[86:89]
	s_barrier
	s_setprio 0
	s_mov_b32 m0, s39
	s_or_b32 s60, s58, 0x80
	ds_read_b128 v[130:133], v217 offset:49152
	ds_read_b128 v[142:145], v217 offset:50176
	ds_read_b128 v[154:157], v217 offset:51200
	ds_read_b128 v[166:169], v217 offset:52224
	ds_read_b128 v[174:177], v217 offset:53248
	ds_read_b128 v[182:185], v217 offset:54272
	ds_read_b128 v[186:189], v217 offset:55296
	ds_read_b128 v[190:193], v217 offset:56320
	buffer_load_dwordx4 v199, s[12:15], s60 offen lds
	s_mov_b32 m0, s40
	s_add_i32 s58, s58, 0x20080
	buffer_load_dwordx4 v215, s[12:15], s60 offen lds
	s_mov_b32 m0, s43
	s_nop 0
	buffer_load_dwordx4 v199, s[12:15], s58 offen lds
	s_mov_b32 m0, s42
	s_nop 0
	buffer_load_dwordx4 v215, s[12:15], s58 offen lds
	s_mov_b32 m0, s41
	s_nop 0
	buffer_load_dwordx4 v0, s[16:19], s59 offen lds
	s_mov_b32 m0, s33
	s_nop 0
	buffer_load_dwordx4 v214, s[16:19], s59 offen lds
	s_waitcnt vmcnt(8)
	s_setprio 1
	s_barrier
	s_waitcnt lgkmcnt(0)
	v_mfma_f32_16x16x32_bf16 v[78:81], v[58:61], v[130:133], v[78:81]
	v_mfma_f32_16x16x32_bf16 v[74:77], v[66:69], v[130:133], v[74:77]
	v_mfma_f32_16x16x32_bf16 v[54:57], v[58:61], v[154:157], v[54:57]
	v_mfma_f32_16x16x32_bf16 v[50:53], v[66:69], v[154:157], v[50:53]
	v_mfma_f32_16x16x32_bf16 v[30:33], v[58:61], v[174:177], v[30:33]
	v_mfma_f32_16x16x32_bf16 v[26:29], v[66:69], v[174:177], v[26:29]
	v_mfma_f32_16x16x32_bf16 v[14:17], v[58:61], v[186:189], v[14:17]
	v_mfma_f32_16x16x32_bf16 v[10:13], v[66:69], v[186:189], v[10:13]
	v_mfma_f32_16x16x32_bf16 v[78:81], v[62:65], v[142:145], v[78:81]
	v_mfma_f32_16x16x32_bf16 v[74:77], v[70:73], v[142:145], v[74:77]
	v_mfma_f32_16x16x32_bf16 v[54:57], v[62:65], v[166:169], v[54:57]
	v_mfma_f32_16x16x32_bf16 v[50:53], v[70:73], v[166:169], v[50:53]
	v_mfma_f32_16x16x32_bf16 v[30:33], v[62:65], v[182:185], v[30:33]
	v_mfma_f32_16x16x32_bf16 v[26:29], v[70:73], v[182:185], v[26:29]
	v_mfma_f32_16x16x32_bf16 v[14:17], v[62:65], v[190:193], v[14:17]
	v_mfma_f32_16x16x32_bf16 v[10:13], v[70:73], v[190:193], v[10:13]
	v_mfma_f32_16x16x32_bf16 v[34:37], v[82:85], v[130:133], v[34:37]
	v_mfma_f32_16x16x32_bf16 v[66:69], v[94:97], v[142:145], v[34:37]
	v_mfma_f32_16x16x32_bf16 v[34:37], v[106:109], v[130:133], v[46:49]
	v_mfma_f32_16x16x32_bf16 v[62:65], v[118:121], v[142:145], v[34:37]
	v_mfma_f32_16x16x32_bf16 v[34:37], v[82:85], v[154:157], v[42:45]
	v_mfma_f32_16x16x32_bf16 v[42:45], v[94:97], v[166:169], v[34:37]
	v_mfma_f32_16x16x32_bf16 v[34:37], v[106:109], v[154:157], v[38:41]
	v_mfma_f32_16x16x32_bf16 v[22:25], v[82:85], v[174:177], v[22:25]
	v_mfma_f32_16x16x32_bf16 v[18:21], v[106:109], v[174:177], v[18:21]
	v_mfma_f32_16x16x32_bf16 v[6:9], v[82:85], v[186:189], v[6:9]
	v_mfma_f32_16x16x32_bf16 v[2:5], v[106:109], v[186:189], v[2:5]
	v_mfma_f32_16x16x32_bf16 v[38:41], v[118:121], v[166:169], v[34:37]
	v_mfma_f32_16x16x32_bf16 v[22:25], v[94:97], v[182:185], v[22:25]
	v_mfma_f32_16x16x32_bf16 v[18:21], v[118:121], v[182:185], v[18:21]
	v_mfma_f32_16x16x32_bf16 v[6:9], v[94:97], v[190:193], v[6:9]
	v_mfma_f32_16x16x32_bf16 v[2:5], v[118:121], v[190:193], v[2:5]
	s_barrier
	s_setprio 0
	s_add_i32 s57, s57, 2
	s_addk_i32 s55, 0x100
	s_addk_i32 s56, 0x100
	s_cmp_gt_u32 s57, 5
	s_cbranch_scc0 .LBB0_903
	v_readlane_b32 s8, v251, 45
	v_readlane_b32 s9, v251, 46
	s_and_b64 vcc, exec, s[8:9]
	s_cbranch_vccz .LBB0_906
	s_barrier

; __device__ __forceinline__ const bf16_t* selA(const Gemm& g, int s) { return sel3(g.A0, g.A1, g.A2, s); }
; __device__ __forceinline__ const bf16_t* selB(const Gemm& g, int s) { return sel3(g.B0, g.B1, g.B2, s); }
; __device__ __forceinline__ Src make_src(const bf16_t* p, size_t off) { Src s_; s_.r = __builtin_amdgcn_make_buffer_rsrc((void*)p, (short)0, 0x7fffffff, 0x00020000); s_.o = (unsigned)off; return s_; }
; template <class Epi, bool ALIGN_EPI, bool SP2, class Hook>
; __device__ __forceinline__ void gemm_phase(LAS unsigned char* lds, const Gemm g, const StaticOrder& S, const Epi& E, Acc& acc, const bool fresh, const Hook& H, const int wave_id) {
;     ...
;         const bool has_next = S.next(ui + 1, nxt);
;         const Src nA = has_next ? make_src(selA(g, nxt.seg), (size_t)nxt.pm * tstepA) : cA, nB = has_next ? make_src(selB(g, nxt.seg), (size_t)nxt.pn * tstep) : cB;
;         for (int t = t0; t < nt; t += 2) {
;             const bool last = (t == nt - 2);
;             const Src a1 = cA + (size_t)(t + 1) * kstep;
;             const Src a2 = last ? nA : cA + (size_t)(t + 2) * kstep, b2 = last ? nB : cB + (size_t)(t + 2) * kstep;
;             const Src a3 = a2 + kstep, b3 = b2 + kstep;
;             if (last && has_next) H(nxt);
.LBB0_1029:
.LBB0_1030:
	v_add_u32_e32 v0, 0x10000, v230
	s_waitcnt vmcnt(0)
	ds_read_b128 v[130:133], v0
	ds_read_b128 v[134:137], v0 offset:1024
	ds_read_b128 v[138:141], v0 offset:2048
	ds_read_b128 v[142:145], v0 offset:3072
	v_add_u32_e32 v0, 0x14000, v230
	ds_read_b128 v[146:149], v0
	ds_read_b128 v[150:153], v0 offset:1024
	ds_read_b128 v[154:157], v0 offset:2048
	ds_read_b128 v[158:161], v0 offset:3072
	s_lshl_b32 s55, s20, 7
	s_add_i32 s18, s73, s55
	s_and_b64 s[12:13], s[16:17], exec
	s_cselect_b32 s13, s31, s9
	s_cselect_b32 s12, s30, s8
	s_cselect_b32 s15, s35, s11
	s_cselect_b32 s14, s34, s10
	s_cselect_b32 s56, s68, s18
	s_add_i32 s21, s74, s55
	s_and_b64 s[16:17], s[16:17], exec
	s_cselect_b32 s54, s69, s21
	s_cselect_b32 s17, s51, s77
	s_cselect_b32 s16, s50, s76
	s_cselect_b32 s19, s53, s7
	s_cselect_b32 s18, s52, s6
	s_or_b32 s21, s56, 0x80
	s_or_b32 s57, s54, 0x80
	s_add_i32 s55, s55, s75
	s_mov_b32 m0, s45
	ds_read_b128 v[162:165], v231
	ds_read_b128 v[166:169], v231 offset:1024
	ds_read_b128 v[170:173], v231 offset:2048
	ds_read_b128 v[174:177], v231 offset:3072
	ds_read_b128 v[178:181], v231 offset:4096
	ds_read_b128 v[182:185], v231 offset:5120
	ds_read_b128 v[186:189], v231 offset:6144
	ds_read_b128 v[190:193], v231 offset:7168
	buffer_load_dwordx4 v199, s[8:11], s55 offen lds
	s_mov_b32 m0, s46
	s_nop 0
	buffer_load_dwordx4 v228, s[8:11], s55 offen lds
	s_waitcnt vmcnt(8)
	s_setprio 1
	s_barrier
	s_waitcnt lgkmcnt(0)
	v_mfma_f32_16x16x32_bf16 v[126:129], v[130:133], v[162:165], v[126:129]
	v_mfma_f32_16x16x32_bf16 v[122:125], v[138:141], v[162:165], v[122:125]
	v_mfma_f32_16x16x32_bf16 v[118:121], v[130:133], v[170:173], v[118:121]
	v_mfma_f32_16x16x32_bf16 v[114:117], v[138:141], v[170:173], v[114:117]
	v_mfma_f32_16x16x32_bf16 v[110:113], v[130:133], v[178:181], v[110:113]
	v_mfma_f32_16x16x32_bf16 v[106:109], v[138:141], v[178:181], v[106:109]
	v_mfma_f32_16x16x32_bf16 v[102:105], v[130:133], v[186:189], v[102:105]
	v_mfma_f32_16x16x32_bf16 v[98:101], v[138:141], v[186:189], v[98:101]
	v_mfma_f32_16x16x32_bf16 v[126:129], v[134:137], v[166:169], v[126:129]
	v_mfma_f32_16x16x32_bf16 v[122:125], v[142:145], v[166:169], v[122:125]
	v_mfma_f32_16x16x32_bf16 v[118:121], v[134:137], v[174:177], v[118:121]
	v_mfma_f32_16x16x32_bf16 v[114:117], v[142:145], v[174:177], v[114:117]
	v_mfma_f32_16x16x32_bf16 v[110:113], v[134:137], v[182:185], v[110:113]
	v_mfma_f32_16x16x32_bf16 v[106:109], v[142:145], v[182:185], v[106:109]
	v_mfma_f32_16x16x32_bf16 v[102:105], v[134:137], v[190:193], v[102:105]
	v_mfma_f32_16x16x32_bf16 v[98:101], v[142:145], v[190:193], v[98:101]
	v_mfma_f32_16x16x32_bf16 v[94:97], v[146:149], v[162:165], v[94:97]
	v_mfma_f32_16x16x32_bf16 v[90:93], v[154:157], v[162:165], v[90:93]
	v_mfma_f32_16x16x32_bf16 v[86:89], v[146:149], v[170:173], v[86:89]
	v_mfma_f32_16x16x32_bf16 v[82:85], v[154:157], v[170:173], v[82:85]
	v_mfma_f32_16x16x32_bf16 v[78:81], v[146:149], v[178:181], v[78:81]
	v_mfma_f32_16x16x32_bf16 v[74:77], v[154:157], v[178:181], v[74:77]
	v_mfma_f32_16x16x32_bf16 v[70:73], v[146:149], v[186:189], v[70:73]
	v_mfma_f32_16x16x32_bf16 v[66:69], v[154:157], v[186:189], v[66:69]
	v_mfma_f32_16x16x32_bf16 v[94:97], v[150:153], v[166:169], v[94:97]
	v_mfma_f32_16x16x32_bf16 v[90:93], v[158:161], v[166:169], v[90:93]
	v_mfma_f32_16x16x32_bf16 v[86:89], v[150:153], v[174:177], v[86:89]
	v_mfma_f32_16x16x32_bf16 v[82:85], v[158:161], v[174:177], v[82:85]
	v_mfma_f32_16x16x32_bf16 v[78:81], v[150:153], v[182:185], v[78:81]
	v_mfma_f32_16x16x32_bf16 v[74:77], v[158:161], v[182:185], v[74:77]
	v_mfma_f32_16x16x32_bf16 v[70:73], v[150:153], v[190:193], v[70:73]
	v_mfma_f32_16x16x32_bf16 v[66:69], v[158:161], v[190:193], v[66:69]
	s_barrier
	s_setprio 0
	s_mov_b32 m0, s92
	ds_read_b128 v[162:165], v231 offset:16384
	ds_read_b128 v[166:169], v231 offset:17408
	ds_read_b128 v[170:173], v231 offset:18432
	ds_read_b128 v[174:177], v231 offset:19456
	ds_read_b128 v[178:181], v231 offset:20480
	ds_read_b128 v[182:185], v231 offset:21504
	ds_read_b128 v[186:189], v231 offset:22528
	ds_read_b128 v[190:193], v231 offset:23552
	buffer_load_dwordx4 v227, s[16:19], s54 offen lds
	s_mov_b32 m0, s93
	s_add_i32 s55, s54, 0x20000
	buffer_load_dwordx4 v229, s[16:19], s54 offen lds
	s_mov_b32 m0, s94
	s_nop 0
	buffer_load_dwordx4 v227, s[16:19], s55 offen lds
	s_mov_b32 m0, s95
	s_nop 0
	buffer_load_dwordx4 v229, s[16:19], s55 offen lds
	s_mov_b32 m0, s44
	s_nop 0
	buffer_load_dwordx4 v199, s[12:15], s56 offen lds
	s_mov_b32 m0, s36
	s_nop 0
	buffer_load_dwordx4 v228, s[12:15], s56 offen lds
	s_waitcnt vmcnt(8)
	s_setprio 1
	s_barrier
	s_waitcnt lgkmcnt(0)
	v_mfma_f32_16x16x32_bf16 v[62:65], v[130:133], v[162:165], v[62:65]
	v_mfma_f32_16x16x32_bf16 v[58:61], v[138:141], v[162:165], v[58:61]
	v_mfma_f32_16x16x32_bf16 v[54:57], v[130:133], v[170:173], v[54:57]
	v_mfma_f32_16x16x32_bf16 v[50:53], v[138:141], v[170:173], v[50:53]
	v_mfma_f32_16x16x32_bf16 v[46:49], v[130:133], v[178:181], v[46:49]
	v_mfma_f32_16x16x32_bf16 v[42:45], v[138:141], v[178:181], v[42:45]
	v_mfma_f32_16x16x32_bf16 v[38:41], v[130:133], v[186:189], v[38:41]
	v_mfma_f32_16x16x32_bf16 v[34:37], v[138:141], v[186:189], v[34:37]
	v_mfma_f32_16x16x32_bf16 v[62:65], v[134:137], v[166:169], v[62:65]
	v_mfma_f32_16x16x32_bf16 v[58:61], v[142:145], v[166:169], v[58:61]
	v_mfma_f32_16x16x32_bf16 v[54:57], v[134:137], v[174:177], v[54:57]
	v_mfma_f32_16x16x32_bf16 v[50:53], v[142:145], v[174:177], v[50:53]
	v_mfma_f32_16x16x32_bf16 v[46:49], v[134:137], v[182:185], v[46:49]
	v_mfma_f32_16x16x32_bf16 v[42:45], v[142:145], v[182:185], v[42:45]
	v_mfma_f32_16x16x32_bf16 v[38:41], v[134:137], v[190:193], v[38:41]
	v_mfma_f32_16x16x32_bf16 v[34:37], v[142:145], v[190:193], v[34:37]
	v_mfma_f32_16x16x32_bf16 v[30:33], v[146:149], v[162:165], v[30:33]
	v_mfma_f32_16x16x32_bf16 v[26:29], v[154:157], v[162:165], v[26:29]
	v_mfma_f32_16x16x32_bf16 v[22:25], v[146:149], v[170:173], v[22:25]
	v_mfma_f32_16x16x32_bf16 v[18:21], v[154:157], v[170:173], v[18:21]
	v_mfma_f32_16x16x32_bf16 v[14:17], v[146:149], v[178:181], v[14:17]
	v_mfma_f32_16x16x32_bf16 v[10:13], v[154:157], v[178:181], v[10:13]
	v_mfma_f32_16x16x32_bf16 v[6:9], v[146:149], v[186:189], v[6:9]
	v_mfma_f32_16x16x32_bf16 v[2:5], v[154:157], v[186:189], v[2:5]
	v_mfma_f32_16x16x32_bf16 v[30:33], v[150:153], v[166:169], v[30:33]
	v_mfma_f32_16x16x32_bf16 v[26:29], v[158:161], v[166:169], v[26:29]
	v_mfma_f32_16x16x32_bf16 v[22:25], v[150:153], v[174:177], v[22:25]
	v_mfma_f32_16x16x32_bf16 v[18:21], v[158:161], v[174:177], v[18:21]
	v_mfma_f32_16x16x32_bf16 v[14:17], v[150:153], v[182:185], v[14:17]
	v_mfma_f32_16x16x32_bf16 v[10:13], v[158:161], v[182:185], v[10:13]
	v_mfma_f32_16x16x32_bf16 v[6:9], v[150:153], v[190:193], v[6:9]
	v_mfma_f32_16x16x32_bf16 v[2:5], v[158:161], v[190:193], v[2:5]
	s_barrier
	s_setprio 0
	v_add_u32_e32 v0, 0x18000, v230
	ds_read_b128 v[130:133], v0
	ds_read_b128 v[134:137], v0 offset:1024
	ds_read_b128 v[138:141], v0 offset:2048
	ds_read_b128 v[142:145], v0 offset:3072
	v_add_u32_e32 v0, 0x1c000, v230
	ds_read_b128 v[146:149], v0
	ds_read_b128 v[150:153], v0 offset:1024
	ds_read_b128 v[154:157], v0 offset:2048
	ds_read_b128 v[158:161], v0 offset:3072
	s_add_i32 s56, s56, 0x20000
	s_mov_b32 m0, s37
	ds_read_b128 v[162:165], v231 offset:32768
	ds_read_b128 v[166:169], v231 offset:33792
	ds_read_b128 v[170:173], v231 offset:34816
	ds_read_b128 v[174:177], v231 offset:35840
	ds_read_b128 v[178:181], v231 offset:36864
	ds_read_b128 v[182:185], v231 offset:37888
	ds_read_b128 v[186:189], v231 offset:38912
	ds_read_b128 v[190:193], v231 offset:39936
	buffer_load_dwordx4 v199, s[12:15], s56 offen lds
	s_mov_b32 m0, s38
	s_nop 0
	buffer_load_dwordx4 v228, s[12:15], s56 offen lds
	s_waitcnt vmcnt(8)
	s_setprio 1
	s_barrier
	s_waitcnt lgkmcnt(0)
	v_mfma_f32_16x16x32_bf16 v[126:129], v[130:133], v[162:165], v[126:129]
	v_mfma_f32_16x16x32_bf16 v[122:125], v[138:141], v[162:165], v[122:125]
	v_mfma_f32_16x16x32_bf16 v[118:121], v[130:133], v[170:173], v[118:121]
	v_mfma_f32_16x16x32_bf16 v[114:117], v[138:141], v[170:173], v[114:117]
	v_mfma_f32_16x16x32_bf16 v[110:113], v[130:133], v[178:181], v[110:113]
	v_mfma_f32_16x16x32_bf16 v[106:109], v[138:141], v[178:181], v[106:109]
	v_mfma_f32_16x16x32_bf16 v[102:105], v[130:133], v[186:189], v[102:105]
	v_mfma_f32_16x16x32_bf16 v[98:101], v[138:141], v[186:189], v[98:101]
	v_mfma_f32_16x16x32_bf16 v[126:129], v[134:137], v[166:169], v[126:129]
	v_mfma_f32_16x16x32_bf16 v[122:125], v[142:145], v[166:169], v[122:125]
	v_mfma_f32_16x16x32_bf16 v[118:121], v[134:137], v[174:177], v[118:121]
	v_mfma_f32_16x16x32_bf16 v[114:117], v[142:145], v[174:177], v[114:117]
	v_mfma_f32_16x16x32_bf16 v[110:113], v[134:137], v[182:185], v[110:113]
	v_mfma_f32_16x16x32_bf16 v[106:109], v[142:145], v[182:185], v[106:109]
	v_mfma_f32_16x16x32_bf16 v[102:105], v[134:137], v[190:193], v[102:105]
	v_mfma_f32_16x16x32_bf16 v[98:101], v[142:145], v[190:193], v[98:101]
	v_mfma_f32_16x16x32_bf16 v[94:97], v[146:149], v[162:165], v[94:97]
	v_mfma_f32_16x16x32_bf16 v[90:93], v[154:157], v[162:165], v[90:93]
	v_mfma_f32_16x16x32_bf16 v[86:89], v[146:149], v[170:173], v[86:89]
	v_mfma_f32_16x16x32_bf16 v[82:85], v[154:157], v[170:173], v[82:85]
	v_mfma_f32_16x16x32_bf16 v[78:81], v[146:149], v[178:181], v[78:81]
	v_mfma_f32_16x16x32_bf16 v[74:77], v[154:157], v[178:181], v[74:77]
	v_mfma_f32_16x16x32_bf16 v[70:73], v[146:149], v[186:189], v[70:73]
	v_mfma_f32_16x16x32_bf16 v[66:69], v[154:157], v[186:189], v[66:69]
	v_mfma_f32_16x16x32_bf16 v[94:97], v[150:153], v[166:169], v[94:97]
	v_mfma_f32_16x16x32_bf16 v[90:93], v[158:161], v[166:169], v[90:93]
	v_mfma_f32_16x16x32_bf16 v[86:89], v[150:153], v[174:177], v[86:89]
	v_mfma_f32_16x16x32_bf16 v[82:85], v[158:161], v[174:177], v[82:85]
	v_mfma_f32_16x16x32_bf16 v[78:81], v[150:153], v[182:185], v[78:81]
	v_mfma_f32_16x16x32_bf16 v[74:77], v[158:161], v[182:185], v[74:77]
	v_mfma_f32_16x16x32_bf16 v[70:73], v[150:153], v[190:193], v[70:73]
	v_mfma_f32_16x16x32_bf16 v[66:69], v[158:161], v[190:193], v[66:69]
	s_barrier
; #define PG8_WAIT_V(n) asm volatile("s_waitcnt vmcnt(" #n ")" ::: "memory")
; template <class Epi, bool ALIGN_EPI, bool SP2, class Hook>
; __device__ __forceinline__ void gemm_phase(LAS unsigned char* lds, const Gemm g, const StaticOrder& S, const Epi& E, Acc& acc, const bool fresh, const Hook& H, const int wave_id) {
;     ...
;         for (int t = t0; t < nt; t += 2) {
;             const bool last = (t == nt - 2);
;             const Src a1 = cA + (size_t)(t + 1) * kstep;
;             const Src a2 = last ? nA : cA + (size_t)(t + 2) * kstep, b2 = last ? nB : cB + (size_t)(t + 2) * kstep;
;             const Src a3 = a2 + kstep, b3 = b2 + kstep;
;             if (last && has_next) H(nxt);
;             if constexpr (SP2) {
;             PG8_TRIP_SP2(PG8_WAIT_V(8));
	s_setprio 0
	s_mov_b32 m0, s39
	ds_read_b128 v[162:165], v231 offset:49152
	ds_read_b128 v[166:169], v231 offset:50176
	ds_read_b128 v[170:173], v231 offset:51200
	ds_read_b128 v[174:177], v231 offset:52224
	ds_read_b128 v[178:181], v231 offset:53248
	ds_read_b128 v[182:185], v231 offset:54272
	ds_read_b128 v[186:189], v231 offset:55296
	ds_read_b128 v[190:193], v231 offset:56320
	buffer_load_dwordx4 v227, s[16:19], s57 offen lds
	s_mov_b32 m0, s40
	s_add_i32 s54, s54, 0x20080
	buffer_load_dwordx4 v229, s[16:19], s57 offen lds
	s_mov_b32 m0, s43
	s_nop 0
	buffer_load_dwordx4 v227, s[16:19], s54 offen lds
	s_mov_b32 m0, s42
	s_nop 0
	buffer_load_dwordx4 v229, s[16:19], s54 offen lds
	s_mov_b32 m0, s41
	s_nop 0
	buffer_load_dwordx4 v199, s[12:15], s21 offen lds
	s_mov_b32 m0, s33
	s_nop 0
	buffer_load_dwordx4 v228, s[12:15], s21 offen lds
	s_waitcnt vmcnt(8)
	s_setprio 1
	s_barrier
	s_waitcnt lgkmcnt(0)
	v_mfma_f32_16x16x32_bf16 v[62:65], v[130:133], v[162:165], v[62:65]
	v_mfma_f32_16x16x32_bf16 v[58:61], v[138:141], v[162:165], v[58:61]
	v_mfma_f32_16x16x32_bf16 v[54:57], v[130:133], v[170:173], v[54:57]
	v_mfma_f32_16x16x32_bf16 v[50:53], v[138:141], v[170:173], v[50:53]
	v_mfma_f32_16x16x32_bf16 v[46:49], v[130:133], v[178:181], v[46:49]
	v_mfma_f32_16x16x32_bf16 v[42:45], v[138:141], v[178:181], v[42:45]
	v_mfma_f32_16x16x32_bf16 v[38:41], v[130:133], v[186:189], v[38:41]
	v_mfma_f32_16x16x32_bf16 v[34:37], v[138:141], v[186:189], v[34:37]
	v_mfma_f32_16x16x32_bf16 v[62:65], v[134:137], v[166:169], v[62:65]
	v_mfma_f32_16x16x32_bf16 v[58:61], v[142:145], v[166:169], v[58:61]
	v_mfma_f32_16x16x32_bf16 v[54:57], v[134:137], v[174:177], v[54:57]
	v_mfma_f32_16x16x32_bf16 v[50:53], v[142:145], v[174:177], v[50:53]
	v_mfma_f32_16x16x32_bf16 v[46:49], v[134:137], v[182:185], v[46:49]
	v_mfma_f32_16x16x32_bf16 v[42:45], v[142:145], v[182:185], v[42:45]
	v_mfma_f32_16x16x32_bf16 v[38:41], v[134:137], v[190:193], v[38:41]
	v_mfma_f32_16x16x32_bf16 v[34:37], v[142:145], v[190:193], v[34:37]
	v_mfma_f32_16x16x32_bf16 v[30:33], v[146:149], v[162:165], v[30:33]
	v_mfma_f32_16x16x32_bf16 v[26:29], v[154:157], v[162:165], v[26:29]
	v_mfma_f32_16x16x32_bf16 v[22:25], v[146:149], v[170:173], v[22:25]
	v_mfma_f32_16x16x32_bf16 v[18:21], v[154:157], v[170:173], v[18:21]
	v_mfma_f32_16x16x32_bf16 v[14:17], v[146:149], v[178:181], v[14:17]
	v_mfma_f32_16x16x32_bf16 v[10:13], v[154:157], v[178:181], v[10:13]
	v_mfma_f32_16x16x32_bf16 v[6:9], v[146:149], v[186:189], v[6:9]
	v_mfma_f32_16x16x32_bf16 v[2:5], v[154:157], v[186:189], v[2:5]
	v_mfma_f32_16x16x32_bf16 v[30:33], v[150:153], v[166:169], v[30:33]
	v_mfma_f32_16x16x32_bf16 v[26:29], v[158:161], v[166:169], v[26:29]
	v_mfma_f32_16x16x32_bf16 v[22:25], v[150:153], v[174:177], v[22:25]
	v_mfma_f32_16x16x32_bf16 v[18:21], v[158:161], v[174:177], v[18:21]
	v_mfma_f32_16x16x32_bf16 v[14:17], v[150:153], v[182:185], v[14:17]
	v_mfma_f32_16x16x32_bf16 v[10:13], v[158:161], v[182:185], v[10:13]
	v_mfma_f32_16x16x32_bf16 v[6:9], v[150:153], v[190:193], v[6:9]
	v_mfma_f32_16x16x32_bf16 v[2:5], v[158:161], v[190:193], v[2:5]
	s_barrier
	s_setprio 0
	s_add_i32 s12, s20, 2
	s_cmp_gt_u32 s20, 5
	s_cbranch_scc1 .LBB0_1032
	s_mov_b32 s20, s12
	s_branch .LBB0_951

; template <class Epi, bool ALIGN_EPI, bool SP2, class Hook>
; __device__ __forceinline__ void gemm_phase(LAS unsigned char* lds, const Gemm g, const StaticOrder& S, const Epi& E, Acc& acc, const bool fresh, const Hook& H, const int wave_id) {
;     ...
;         for (int t = t0; t < nt; t += 2) {
;             const bool last = (t == nt - 2);
;             const Src a1 = cA + (size_t)(t + 1) * kstep;
;             const Src a2 = last ? nA : cA + (size_t)(t + 2) * kstep, b2 = last ? nB : cB + (size_t)(t + 2) * kstep;
;             const Src a3 = a2 + kstep, b3 = b2 + kstep;
;             if (last && has_next) H(nxt);
.LBB0_1235:
	v_add_u32_e32 v142, 0x10000, v161
	v_add_u32_e32 v163, 0x14000, v161
	ds_read_b128 v[130:133], v142
	ds_read_b128 v[134:137], v142 offset:1024
	ds_read_b128 v[138:141], v142 offset:2048
	ds_read_b128 v[142:145], v142 offset:3072
	ds_read_b128 v[146:149], v163
	ds_read_b128 v[150:153], v163 offset:1024
	ds_read_b128 v[154:157], v163 offset:2048
	ds_read_b128 v[164:167], v163 offset:3072
	s_add_i32 s16, s2, 0xfffc0080
	s_cmp_eq_u32 s59, 12
	s_cselect_b32 s62, s55, s16
	s_cselect_b32 s17, s31, s9
	s_cselect_b32 s16, s30, s8
	s_cselect_b32 s19, s35, s51
	s_cselect_b32 s18, s34, s50
	s_cselect_b32 s60, s56, s3
	s_cselect_b32 s20, s26, s12
	s_cselect_b32 s21, s27, s13
	s_cselect_b32 s22, s28, s14
	s_cselect_b32 s23, s29, s15
	s_or_b32 s61, s62, 0x80
	s_mov_b32 m0, s45
	ds_read_b128 v[168:171], v162
	ds_read_b128 v[172:175], v162 offset:1024
	ds_read_b128 v[176:179], v162 offset:2048
	ds_read_b128 v[180:183], v162 offset:3072
	ds_read_b128 v[184:187], v162 offset:4096
	ds_read_b128 v[188:191], v162 offset:5120
	ds_read_b128 v[192:195], v162 offset:6144
	ds_read_b128 v[200:203], v162 offset:7168
	buffer_load_dwordx4 v0, s[12:15], s2 offen lds
	s_mov_b32 m0, s46
	s_nop 0
	buffer_load_dwordx4 v159, s[12:15], s2 offen lds
	s_waitcnt vmcnt(8)
	s_setprio 1
	s_barrier
	s_waitcnt lgkmcnt(0)
	v_mfma_f32_16x16x32_bf16 v[126:129], v[130:133], v[168:171], v[126:129]
	v_mfma_f32_16x16x32_bf16 v[122:125], v[138:141], v[168:171], v[122:125]
	v_mfma_f32_16x16x32_bf16 v[110:113], v[130:133], v[176:179], v[110:113]
	v_mfma_f32_16x16x32_bf16 v[106:109], v[138:141], v[176:179], v[106:109]
	v_mfma_f32_16x16x32_bf16 v[94:97], v[130:133], v[184:187], v[94:97]
	v_mfma_f32_16x16x32_bf16 v[90:93], v[138:141], v[184:187], v[90:93]
	v_mfma_f32_16x16x32_bf16 v[78:81], v[130:133], v[192:195], v[78:81]
	v_mfma_f32_16x16x32_bf16 v[74:77], v[138:141], v[192:195], v[74:77]
	v_mfma_f32_16x16x32_bf16 v[126:129], v[134:137], v[172:175], v[126:129]
	v_mfma_f32_16x16x32_bf16 v[122:125], v[142:145], v[172:175], v[122:125]
	v_mfma_f32_16x16x32_bf16 v[110:113], v[134:137], v[180:183], v[110:113]
	v_mfma_f32_16x16x32_bf16 v[106:109], v[142:145], v[180:183], v[106:109]
	v_mfma_f32_16x16x32_bf16 v[94:97], v[134:137], v[188:191], v[94:97]
	v_mfma_f32_16x16x32_bf16 v[90:93], v[142:145], v[188:191], v[90:93]
	v_mfma_f32_16x16x32_bf16 v[78:81], v[134:137], v[200:203], v[78:81]
	v_mfma_f32_16x16x32_bf16 v[74:77], v[142:145], v[200:203], v[74:77]
	v_mfma_f32_16x16x32_bf16 v[118:121], v[146:149], v[168:171], v[118:121]
	v_mfma_f32_16x16x32_bf16 v[114:117], v[154:157], v[168:171], v[114:117]
	v_mfma_f32_16x16x32_bf16 v[102:105], v[146:149], v[176:179], v[102:105]
	v_mfma_f32_16x16x32_bf16 v[98:101], v[154:157], v[176:179], v[98:101]
	v_mfma_f32_16x16x32_bf16 v[86:89], v[146:149], v[184:187], v[86:89]
	v_mfma_f32_16x16x32_bf16 v[82:85], v[154:157], v[184:187], v[82:85]
	v_mfma_f32_16x16x32_bf16 v[70:73], v[146:149], v[192:195], v[70:73]
	v_mfma_f32_16x16x32_bf16 v[66:69], v[154:157], v[192:195], v[66:69]
	v_mfma_f32_16x16x32_bf16 v[118:121], v[150:153], v[172:175], v[118:121]
	v_mfma_f32_16x16x32_bf16 v[114:117], v[164:167], v[172:175], v[114:117]
	v_mfma_f32_16x16x32_bf16 v[102:105], v[150:153], v[180:183], v[102:105]
	v_mfma_f32_16x16x32_bf16 v[98:101], v[164:167], v[180:183], v[98:101]
	v_mfma_f32_16x16x32_bf16 v[86:89], v[150:153], v[188:191], v[86:89]
	v_mfma_f32_16x16x32_bf16 v[82:85], v[164:167], v[188:191], v[82:85]
	v_mfma_f32_16x16x32_bf16 v[70:73], v[150:153], v[200:203], v[70:73]
	v_mfma_f32_16x16x32_bf16 v[66:69], v[164:167], v[200:203], v[66:69]
	s_barrier
	s_setprio 0
	s_mov_b32 m0, s92
	ds_read_b128 v[168:171], v162 offset:16384
	ds_read_b128 v[172:175], v162 offset:17408
	ds_read_b128 v[176:179], v162 offset:18432
	ds_read_b128 v[180:183], v162 offset:19456
	ds_read_b128 v[184:187], v162 offset:20480
	ds_read_b128 v[188:191], v162 offset:21504
	ds_read_b128 v[192:195], v162 offset:22528
	ds_read_b128 v[200:203], v162 offset:23552
	buffer_load_dwordx4 v158, s[16:19], s60 offen lds
	s_mov_b32 m0, s93
	s_add_i32 s63, s60, 0x40000
	buffer_load_dwordx4 v160, s[16:19], s60 offen lds
	s_mov_b32 m0, s94
	s_nop 0
	buffer_load_dwordx4 v158, s[16:19], s63 offen lds
	s_mov_b32 m0, s95
	s_nop 0
	buffer_load_dwordx4 v160, s[16:19], s63 offen lds
	s_mov_b32 m0, s44
	s_nop 0
	buffer_load_dwordx4 v0, s[20:23], s62 offen lds
	s_mov_b32 m0, s36
	s_nop 0
	buffer_load_dwordx4 v159, s[20:23], s62 offen lds
	s_waitcnt vmcnt(8)
	s_setprio 1
	s_barrier
	s_waitcnt lgkmcnt(0)
	v_mfma_f32_16x16x32_bf16 v[62:65], v[130:133], v[168:171], v[62:65]
	v_mfma_f32_16x16x32_bf16 v[58:61], v[138:141], v[168:171], v[58:61]
	v_mfma_f32_16x16x32_bf16 v[46:49], v[130:133], v[176:179], v[46:49]
	v_mfma_f32_16x16x32_bf16 v[42:45], v[138:141], v[176:179], v[42:45]
	v_mfma_f32_16x16x32_bf16 v[30:33], v[130:133], v[184:187], v[30:33]
	v_mfma_f32_16x16x32_bf16 v[26:29], v[138:141], v[184:187], v[26:29]
	v_mfma_f32_16x16x32_bf16 v[14:17], v[130:133], v[192:195], v[14:17]
	v_mfma_f32_16x16x32_bf16 v[10:13], v[138:141], v[192:195], v[10:13]
	v_mfma_f32_16x16x32_bf16 v[62:65], v[134:137], v[172:175], v[62:65]
	v_mfma_f32_16x16x32_bf16 v[58:61], v[142:145], v[172:175], v[58:61]
	v_mfma_f32_16x16x32_bf16 v[46:49], v[134:137], v[180:183], v[46:49]
	v_mfma_f32_16x16x32_bf16 v[42:45], v[142:145], v[180:183], v[42:45]
	v_mfma_f32_16x16x32_bf16 v[30:33], v[134:137], v[188:191], v[30:33]
	v_mfma_f32_16x16x32_bf16 v[26:29], v[142:145], v[188:191], v[26:29]
	v_mfma_f32_16x16x32_bf16 v[14:17], v[134:137], v[200:203], v[14:17]
	v_mfma_f32_16x16x32_bf16 v[10:13], v[142:145], v[200:203], v[10:13]
	v_mfma_f32_16x16x32_bf16 v[54:57], v[146:149], v[168:171], v[54:57]
	v_mfma_f32_16x16x32_bf16 v[50:53], v[154:157], v[168:171], v[50:53]
	v_mfma_f32_16x16x32_bf16 v[38:41], v[146:149], v[176:179], v[38:41]
	v_mfma_f32_16x16x32_bf16 v[34:37], v[154:157], v[176:179], v[34:37]
	v_mfma_f32_16x16x32_bf16 v[22:25], v[146:149], v[184:187], v[22:25]
	v_mfma_f32_16x16x32_bf16 v[18:21], v[154:157], v[184:187], v[18:21]
	v_mfma_f32_16x16x32_bf16 v[6:9], v[146:149], v[192:195], v[6:9]
	v_mfma_f32_16x16x32_bf16 v[2:5], v[154:157], v[192:195], v[2:5]
	v_mfma_f32_16x16x32_bf16 v[54:57], v[150:153], v[172:175], v[54:57]
	v_mfma_f32_16x16x32_bf16 v[50:53], v[164:167], v[172:175], v[50:53]
	v_mfma_f32_16x16x32_bf16 v[38:41], v[150:153], v[180:183], v[38:41]
	v_mfma_f32_16x16x32_bf16 v[34:37], v[164:167], v[180:183], v[34:37]
	v_mfma_f32_16x16x32_bf16 v[22:25], v[150:153], v[188:191], v[22:25]
	v_mfma_f32_16x16x32_bf16 v[18:21], v[164:167], v[188:191], v[18:21]
	v_mfma_f32_16x16x32_bf16 v[6:9], v[150:153], v[200:203], v[6:9]
	v_mfma_f32_16x16x32_bf16 v[2:5], v[164:167], v[200:203], v[2:5]
	s_barrier
; #define PG8_WAIT_V(n) asm volatile("s_waitcnt vmcnt(" #n ")" ::: "memory")
; template <class Epi, bool ALIGN_EPI, bool SP2, class Hook>
; __device__ __forceinline__ void gemm_phase(LAS unsigned char* lds, const Gemm g, const StaticOrder& S, const Epi& E, Acc& acc, const bool fresh, const Hook& H, const int wave_id) {
;     ...
;         for (int t = t0; t < nt; t += 2) {
;             const bool last = (t == nt - 2);
;             const Src a1 = cA + (size_t)(t + 1) * kstep;
;             const Src a2 = last ? nA : cA + (size_t)(t + 2) * kstep, b2 = last ? nB : cB + (size_t)(t + 2) * kstep;
;             const Src a3 = a2 + kstep, b3 = b2 + kstep;
;             if (last && has_next) H(nxt);
;             if constexpr (SP2) {
;             PG8_TRIP_SP2(PG8_WAIT_V(8));
	s_setprio 0
	v_add_u32_e32 v142, 0x18000, v161
	v_add_u32_e32 v163, 0x1c000, v161
	ds_read_b128 v[130:133], v142
	ds_read_b128 v[134:137], v142 offset:1024
	ds_read_b128 v[138:141], v142 offset:2048
	ds_read_b128 v[142:145], v142 offset:3072
	ds_read_b128 v[146:149], v163
	ds_read_b128 v[150:153], v163 offset:1024
	ds_read_b128 v[154:157], v163 offset:2048
	ds_read_b128 v[164:167], v163 offset:3072
	s_add_i32 s62, s62, 0x40000
	s_mov_b32 m0, s37
	ds_read_b128 v[168:171], v162 offset:32768
	ds_read_b128 v[172:175], v162 offset:33792
	ds_read_b128 v[176:179], v162 offset:34816
	ds_read_b128 v[180:183], v162 offset:35840
	ds_read_b128 v[184:187], v162 offset:36864
	ds_read_b128 v[188:191], v162 offset:37888
	ds_read_b128 v[192:195], v162 offset:38912
	ds_read_b128 v[200:203], v162 offset:39936
	buffer_load_dwordx4 v0, s[20:23], s62 offen lds
	s_mov_b32 m0, s38
	s_nop 0
	buffer_load_dwordx4 v159, s[20:23], s62 offen lds
	s_waitcnt vmcnt(8)
	s_setprio 1
	s_barrier
	s_waitcnt lgkmcnt(0)
	v_mfma_f32_16x16x32_bf16 v[126:129], v[130:133], v[168:171], v[126:129]
	v_mfma_f32_16x16x32_bf16 v[122:125], v[138:141], v[168:171], v[122:125]
	v_mfma_f32_16x16x32_bf16 v[110:113], v[130:133], v[176:179], v[110:113]
	v_mfma_f32_16x16x32_bf16 v[106:109], v[138:141], v[176:179], v[106:109]
	v_mfma_f32_16x16x32_bf16 v[94:97], v[130:133], v[184:187], v[94:97]
	v_mfma_f32_16x16x32_bf16 v[90:93], v[138:141], v[184:187], v[90:93]
	v_mfma_f32_16x16x32_bf16 v[78:81], v[130:133], v[192:195], v[78:81]
	v_mfma_f32_16x16x32_bf16 v[74:77], v[138:141], v[192:195], v[74:77]
	v_mfma_f32_16x16x32_bf16 v[126:129], v[134:137], v[172:175], v[126:129]
	v_mfma_f32_16x16x32_bf16 v[122:125], v[142:145], v[172:175], v[122:125]
	v_mfma_f32_16x16x32_bf16 v[110:113], v[134:137], v[180:183], v[110:113]
	v_mfma_f32_16x16x32_bf16 v[106:109], v[142:145], v[180:183], v[106:109]
	v_mfma_f32_16x16x32_bf16 v[94:97], v[134:137], v[188:191], v[94:97]
	v_mfma_f32_16x16x32_bf16 v[90:93], v[142:145], v[188:191], v[90:93]
	v_mfma_f32_16x16x32_bf16 v[78:81], v[134:137], v[200:203], v[78:81]
	v_mfma_f32_16x16x32_bf16 v[74:77], v[142:145], v[200:203], v[74:77]
	v_mfma_f32_16x16x32_bf16 v[118:121], v[146:149], v[168:171], v[118:121]
	v_mfma_f32_16x16x32_bf16 v[114:117], v[154:157], v[168:171], v[114:117]
	v_mfma_f32_16x16x32_bf16 v[102:105], v[146:149], v[176:179], v[102:105]
	v_mfma_f32_16x16x32_bf16 v[98:101], v[154:157], v[176:179], v[98:101]
	v_mfma_f32_16x16x32_bf16 v[86:89], v[146:149], v[184:187], v[86:89]
	v_mfma_f32_16x16x32_bf16 v[82:85], v[154:157], v[184:187], v[82:85]
	v_mfma_f32_16x16x32_bf16 v[70:73], v[146:149], v[192:195], v[70:73]
	v_mfma_f32_16x16x32_bf16 v[66:69], v[154:157], v[192:195], v[66:69]
	v_mfma_f32_16x16x32_bf16 v[118:121], v[150:153], v[172:175], v[118:121]
	v_mfma_f32_16x16x32_bf16 v[114:117], v[164:167], v[172:175], v[114:117]
	v_mfma_f32_16x16x32_bf16 v[102:105], v[150:153], v[180:183], v[102:105]
	v_mfma_f32_16x16x32_bf16 v[98:101], v[164:167], v[180:183], v[98:101]
	v_mfma_f32_16x16x32_bf16 v[86:89], v[150:153], v[188:191], v[86:89]
	v_mfma_f32_16x16x32_bf16 v[82:85], v[164:167], v[188:191], v[82:85]
	v_mfma_f32_16x16x32_bf16 v[70:73], v[150:153], v[200:203], v[70:73]
	v_mfma_f32_16x16x32_bf16 v[66:69], v[164:167], v[200:203], v[66:69]
	s_barrier
	s_setprio 0
	s_mov_b32 m0, s39
	s_or_b32 s62, s60, 0x80
	ds_read_b128 v[168:171], v162 offset:49152
	ds_read_b128 v[172:175], v162 offset:50176
	ds_read_b128 v[176:179], v162 offset:51200
	ds_read_b128 v[180:183], v162 offset:52224
	ds_read_b128 v[184:187], v162 offset:53248
	ds_read_b128 v[188:191], v162 offset:54272
	ds_read_b128 v[192:195], v162 offset:55296
	ds_read_b128 v[200:203], v162 offset:56320
	buffer_load_dwordx4 v158, s[16:19], s62 offen lds
	s_mov_b32 m0, s40
	s_add_i32 s60, s60, 0x40080
	buffer_load_dwordx4 v160, s[16:19], s62 offen lds
	s_mov_b32 m0, s43
	s_nop 0
	buffer_load_dwordx4 v158, s[16:19], s60 offen lds
	s_mov_b32 m0, s42
	s_nop 0
	buffer_load_dwordx4 v160, s[16:19], s60 offen lds
	s_mov_b32 m0, s41
	s_nop 0
	buffer_load_dwordx4 v0, s[20:23], s61 offen lds
	s_mov_b32 m0, s33
	s_nop 0
	buffer_load_dwordx4 v159, s[20:23], s61 offen lds
	s_waitcnt vmcnt(8)
	s_setprio 1
	s_barrier
	s_waitcnt lgkmcnt(0)
	v_mfma_f32_16x16x32_bf16 v[62:65], v[130:133], v[168:171], v[62:65]
	v_mfma_f32_16x16x32_bf16 v[58:61], v[138:141], v[168:171], v[58:61]
	v_mfma_f32_16x16x32_bf16 v[46:49], v[130:133], v[176:179], v[46:49]
	v_mfma_f32_16x16x32_bf16 v[42:45], v[138:141], v[176:179], v[42:45]
	v_mfma_f32_16x16x32_bf16 v[30:33], v[130:133], v[184:187], v[30:33]
	v_mfma_f32_16x16x32_bf16 v[26:29], v[138:141], v[184:187], v[26:29]
	v_mfma_f32_16x16x32_bf16 v[14:17], v[130:133], v[192:195], v[14:17]
	v_mfma_f32_16x16x32_bf16 v[10:13], v[138:141], v[192:195], v[10:13]
	v_mfma_f32_16x16x32_bf16 v[62:65], v[134:137], v[172:175], v[62:65]
	v_mfma_f32_16x16x32_bf16 v[58:61], v[142:145], v[172:175], v[58:61]
	v_mfma_f32_16x16x32_bf16 v[46:49], v[134:137], v[180:183], v[46:49]
	v_mfma_f32_16x16x32_bf16 v[42:45], v[142:145], v[180:183], v[42:45]
	v_mfma_f32_16x16x32_bf16 v[30:33], v[134:137], v[188:191], v[30:33]
	v_mfma_f32_16x16x32_bf16 v[26:29], v[142:145], v[188:191], v[26:29]
	v_mfma_f32_16x16x32_bf16 v[14:17], v[134:137], v[200:203], v[14:17]
	v_mfma_f32_16x16x32_bf16 v[10:13], v[142:145], v[200:203], v[10:13]
	v_mfma_f32_16x16x32_bf16 v[54:57], v[146:149], v[168:171], v[54:57]
	v_mfma_f32_16x16x32_bf16 v[50:53], v[154:157], v[168:171], v[50:53]
	v_mfma_f32_16x16x32_bf16 v[38:41], v[146:149], v[176:179], v[38:41]
	v_mfma_f32_16x16x32_bf16 v[34:37], v[154:157], v[176:179], v[34:37]
	v_mfma_f32_16x16x32_bf16 v[22:25], v[146:149], v[184:187], v[22:25]
	v_mfma_f32_16x16x32_bf16 v[18:21], v[154:157], v[184:187], v[18:21]
	v_mfma_f32_16x16x32_bf16 v[6:9], v[146:149], v[192:195], v[6:9]
	v_mfma_f32_16x16x32_bf16 v[2:5], v[154:157], v[192:195], v[2:5]
	v_mfma_f32_16x16x32_bf16 v[54:57], v[150:153], v[172:175], v[54:57]
	v_mfma_f32_16x16x32_bf16 v[50:53], v[164:167], v[172:175], v[50:53]
	v_mfma_f32_16x16x32_bf16 v[38:41], v[150:153], v[180:183], v[38:41]
	v_mfma_f32_16x16x32_bf16 v[34:37], v[164:167], v[180:183], v[34:37]
	v_mfma_f32_16x16x32_bf16 v[22:25], v[150:153], v[188:191], v[22:25]
	v_mfma_f32_16x16x32_bf16 v[18:21], v[164:167], v[188:191], v[18:21]
	v_mfma_f32_16x16x32_bf16 v[6:9], v[150:153], v[200:203], v[6:9]
	v_mfma_f32_16x16x32_bf16 v[2:5], v[164:167], v[200:203], v[2:5]
	s_barrier
	s_setprio 0
	s_add_i32 s59, s59, 2
	s_addk_i32 s2, 0x100
	s_addk_i32 s3, 0x100
	s_cmp_gt_u32 s59, 13
	s_cbranch_scc0 .LBB0_1235
	v_readlane_b32 s2, v251, 45
	v_readlane_b32 s3, v251, 46
	s_and_b64 vcc, exec, s[2:3]
	s_cbranch_vccz .LBB0_1238
	s_barrier

; #define PG8_WAIT_V(n) asm volatile("s_waitcnt vmcnt(" #n ")" ::: "memory")
; template <class Epi, bool ALIGN_EPI, bool SP2, class Hook>
; __device__ __forceinline__ void gemm_phase(LAS unsigned char* lds, const Gemm g, const StaticOrder& S, const Epi& E, Acc& acc, const bool fresh, const Hook& H, const int wave_id) {
;     ...
;         if constexpr (SP2 && Epi::NSTORE > 0) {
;             const Src a1 = cA + kstep, a2 = cA + 2 * kstep, b2 = cB + 2 * kstep, a3 = a2 + kstep, b3 = b2 + kstep;
;             if constexpr (Epi::NSTORE == 16) PG8_TRIP_SP2(PG8_WAIT_V(24)); else PG8_TRIP_SP2(PG8_WAIT_V(16));
;             t0 = 2;
;         }
.LBB0_1452:
	ds_read_b128 v[2:5], v138
	ds_read_b128 v[6:9], v138 offset:1024
	ds_read_b128 v[10:13], v138 offset:2048
	ds_read_b128 v[14:17], v138 offset:3072
	ds_read_b128 v[18:21], v139
	ds_read_b128 v[22:25], v139 offset:1024
	ds_read_b128 v[26:29], v139 offset:2048
	ds_read_b128 v[30:33], v139 offset:3072
	s_or_b32 s3, s50, 0x100
	s_or_b32 s2, s50, 0x180
	s_or_b32 s12, s51, 0x100
	s_or_b32 s13, s50, 0x40080
	s_mov_b32 m0, s45
	ds_read_b128 v[34:37], v137
	ds_read_b128 v[38:41], v137 offset:1024
	ds_read_b128 v[42:45], v137 offset:2048
	ds_read_b128 v[46:49], v137 offset:3072
	ds_read_b128 v[50:53], v137 offset:4096
	ds_read_b128 v[54:57], v137 offset:5120
	ds_read_b128 v[58:61], v137 offset:6144
	ds_read_b128 v[62:65], v137 offset:7168
	buffer_load_dwordx4 v132, s[4:7], s13 offen lds
	s_mov_b32 m0, s46
	s_nop 0
	buffer_load_dwordx4 v134, s[4:7], s13 offen lds
	s_waitcnt vmcnt(16)
	s_setprio 1
	s_barrier
	s_waitcnt lgkmcnt(0)
	v_mfma_f32_16x16x32_bf16 v[90:93], v[2:5], v[58:61], 0
	v_mfma_f32_16x16x32_bf16 v[66:69], v[2:5], v[34:37], 0
	v_mfma_f32_16x16x32_bf16 v[70:73], v[10:13], v[34:37], 0
	v_mfma_f32_16x16x32_bf16 v[74:77], v[2:5], v[42:45], 0
	v_mfma_f32_16x16x32_bf16 v[78:81], v[10:13], v[42:45], 0
	v_mfma_f32_16x16x32_bf16 v[82:85], v[2:5], v[50:53], 0
	v_mfma_f32_16x16x32_bf16 v[86:89], v[10:13], v[50:53], 0
	v_mfma_f32_16x16x32_bf16 v[96:99], v[6:9], v[62:65], v[90:93]
	v_mfma_f32_16x16x32_bf16 v[90:93], v[10:13], v[58:61], 0
	v_mfma_f32_16x16x32_bf16 v[66:69], v[6:9], v[38:41], v[66:69]
	v_mfma_f32_16x16x32_bf16 v[70:73], v[14:17], v[38:41], v[70:73]
	v_mfma_f32_16x16x32_bf16 v[74:77], v[6:9], v[46:49], v[74:77]
	v_mfma_f32_16x16x32_bf16 v[78:81], v[14:17], v[46:49], v[78:81]
	v_mfma_f32_16x16x32_bf16 v[82:85], v[6:9], v[54:57], v[82:85]
	v_mfma_f32_16x16x32_bf16 v[86:89], v[14:17], v[54:57], v[86:89]
	v_mfma_f32_16x16x32_bf16 v[104:107], v[14:17], v[62:65], v[90:93]
	v_mfma_f32_16x16x32_bf16 v[90:93], v[18:21], v[34:37], 0
	v_mfma_f32_16x16x32_bf16 v[34:37], v[26:29], v[34:37], 0
	v_mfma_f32_16x16x32_bf16 v[112:115], v[22:25], v[38:41], v[90:93]
	v_mfma_f32_16x16x32_bf16 v[34:37], v[30:33], v[38:41], v[34:37]
	v_mfma_f32_16x16x32_bf16 v[38:41], v[18:21], v[42:45], 0
	v_mfma_f32_16x16x32_bf16 v[42:45], v[26:29], v[42:45], 0
	v_mfma_f32_16x16x32_bf16 v[38:41], v[22:25], v[46:49], v[38:41]
	v_mfma_f32_16x16x32_bf16 v[42:45], v[30:33], v[46:49], v[42:45]
	v_mfma_f32_16x16x32_bf16 v[46:49], v[18:21], v[50:53], 0
	v_mfma_f32_16x16x32_bf16 v[50:53], v[26:29], v[50:53], 0
	v_mfma_f32_16x16x32_bf16 v[46:49], v[22:25], v[54:57], v[46:49]
	v_mfma_f32_16x16x32_bf16 v[50:53], v[30:33], v[54:57], v[50:53]
	v_mfma_f32_16x16x32_bf16 v[54:57], v[18:21], v[58:61], 0
	v_mfma_f32_16x16x32_bf16 v[58:61], v[26:29], v[58:61], 0
	v_mfma_f32_16x16x32_bf16 v[54:57], v[22:25], v[62:65], v[54:57]
	v_mfma_f32_16x16x32_bf16 v[58:61], v[30:33], v[62:65], v[58:61]
	s_barrier
	s_setprio 0
	s_mov_b32 m0, s92
	ds_read_b128 v[62:65], v137 offset:16384
	ds_read_b128 v[90:93], v137 offset:17408
	ds_read_b128 v[100:103], v137 offset:18432
	ds_read_b128 v[108:111], v137 offset:19456
	ds_read_b128 v[116:119], v137 offset:20480
	ds_read_b128 v[120:123], v137 offset:21504
	ds_read_b128 v[124:127], v137 offset:22528
	ds_read_b128 v[128:131], v137 offset:23552
	buffer_load_dwordx4 v133, s[8:11], s12 offen lds
	s_mov_b32 m0, s93
	s_nop 0
	buffer_load_dwordx4 v135, s[8:11], s12 offen lds
	s_or_b32 s12, s51, 0x40100
	s_mov_b32 m0, s94
	s_nop 0
	buffer_load_dwordx4 v133, s[8:11], s12 offen lds
	s_mov_b32 m0, s95
	s_nop 0
	buffer_load_dwordx4 v135, s[8:11], s12 offen lds
	s_mov_b32 m0, s44
	s_nop 0
	buffer_load_dwordx4 v132, s[4:7], s3 offen lds
	s_mov_b32 m0, s36
	s_nop 0
	buffer_load_dwordx4 v134, s[4:7], s3 offen lds
	s_waitcnt vmcnt(16)
	s_setprio 1
	s_barrier
	s_waitcnt lgkmcnt(0)
	v_mfma_f32_16x16x32_bf16 v[142:145], v[2:5], v[62:65], 0
	v_mfma_f32_16x16x32_bf16 v[150:153], v[2:5], v[100:103], 0
	v_mfma_f32_16x16x32_bf16 v[158:161], v[2:5], v[116:119], 0
	v_mfma_f32_16x16x32_bf16 v[2:5], v[2:5], v[124:127], 0
	v_mfma_f32_16x16x32_bf16 v[142:145], v[6:9], v[90:93], v[142:145]
	v_mfma_f32_16x16x32_bf16 v[150:153], v[6:9], v[108:111], v[150:153]
	v_mfma_f32_16x16x32_bf16 v[158:161], v[6:9], v[120:123], v[158:161]
	v_mfma_f32_16x16x32_bf16 v[2:5], v[6:9], v[128:131], v[2:5]
	v_mfma_f32_16x16x32_bf16 v[6:9], v[10:13], v[124:127], 0
	v_mfma_f32_16x16x32_bf16 v[146:149], v[10:13], v[62:65], 0
	v_mfma_f32_16x16x32_bf16 v[154:157], v[10:13], v[100:103], 0
	v_mfma_f32_16x16x32_bf16 v[162:165], v[10:13], v[116:119], 0
	v_mfma_f32_16x16x32_bf16 v[6:9], v[14:17], v[128:131], v[6:9]
	v_mfma_f32_16x16x32_bf16 v[146:149], v[14:17], v[90:93], v[146:149]
	v_mfma_f32_16x16x32_bf16 v[154:157], v[14:17], v[108:111], v[154:157]
	v_mfma_f32_16x16x32_bf16 v[162:165], v[14:17], v[120:123], v[162:165]
	v_mfma_f32_16x16x32_bf16 v[10:13], v[18:21], v[62:65], 0
	v_mfma_f32_16x16x32_bf16 v[166:169], v[22:25], v[90:93], v[10:13]
	v_mfma_f32_16x16x32_bf16 v[10:13], v[26:29], v[62:65], 0
	v_mfma_f32_16x16x32_bf16 v[170:173], v[30:33], v[90:93], v[10:13]
	v_mfma_f32_16x16x32_bf16 v[10:13], v[18:21], v[100:103], 0
	v_mfma_f32_16x16x32_bf16 v[174:177], v[22:25], v[108:111], v[10:13]
	v_mfma_f32_16x16x32_bf16 v[10:13], v[26:29], v[100:103], 0
	v_mfma_f32_16x16x32_bf16 v[178:181], v[30:33], v[108:111], v[10:13]
	v_mfma_f32_16x16x32_bf16 v[10:13], v[18:21], v[116:119], 0
	v_mfma_f32_16x16x32_bf16 v[182:185], v[22:25], v[120:123], v[10:13]
	v_mfma_f32_16x16x32_bf16 v[10:13], v[26:29], v[116:119], 0
	v_mfma_f32_16x16x32_bf16 v[186:189], v[30:33], v[120:123], v[10:13]
	v_mfma_f32_16x16x32_bf16 v[10:13], v[18:21], v[124:127], 0
	v_mfma_f32_16x16x32_bf16 v[16:19], v[22:25], v[128:131], v[10:13]
	v_mfma_f32_16x16x32_bf16 v[10:13], v[26:29], v[124:127], 0
	v_mfma_f32_16x16x32_bf16 v[190:193], v[30:33], v[128:131], v[10:13]
	s_barrier
; #define PG8_WAIT_V(n) asm volatile("s_waitcnt vmcnt(" #n ")" ::: "memory")
; template <class Epi, bool ALIGN_EPI, bool SP2, class Hook>
; __device__ __forceinline__ void gemm_phase(LAS unsigned char* lds, const Gemm g, const StaticOrder& S, const Epi& E, Acc& acc, const bool fresh, const Hook& H, const int wave_id) {
;     ...
;         if constexpr (SP2 && Epi::NSTORE > 0) {
;             const Src a1 = cA + kstep, a2 = cA + 2 * kstep, b2 = cB + 2 * kstep, a3 = a2 + kstep, b3 = b2 + kstep;
;             if constexpr (Epi::NSTORE == 16) PG8_TRIP_SP2(PG8_WAIT_V(24)); else PG8_TRIP_SP2(PG8_WAIT_V(16));
;             t0 = 2;
;         }
	s_setprio 0
	s_nop 4
	ds_read_b128 v[10:13], v140
	ds_read_b128 v[24:27], v140 offset:1024
	ds_read_b128 v[194:197], v140 offset:2048
	ds_read_b128 v[200:203], v140 offset:3072
	ds_read_b128 v[204:207], v141
	ds_read_b128 v[208:211], v141 offset:1024
	ds_read_b128 v[212:215], v141 offset:2048
	ds_read_b128 v[138:141], v141 offset:3072
	s_or_b32 s3, s50, 0x40100
	s_mov_b32 m0, s37
	ds_read_b128 v[20:23], v137 offset:32768
	ds_read_b128 v[28:31], v137 offset:33792
	ds_read_b128 v[216:219], v137 offset:34816
	ds_read_b128 v[220:223], v137 offset:35840
	ds_read_b128 v[228:231], v137 offset:36864
	ds_read_b128 v[232:235], v137 offset:37888
	ds_read_b128 v[236:239], v137 offset:38912
	ds_read_b128 v[240:243], v137 offset:39936
	buffer_load_dwordx4 v132, s[4:7], s3 offen lds
	s_mov_b32 m0, s38
	s_nop 0
	buffer_load_dwordx4 v134, s[4:7], s3 offen lds
	s_waitcnt vmcnt(8)
	s_setprio 1
	s_barrier
	s_waitcnt lgkmcnt(0)
	v_mfma_f32_16x16x32_bf16 v[62:65], v[10:13], v[20:23], v[66:69]
	v_mfma_f32_16x16x32_bf16 v[124:127], v[24:27], v[28:31], v[62:65]
	v_mfma_f32_16x16x32_bf16 v[62:65], v[194:197], v[20:23], v[70:73]
	v_mfma_f32_16x16x32_bf16 v[116:119], v[200:203], v[28:31], v[62:65]
	v_mfma_f32_16x16x32_bf16 v[62:65], v[10:13], v[216:219], v[74:77]
	v_mfma_f32_16x16x32_bf16 v[108:111], v[24:27], v[220:223], v[62:65]
	v_mfma_f32_16x16x32_bf16 v[62:65], v[194:197], v[216:219], v[78:81]
	v_mfma_f32_16x16x32_bf16 v[100:103], v[200:203], v[220:223], v[62:65]
	v_mfma_f32_16x16x32_bf16 v[62:65], v[10:13], v[228:231], v[82:85]
	v_mfma_f32_16x16x32_bf16 v[92:95], v[24:27], v[232:235], v[62:65]
	v_mfma_f32_16x16x32_bf16 v[62:65], v[194:197], v[228:231], v[86:89]
	v_mfma_f32_16x16x32_bf16 v[84:87], v[200:203], v[232:235], v[62:65]
	v_mfma_f32_16x16x32_bf16 v[62:65], v[10:13], v[236:239], v[96:99]
	v_mfma_f32_16x16x32_bf16 v[76:79], v[24:27], v[240:243], v[62:65]
	v_mfma_f32_16x16x32_bf16 v[62:65], v[194:197], v[236:239], v[104:107]
	v_mfma_f32_16x16x32_bf16 v[64:67], v[200:203], v[240:243], v[62:65]
	v_mfma_f32_16x16x32_bf16 v[68:71], v[204:207], v[20:23], v[112:115]
	v_mfma_f32_16x16x32_bf16 v[20:23], v[212:215], v[20:23], v[34:37]
	v_mfma_f32_16x16x32_bf16 v[120:123], v[138:141], v[28:31], v[20:23]
	v_mfma_f32_16x16x32_bf16 v[20:23], v[204:207], v[216:219], v[38:41]
	v_mfma_f32_16x16x32_bf16 v[112:115], v[208:211], v[220:223], v[20:23]
	v_mfma_f32_16x16x32_bf16 v[20:23], v[212:215], v[216:219], v[42:45]
	v_mfma_f32_16x16x32_bf16 v[104:107], v[138:141], v[220:223], v[20:23]
	v_mfma_f32_16x16x32_bf16 v[20:23], v[204:207], v[228:231], v[46:49]
	v_mfma_f32_16x16x32_bf16 v[96:99], v[208:211], v[232:235], v[20:23]
	v_mfma_f32_16x16x32_bf16 v[20:23], v[212:215], v[228:231], v[50:53]
	v_mfma_f32_16x16x32_bf16 v[88:91], v[138:141], v[232:235], v[20:23]
	v_mfma_f32_16x16x32_bf16 v[20:23], v[204:207], v[236:239], v[54:57]
	v_mfma_f32_16x16x32_bf16 v[80:83], v[208:211], v[240:243], v[20:23]
	v_mfma_f32_16x16x32_bf16 v[20:23], v[212:215], v[236:239], v[58:61]
	v_mfma_f32_16x16x32_bf16 v[128:131], v[208:211], v[28:31], v[68:71]
	v_mfma_f32_16x16x32_bf16 v[68:71], v[138:141], v[240:243], v[20:23]
	s_barrier
	s_setprio 0
	s_mov_b32 m0, s39
	s_or_b32 s3, s51, 0x180
	ds_read_b128 v[32:35], v137 offset:49152
	ds_read_b128 v[40:43], v137 offset:50176
	ds_read_b128 v[216:219], v137 offset:51200
	ds_read_b128 v[220:223], v137 offset:52224
	ds_read_b128 v[228:231], v137 offset:53248
	ds_read_b128 v[232:235], v137 offset:54272
	ds_read_b128 v[236:239], v137 offset:55296
	ds_read_b128 v[240:243], v137 offset:56320
	buffer_load_dwordx4 v133, s[8:11], s3 offen lds
	s_mov_b32 m0, s40
	s_nop 0
	buffer_load_dwordx4 v135, s[8:11], s3 offen lds
	s_or_b32 s3, s51, 0x40180
	s_mov_b32 m0, s43
	s_nop 0
	buffer_load_dwordx4 v133, s[8:11], s3 offen lds
	s_mov_b32 m0, s42
	s_nop 0
	buffer_load_dwordx4 v135, s[8:11], s3 offen lds
	s_mov_b32 m0, s41
	s_nop 0
	buffer_load_dwordx4 v132, s[4:7], s2 offen lds
	s_mov_b32 m0, s33
	s_nop 0
	buffer_load_dwordx4 v134, s[4:7], s2 offen lds
	s_waitcnt vmcnt(8)
	s_setprio 1
	s_barrier
	s_waitcnt lgkmcnt(0)
	v_mfma_f32_16x16x32_bf16 v[20:23], v[10:13], v[32:35], v[142:145]
	v_mfma_f32_16x16x32_bf16 v[60:63], v[24:27], v[40:43], v[20:23]
	v_mfma_f32_16x16x32_bf16 v[20:23], v[194:197], v[32:35], v[146:149]
	v_mfma_f32_16x16x32_bf16 v[52:55], v[200:203], v[40:43], v[20:23]
	v_mfma_f32_16x16x32_bf16 v[20:23], v[10:13], v[216:219], v[150:153]
	v_mfma_f32_16x16x32_bf16 v[44:47], v[24:27], v[220:223], v[20:23]
	v_mfma_f32_16x16x32_bf16 v[20:23], v[194:197], v[216:219], v[154:157]
	v_mfma_f32_16x16x32_bf16 v[36:39], v[200:203], v[220:223], v[20:23]
	v_mfma_f32_16x16x32_bf16 v[20:23], v[10:13], v[228:231], v[158:161]
	v_mfma_f32_16x16x32_bf16 v[2:5], v[10:13], v[236:239], v[2:5]
	v_mfma_f32_16x16x32_bf16 v[28:31], v[24:27], v[232:235], v[20:23]
	v_mfma_f32_16x16x32_bf16 v[20:23], v[194:197], v[228:231], v[162:165]
	v_mfma_f32_16x16x32_bf16 v[12:15], v[24:27], v[240:243], v[2:5]
	v_mfma_f32_16x16x32_bf16 v[2:5], v[194:197], v[236:239], v[6:9]
	v_mfma_f32_16x16x32_bf16 v[20:23], v[200:203], v[232:235], v[20:23]
	v_mfma_f32_16x16x32_bf16 v[4:7], v[200:203], v[240:243], v[2:5]
	v_mfma_f32_16x16x32_bf16 v[8:11], v[204:207], v[32:35], v[166:169]
	v_mfma_f32_16x16x32_bf16 v[72:75], v[208:211], v[40:43], v[8:11]
	v_mfma_f32_16x16x32_bf16 v[8:11], v[212:215], v[32:35], v[170:173]
	v_mfma_f32_16x16x32_bf16 v[56:59], v[138:141], v[40:43], v[8:11]
	v_mfma_f32_16x16x32_bf16 v[8:11], v[204:207], v[216:219], v[174:177]
	v_mfma_f32_16x16x32_bf16 v[48:51], v[208:211], v[220:223], v[8:11]
	v_mfma_f32_16x16x32_bf16 v[8:11], v[212:215], v[216:219], v[178:181]
	v_mfma_f32_16x16x32_bf16 v[40:43], v[138:141], v[220:223], v[8:11]
	v_mfma_f32_16x16x32_bf16 v[8:11], v[204:207], v[228:231], v[182:185]
	v_mfma_f32_16x16x32_bf16 v[32:35], v[208:211], v[232:235], v[8:11]
	v_mfma_f32_16x16x32_bf16 v[8:11], v[212:215], v[228:231], v[186:189]
	v_mfma_f32_16x16x32_bf16 v[24:27], v[138:141], v[232:235], v[8:11]
	v_mfma_f32_16x16x32_bf16 v[8:11], v[204:207], v[236:239], v[16:19]
	v_mfma_f32_16x16x32_bf16 v[16:19], v[208:211], v[240:243], v[8:11]
	v_mfma_f32_16x16x32_bf16 v[8:11], v[212:215], v[236:239], v[190:193]
	v_mfma_f32_16x16x32_bf16 v[8:11], v[138:141], v[240:243], v[8:11]
	s_barrier
	s_setprio 0
	s_mov_b64 s[2:3], 0
	v_mov_b64_e32 v[234:235], v[226:227]
	v_mov_b32_e32 v226, v0
	v_mov_b64_e32 v[236:237], v[198:199]
	v_mov_b32_e32 v198, v225

; template <class Epi, bool ALIGN_EPI, bool SP2, class Hook>
; __device__ __forceinline__ void gemm_phase(LAS unsigned char* lds, const Gemm g, const StaticOrder& S, const Epi& E, Acc& acc, const bool fresh, const Hook& H, const int wave_id) {
;     ...
;         for (int t = t0; t < nt; t += 2) {
;             const bool last = (t == nt - 2);
;             const Src a1 = cA + (size_t)(t + 1) * kstep;
;             const Src a2 = last ? nA : cA + (size_t)(t + 2) * kstep, b2 = last ? nB : cB + (size_t)(t + 2) * kstep;
;             const Src a3 = a2 + kstep, b3 = b2 + kstep;
;             if (last && has_next) H(nxt);
.LBB0_1461:
	v_add_u32_e32 v138, 0x10000, v136
	v_add_u32_e32 v139, 0x14000, v136
	ds_read_b128 v[140:143], v138
	ds_read_b128 v[144:147], v138 offset:1024
	ds_read_b128 v[148:151], v138 offset:2048
	ds_read_b128 v[152:155], v138 offset:3072
	ds_read_b128 v[156:159], v139
	ds_read_b128 v[160:163], v139 offset:1024
	ds_read_b128 v[164:167], v139 offset:2048
	ds_read_b128 v[168:171], v139 offset:3072
	s_add_i32 s16, s55, 0xfffc0080
	s_cmp_eq_u32 s54, 12
	s_cselect_b32 s59, s50, s16
	s_cselect_b32 s17, s9, s77
	s_cselect_b32 s16, s8, s76
	s_cselect_b32 s19, s11, s29
	s_cselect_b32 s18, s10, s28
	s_cselect_b32 s57, s51, s56
	s_cselect_b32 s20, s4, s12
	s_cselect_b32 s21, s5, s13
	s_cselect_b32 s22, s6, s14
	s_cselect_b32 s23, s7, s15
	s_or_b32 s58, s59, 0x80
	s_mov_b32 m0, s45
	ds_read_b128 v[172:175], v137
	ds_read_b128 v[176:179], v137 offset:1024
	ds_read_b128 v[180:183], v137 offset:2048
	ds_read_b128 v[184:187], v137 offset:3072
	ds_read_b128 v[188:191], v137 offset:4096
	ds_read_b128 v[192:195], v137 offset:5120
	ds_read_b128 v[200:203], v137 offset:6144
	ds_read_b128 v[204:207], v137 offset:7168
	buffer_load_dwordx4 v132, s[12:15], s55 offen lds
	s_mov_b32 m0, s46
	s_nop 0
	buffer_load_dwordx4 v134, s[12:15], s55 offen lds
	s_waitcnt vmcnt(8)
	s_setprio 1
	s_barrier
	s_waitcnt lgkmcnt(0)
	v_mfma_f32_16x16x32_bf16 v[124:127], v[140:143], v[172:175], v[124:127]
	v_mfma_f32_16x16x32_bf16 v[116:119], v[148:151], v[172:175], v[116:119]
	v_mfma_f32_16x16x32_bf16 v[108:111], v[140:143], v[180:183], v[108:111]
	v_mfma_f32_16x16x32_bf16 v[100:103], v[148:151], v[180:183], v[100:103]
	v_mfma_f32_16x16x32_bf16 v[92:95], v[140:143], v[188:191], v[92:95]
	v_mfma_f32_16x16x32_bf16 v[84:87], v[148:151], v[188:191], v[84:87]
	v_mfma_f32_16x16x32_bf16 v[76:79], v[140:143], v[200:203], v[76:79]
	v_mfma_f32_16x16x32_bf16 v[64:67], v[148:151], v[200:203], v[64:67]
	v_mfma_f32_16x16x32_bf16 v[124:127], v[144:147], v[176:179], v[124:127]
	v_mfma_f32_16x16x32_bf16 v[116:119], v[152:155], v[176:179], v[116:119]
	v_mfma_f32_16x16x32_bf16 v[108:111], v[144:147], v[184:187], v[108:111]
	v_mfma_f32_16x16x32_bf16 v[100:103], v[152:155], v[184:187], v[100:103]
	v_mfma_f32_16x16x32_bf16 v[92:95], v[144:147], v[192:195], v[92:95]
	v_mfma_f32_16x16x32_bf16 v[84:87], v[152:155], v[192:195], v[84:87]
	v_mfma_f32_16x16x32_bf16 v[76:79], v[144:147], v[204:207], v[76:79]
	v_mfma_f32_16x16x32_bf16 v[64:67], v[152:155], v[204:207], v[64:67]
	v_mfma_f32_16x16x32_bf16 v[128:131], v[156:159], v[172:175], v[128:131]
	v_mfma_f32_16x16x32_bf16 v[120:123], v[164:167], v[172:175], v[120:123]
	v_mfma_f32_16x16x32_bf16 v[112:115], v[156:159], v[180:183], v[112:115]
	v_mfma_f32_16x16x32_bf16 v[104:107], v[164:167], v[180:183], v[104:107]
	v_mfma_f32_16x16x32_bf16 v[96:99], v[156:159], v[188:191], v[96:99]
	v_mfma_f32_16x16x32_bf16 v[88:91], v[164:167], v[188:191], v[88:91]
	v_mfma_f32_16x16x32_bf16 v[80:83], v[156:159], v[200:203], v[80:83]
	v_mfma_f32_16x16x32_bf16 v[68:71], v[164:167], v[200:203], v[68:71]
	v_mfma_f32_16x16x32_bf16 v[128:131], v[160:163], v[176:179], v[128:131]
	v_mfma_f32_16x16x32_bf16 v[120:123], v[168:171], v[176:179], v[120:123]
	v_mfma_f32_16x16x32_bf16 v[112:115], v[160:163], v[184:187], v[112:115]
	v_mfma_f32_16x16x32_bf16 v[104:107], v[168:171], v[184:187], v[104:107]
	v_mfma_f32_16x16x32_bf16 v[96:99], v[160:163], v[192:195], v[96:99]
	v_mfma_f32_16x16x32_bf16 v[88:91], v[168:171], v[192:195], v[88:91]
	v_mfma_f32_16x16x32_bf16 v[80:83], v[160:163], v[204:207], v[80:83]
	v_mfma_f32_16x16x32_bf16 v[68:71], v[168:171], v[204:207], v[68:71]
	s_barrier
	s_setprio 0
	s_mov_b32 m0, s92
	ds_read_b128 v[172:175], v137 offset:16384
	ds_read_b128 v[176:179], v137 offset:17408
	ds_read_b128 v[180:183], v137 offset:18432
	ds_read_b128 v[184:187], v137 offset:19456
	ds_read_b128 v[188:191], v137 offset:20480
	ds_read_b128 v[192:195], v137 offset:21504
	ds_read_b128 v[200:203], v137 offset:22528
	ds_read_b128 v[204:207], v137 offset:23552
	buffer_load_dwordx4 v133, s[16:19], s57 offen lds
	s_mov_b32 m0, s93
	s_add_i32 s60, s57, 0x40000
	buffer_load_dwordx4 v135, s[16:19], s57 offen lds
	s_mov_b32 m0, s94
	s_nop 0
	buffer_load_dwordx4 v133, s[16:19], s60 offen lds
	s_mov_b32 m0, s95
	s_nop 0
	buffer_load_dwordx4 v135, s[16:19], s60 offen lds
	s_mov_b32 m0, s44
	s_nop 0
	buffer_load_dwordx4 v132, s[20:23], s59 offen lds
	s_mov_b32 m0, s36
	s_nop 0
	buffer_load_dwordx4 v134, s[20:23], s59 offen lds
	s_waitcnt vmcnt(8)
	s_setprio 1
	s_barrier
	s_waitcnt lgkmcnt(0)
	v_mfma_f32_16x16x32_bf16 v[60:63], v[140:143], v[172:175], v[60:63]
	v_mfma_f32_16x16x32_bf16 v[52:55], v[148:151], v[172:175], v[52:55]
	v_mfma_f32_16x16x32_bf16 v[44:47], v[140:143], v[180:183], v[44:47]
	v_mfma_f32_16x16x32_bf16 v[36:39], v[148:151], v[180:183], v[36:39]
	v_mfma_f32_16x16x32_bf16 v[28:31], v[140:143], v[188:191], v[28:31]
	v_mfma_f32_16x16x32_bf16 v[20:23], v[148:151], v[188:191], v[20:23]
	v_mfma_f32_16x16x32_bf16 v[12:15], v[140:143], v[200:203], v[12:15]
	v_mfma_f32_16x16x32_bf16 v[2:5], v[148:151], v[200:203], v[4:7]
	v_mfma_f32_16x16x32_bf16 v[60:63], v[144:147], v[176:179], v[60:63]
	v_mfma_f32_16x16x32_bf16 v[52:55], v[152:155], v[176:179], v[52:55]
	v_mfma_f32_16x16x32_bf16 v[44:47], v[144:147], v[184:187], v[44:47]
	v_mfma_f32_16x16x32_bf16 v[36:39], v[152:155], v[184:187], v[36:39]
	v_mfma_f32_16x16x32_bf16 v[28:31], v[144:147], v[192:195], v[28:31]
	v_mfma_f32_16x16x32_bf16 v[20:23], v[152:155], v[192:195], v[20:23]
	v_mfma_f32_16x16x32_bf16 v[12:15], v[144:147], v[204:207], v[12:15]
	v_mfma_f32_16x16x32_bf16 v[2:5], v[152:155], v[204:207], v[2:5]
	v_mfma_f32_16x16x32_bf16 v[72:75], v[156:159], v[172:175], v[72:75]
	v_mfma_f32_16x16x32_bf16 v[56:59], v[164:167], v[172:175], v[56:59]
	v_mfma_f32_16x16x32_bf16 v[48:51], v[156:159], v[180:183], v[48:51]
	v_mfma_f32_16x16x32_bf16 v[40:43], v[164:167], v[180:183], v[40:43]
	v_mfma_f32_16x16x32_bf16 v[32:35], v[156:159], v[188:191], v[32:35]
	v_mfma_f32_16x16x32_bf16 v[24:27], v[164:167], v[188:191], v[24:27]
	v_mfma_f32_16x16x32_bf16 v[16:19], v[156:159], v[200:203], v[16:19]
	v_mfma_f32_16x16x32_bf16 v[6:9], v[164:167], v[200:203], v[8:11]
	v_mfma_f32_16x16x32_bf16 v[72:75], v[160:163], v[176:179], v[72:75]
	v_mfma_f32_16x16x32_bf16 v[56:59], v[168:171], v[176:179], v[56:59]
	v_mfma_f32_16x16x32_bf16 v[48:51], v[160:163], v[184:187], v[48:51]
	v_mfma_f32_16x16x32_bf16 v[40:43], v[168:171], v[184:187], v[40:43]
	v_mfma_f32_16x16x32_bf16 v[32:35], v[160:163], v[192:195], v[32:35]
	v_mfma_f32_16x16x32_bf16 v[24:27], v[168:171], v[192:195], v[24:27]
	v_mfma_f32_16x16x32_bf16 v[16:19], v[160:163], v[204:207], v[16:19]
	v_mfma_f32_16x16x32_bf16 v[8:11], v[168:171], v[204:207], v[6:9]
	s_barrier
; #define PG8_WAIT_V(n) asm volatile("s_waitcnt vmcnt(" #n ")" ::: "memory")
; template <class Epi, bool ALIGN_EPI, bool SP2, class Hook>
; __device__ __forceinline__ void gemm_phase(LAS unsigned char* lds, const Gemm g, const StaticOrder& S, const Epi& E, Acc& acc, const bool fresh, const Hook& H, const int wave_id) {
;     ...
;         for (int t = t0; t < nt; t += 2) {
;             const bool last = (t == nt - 2);
;             const Src a1 = cA + (size_t)(t + 1) * kstep;
;             const Src a2 = last ? nA : cA + (size_t)(t + 2) * kstep, b2 = last ? nB : cB + (size_t)(t + 2) * kstep;
;             const Src a3 = a2 + kstep, b3 = b2 + kstep;
;             if (last && has_next) H(nxt);
;             if constexpr (SP2) {
;             PG8_TRIP_SP2(PG8_WAIT_V(8));
	s_setprio 0
	v_add_u32_e32 v140, 0x18000, v136
	v_add_u32_e32 v141, 0x1c000, v136
	ds_read_b128 v[142:145], v140
	ds_read_b128 v[146:149], v140 offset:1024
	ds_read_b128 v[150:153], v140 offset:2048
	ds_read_b128 v[154:157], v140 offset:3072
	ds_read_b128 v[158:161], v141
	ds_read_b128 v[162:165], v141 offset:1024
	ds_read_b128 v[166:169], v141 offset:2048
	ds_read_b128 v[170:173], v141 offset:3072
	s_add_i32 s59, s59, 0x40000
	s_mov_b32 m0, s37
	ds_read_b128 v[174:177], v137 offset:32768
	ds_read_b128 v[178:181], v137 offset:33792
	ds_read_b128 v[182:185], v137 offset:34816
	ds_read_b128 v[186:189], v137 offset:35840
	ds_read_b128 v[190:193], v137 offset:36864
	ds_read_b128 v[194:197], v137 offset:37888
	ds_read_b128 v[200:203], v137 offset:38912
	ds_read_b128 v[204:207], v137 offset:39936
	buffer_load_dwordx4 v132, s[20:23], s59 offen lds
	s_mov_b32 m0, s38
	s_nop 0
	buffer_load_dwordx4 v134, s[20:23], s59 offen lds
	s_waitcnt vmcnt(8)
	s_setprio 1
	s_barrier
	s_waitcnt lgkmcnt(0)
	v_mfma_f32_16x16x32_bf16 v[124:127], v[142:145], v[174:177], v[124:127]
	v_mfma_f32_16x16x32_bf16 v[116:119], v[150:153], v[174:177], v[116:119]
	v_mfma_f32_16x16x32_bf16 v[108:111], v[142:145], v[182:185], v[108:111]
	v_mfma_f32_16x16x32_bf16 v[100:103], v[150:153], v[182:185], v[100:103]
	v_mfma_f32_16x16x32_bf16 v[92:95], v[142:145], v[190:193], v[92:95]
	v_mfma_f32_16x16x32_bf16 v[84:87], v[150:153], v[190:193], v[84:87]
	v_mfma_f32_16x16x32_bf16 v[76:79], v[142:145], v[200:203], v[76:79]
	v_mfma_f32_16x16x32_bf16 v[64:67], v[150:153], v[200:203], v[64:67]
	v_mfma_f32_16x16x32_bf16 v[124:127], v[146:149], v[178:181], v[124:127]
	v_mfma_f32_16x16x32_bf16 v[116:119], v[154:157], v[178:181], v[116:119]
	v_mfma_f32_16x16x32_bf16 v[108:111], v[146:149], v[186:189], v[108:111]
	v_mfma_f32_16x16x32_bf16 v[100:103], v[154:157], v[186:189], v[100:103]
	v_mfma_f32_16x16x32_bf16 v[92:95], v[146:149], v[194:197], v[92:95]
	v_mfma_f32_16x16x32_bf16 v[84:87], v[154:157], v[194:197], v[84:87]
	v_mfma_f32_16x16x32_bf16 v[76:79], v[146:149], v[204:207], v[76:79]
	v_mfma_f32_16x16x32_bf16 v[64:67], v[154:157], v[204:207], v[64:67]
	v_mfma_f32_16x16x32_bf16 v[128:131], v[158:161], v[174:177], v[128:131]
	v_mfma_f32_16x16x32_bf16 v[120:123], v[166:169], v[174:177], v[120:123]
	v_mfma_f32_16x16x32_bf16 v[112:115], v[158:161], v[182:185], v[112:115]
	v_mfma_f32_16x16x32_bf16 v[104:107], v[166:169], v[182:185], v[104:107]
	v_mfma_f32_16x16x32_bf16 v[96:99], v[158:161], v[190:193], v[96:99]
	v_mfma_f32_16x16x32_bf16 v[88:91], v[166:169], v[190:193], v[88:91]
	v_mfma_f32_16x16x32_bf16 v[80:83], v[158:161], v[200:203], v[80:83]
	v_mfma_f32_16x16x32_bf16 v[68:71], v[166:169], v[200:203], v[68:71]
	v_mfma_f32_16x16x32_bf16 v[128:131], v[162:165], v[178:181], v[128:131]
	v_mfma_f32_16x16x32_bf16 v[120:123], v[170:173], v[178:181], v[120:123]
	v_mfma_f32_16x16x32_bf16 v[112:115], v[162:165], v[186:189], v[112:115]
	v_mfma_f32_16x16x32_bf16 v[104:107], v[170:173], v[186:189], v[104:107]
	v_mfma_f32_16x16x32_bf16 v[96:99], v[162:165], v[194:197], v[96:99]
	v_mfma_f32_16x16x32_bf16 v[88:91], v[170:173], v[194:197], v[88:91]
	v_mfma_f32_16x16x32_bf16 v[80:83], v[162:165], v[204:207], v[80:83]
	v_mfma_f32_16x16x32_bf16 v[68:71], v[170:173], v[204:207], v[68:71]
	s_barrier
	s_setprio 0
	s_mov_b32 m0, s39
	s_or_b32 s59, s57, 0x80
	ds_read_b128 v[174:177], v137 offset:49152
	ds_read_b128 v[178:181], v137 offset:50176
	ds_read_b128 v[182:185], v137 offset:51200
	ds_read_b128 v[186:189], v137 offset:52224
	ds_read_b128 v[190:193], v137 offset:53248
	ds_read_b128 v[194:197], v137 offset:54272
	ds_read_b128 v[200:203], v137 offset:55296
	ds_read_b128 v[204:207], v137 offset:56320
	buffer_load_dwordx4 v133, s[16:19], s59 offen lds
	s_mov_b32 m0, s40
	s_add_i32 s57, s57, 0x40080
	buffer_load_dwordx4 v135, s[16:19], s59 offen lds
	s_mov_b32 m0, s43
	s_nop 0
	buffer_load_dwordx4 v133, s[16:19], s57 offen lds
	s_mov_b32 m0, s42
	s_nop 0
	buffer_load_dwordx4 v135, s[16:19], s57 offen lds
	s_mov_b32 m0, s41
	s_nop 0
	buffer_load_dwordx4 v132, s[20:23], s58 offen lds
	s_mov_b32 m0, s33
	s_nop 0
	buffer_load_dwordx4 v134, s[20:23], s58 offen lds
	s_waitcnt vmcnt(8)
	s_setprio 1
	s_barrier
	s_waitcnt lgkmcnt(0)
	v_mfma_f32_16x16x32_bf16 v[60:63], v[142:145], v[174:177], v[60:63]
	v_mfma_f32_16x16x32_bf16 v[52:55], v[150:153], v[174:177], v[52:55]
	v_mfma_f32_16x16x32_bf16 v[44:47], v[142:145], v[182:185], v[44:47]
	v_mfma_f32_16x16x32_bf16 v[36:39], v[150:153], v[182:185], v[36:39]
	v_mfma_f32_16x16x32_bf16 v[28:31], v[142:145], v[190:193], v[28:31]
	v_mfma_f32_16x16x32_bf16 v[20:23], v[150:153], v[190:193], v[20:23]
	v_mfma_f32_16x16x32_bf16 v[12:15], v[142:145], v[200:203], v[12:15]
	v_mfma_f32_16x16x32_bf16 v[2:5], v[150:153], v[200:203], v[2:5]
	v_mfma_f32_16x16x32_bf16 v[60:63], v[146:149], v[178:181], v[60:63]
	v_mfma_f32_16x16x32_bf16 v[52:55], v[154:157], v[178:181], v[52:55]
	v_mfma_f32_16x16x32_bf16 v[44:47], v[146:149], v[186:189], v[44:47]
	v_mfma_f32_16x16x32_bf16 v[36:39], v[154:157], v[186:189], v[36:39]
	v_mfma_f32_16x16x32_bf16 v[28:31], v[146:149], v[194:197], v[28:31]
	v_mfma_f32_16x16x32_bf16 v[20:23], v[154:157], v[194:197], v[20:23]
	v_mfma_f32_16x16x32_bf16 v[12:15], v[146:149], v[204:207], v[12:15]
	v_mfma_f32_16x16x32_bf16 v[4:7], v[154:157], v[204:207], v[2:5]
	v_mfma_f32_16x16x32_bf16 v[72:75], v[158:161], v[174:177], v[72:75]
	v_mfma_f32_16x16x32_bf16 v[56:59], v[166:169], v[174:177], v[56:59]
	v_mfma_f32_16x16x32_bf16 v[48:51], v[158:161], v[182:185], v[48:51]
	v_mfma_f32_16x16x32_bf16 v[40:43], v[166:169], v[182:185], v[40:43]
	v_mfma_f32_16x16x32_bf16 v[32:35], v[158:161], v[190:193], v[32:35]
	v_mfma_f32_16x16x32_bf16 v[24:27], v[166:169], v[190:193], v[24:27]
	v_mfma_f32_16x16x32_bf16 v[16:19], v[158:161], v[200:203], v[16:19]
	v_mfma_f32_16x16x32_bf16 v[8:11], v[166:169], v[200:203], v[8:11]
	v_mfma_f32_16x16x32_bf16 v[72:75], v[162:165], v[178:181], v[72:75]
	v_mfma_f32_16x16x32_bf16 v[56:59], v[170:173], v[178:181], v[56:59]
	v_mfma_f32_16x16x32_bf16 v[48:51], v[162:165], v[186:189], v[48:51]
	v_mfma_f32_16x16x32_bf16 v[40:43], v[170:173], v[186:189], v[40:43]
	v_mfma_f32_16x16x32_bf16 v[32:35], v[162:165], v[194:197], v[32:35]
	v_mfma_f32_16x16x32_bf16 v[24:27], v[170:173], v[194:197], v[24:27]
	v_mfma_f32_16x16x32_bf16 v[16:19], v[162:165], v[204:207], v[16:19]
	v_mfma_f32_16x16x32_bf16 v[8:11], v[170:173], v[204:207], v[8:11]
	s_barrier
	s_setprio 0
	s_add_i32 s54, s54, 2
	s_addk_i32 s55, 0x100
	s_addk_i32 s56, 0x100
	s_cmp_gt_u32 s54, 13
	s_cbranch_scc0 .LBB0_1461
	v_readlane_b32 s12, v251, 45
	v_readlane_b32 s13, v251, 46
	s_and_b64 vcc, exec, s[12:13]
	s_cbranch_vccz .LBB0_1464
	s_barrier

; template <class Epi, bool ALIGN_EPI, bool SP2, class Hook>
; __device__ __forceinline__ void gemm_phase(LAS unsigned char* lds, const Gemm g, const StaticOrder& S, const Epi& E, Acc& acc, const bool fresh, const Hook& H, const int wave_id) {
;     ...
;         for (int t = t0; t < nt; t += 2) {
;             const bool last = (t == nt - 2);
;             const Src a1 = cA + (size_t)(t + 1) * kstep;
;             const Src a2 = last ? nA : cA + (size_t)(t + 2) * kstep, b2 = last ? nB : cB + (size_t)(t + 2) * kstep;
;             const Src a3 = a2 + kstep, b3 = b2 + kstep;
;             if (last && has_next) H(nxt);
.LBB0_1572:
	v_add_u32_e32 v142, 0x10000, v161
	v_add_u32_e32 v163, 0x14000, v161
	ds_read_b128 v[130:133], v142
	ds_read_b128 v[134:137], v142 offset:1024
	ds_read_b128 v[138:141], v142 offset:2048
	ds_read_b128 v[142:145], v142 offset:3072
	ds_read_b128 v[146:149], v163
	ds_read_b128 v[150:153], v163 offset:1024
	ds_read_b128 v[154:157], v163 offset:2048
	ds_read_b128 v[164:167], v163 offset:3072
	s_add_i32 s16, s2, 0xfff40080
	s_cmp_eq_u32 s61, 40
	s_cselect_b32 s64, s57, s16
	s_cselect_b32 s17, s35, s9
	s_cselect_b32 s16, s34, s8
	s_cselect_b32 s19, s51, s53
	s_cselect_b32 s18, s50, s52
	s_cselect_b32 s62, s58, s3
	s_cselect_b32 s20, s10, s12
	s_cselect_b32 s21, s11, s13
	s_cselect_b32 s22, s30, s14
	s_cselect_b32 s23, s31, s15
	s_or_b32 s63, s64, 0x80
	s_mov_b32 m0, s45
	ds_read_b128 v[168:171], v162
	ds_read_b128 v[172:175], v162 offset:1024
	ds_read_b128 v[176:179], v162 offset:2048
	ds_read_b128 v[180:183], v162 offset:3072
	ds_read_b128 v[184:187], v162 offset:4096
	ds_read_b128 v[188:191], v162 offset:5120
	ds_read_b128 v[192:195], v162 offset:6144
	ds_read_b128 v[200:203], v162 offset:7168
	buffer_load_dwordx4 v0, s[12:15], s2 offen lds
	s_mov_b32 m0, s46
	s_nop 0
	buffer_load_dwordx4 v159, s[12:15], s2 offen lds
	s_waitcnt vmcnt(8)
	s_setprio 1
	s_barrier
	s_waitcnt lgkmcnt(0)
	v_mfma_f32_16x16x32_bf16 v[126:129], v[130:133], v[168:171], v[126:129]
	v_mfma_f32_16x16x32_bf16 v[122:125], v[138:141], v[168:171], v[122:125]
	v_mfma_f32_16x16x32_bf16 v[110:113], v[130:133], v[176:179], v[110:113]
	v_mfma_f32_16x16x32_bf16 v[106:109], v[138:141], v[176:179], v[106:109]
	v_mfma_f32_16x16x32_bf16 v[94:97], v[130:133], v[184:187], v[94:97]
	v_mfma_f32_16x16x32_bf16 v[90:93], v[138:141], v[184:187], v[90:93]
	v_mfma_f32_16x16x32_bf16 v[78:81], v[130:133], v[192:195], v[78:81]
	v_mfma_f32_16x16x32_bf16 v[74:77], v[138:141], v[192:195], v[74:77]
	v_mfma_f32_16x16x32_bf16 v[126:129], v[134:137], v[172:175], v[126:129]
	v_mfma_f32_16x16x32_bf16 v[122:125], v[142:145], v[172:175], v[122:125]
	v_mfma_f32_16x16x32_bf16 v[110:113], v[134:137], v[180:183], v[110:113]
	v_mfma_f32_16x16x32_bf16 v[106:109], v[142:145], v[180:183], v[106:109]
	v_mfma_f32_16x16x32_bf16 v[94:97], v[134:137], v[188:191], v[94:97]
	v_mfma_f32_16x16x32_bf16 v[90:93], v[142:145], v[188:191], v[90:93]
	v_mfma_f32_16x16x32_bf16 v[78:81], v[134:137], v[200:203], v[78:81]
	v_mfma_f32_16x16x32_bf16 v[74:77], v[142:145], v[200:203], v[74:77]
	v_mfma_f32_16x16x32_bf16 v[118:121], v[146:149], v[168:171], v[118:121]
	v_mfma_f32_16x16x32_bf16 v[114:117], v[154:157], v[168:171], v[114:117]
	v_mfma_f32_16x16x32_bf16 v[102:105], v[146:149], v[176:179], v[102:105]
	v_mfma_f32_16x16x32_bf16 v[98:101], v[154:157], v[176:179], v[98:101]
	v_mfma_f32_16x16x32_bf16 v[86:89], v[146:149], v[184:187], v[86:89]
	v_mfma_f32_16x16x32_bf16 v[82:85], v[154:157], v[184:187], v[82:85]
	v_mfma_f32_16x16x32_bf16 v[70:73], v[146:149], v[192:195], v[70:73]
	v_mfma_f32_16x16x32_bf16 v[66:69], v[154:157], v[192:195], v[66:69]
	v_mfma_f32_16x16x32_bf16 v[118:121], v[150:153], v[172:175], v[118:121]
	v_mfma_f32_16x16x32_bf16 v[114:117], v[164:167], v[172:175], v[114:117]
	v_mfma_f32_16x16x32_bf16 v[102:105], v[150:153], v[180:183], v[102:105]
	v_mfma_f32_16x16x32_bf16 v[98:101], v[164:167], v[180:183], v[98:101]
	v_mfma_f32_16x16x32_bf16 v[86:89], v[150:153], v[188:191], v[86:89]
	v_mfma_f32_16x16x32_bf16 v[82:85], v[164:167], v[188:191], v[82:85]
	v_mfma_f32_16x16x32_bf16 v[70:73], v[150:153], v[200:203], v[70:73]
	v_mfma_f32_16x16x32_bf16 v[66:69], v[164:167], v[200:203], v[66:69]
	s_barrier
	s_setprio 0
	s_mov_b32 m0, s92
	ds_read_b128 v[168:171], v162 offset:16384
	ds_read_b128 v[172:175], v162 offset:17408
	ds_read_b128 v[176:179], v162 offset:18432
	ds_read_b128 v[180:183], v162 offset:19456
	ds_read_b128 v[184:187], v162 offset:20480
	ds_read_b128 v[188:191], v162 offset:21504
	ds_read_b128 v[192:195], v162 offset:22528
	ds_read_b128 v[200:203], v162 offset:23552
	buffer_load_dwordx4 v158, s[16:19], s62 offen lds
	s_mov_b32 m0, s93
	s_add_i32 s65, s62, 0xb0000
	buffer_load_dwordx4 v160, s[16:19], s62 offen lds
	s_mov_b32 m0, s94
	s_nop 0
	buffer_load_dwordx4 v158, s[16:19], s65 offen lds
	s_mov_b32 m0, s95
	s_nop 0
	buffer_load_dwordx4 v160, s[16:19], s65 offen lds
	s_mov_b32 m0, s44
	s_nop 0
	buffer_load_dwordx4 v0, s[20:23], s64 offen lds
	s_mov_b32 m0, s36
	s_nop 0
	buffer_load_dwordx4 v159, s[20:23], s64 offen lds
	s_waitcnt vmcnt(8)
	s_setprio 1
	s_barrier
	s_waitcnt lgkmcnt(0)
	v_mfma_f32_16x16x32_bf16 v[62:65], v[130:133], v[168:171], v[62:65]
	v_mfma_f32_16x16x32_bf16 v[58:61], v[138:141], v[168:171], v[58:61]
	v_mfma_f32_16x16x32_bf16 v[46:49], v[130:133], v[176:179], v[46:49]
	v_mfma_f32_16x16x32_bf16 v[42:45], v[138:141], v[176:179], v[42:45]
	v_mfma_f32_16x16x32_bf16 v[30:33], v[130:133], v[184:187], v[30:33]
	v_mfma_f32_16x16x32_bf16 v[26:29], v[138:141], v[184:187], v[26:29]
	v_mfma_f32_16x16x32_bf16 v[14:17], v[130:133], v[192:195], v[14:17]
	v_mfma_f32_16x16x32_bf16 v[10:13], v[138:141], v[192:195], v[10:13]
	v_mfma_f32_16x16x32_bf16 v[62:65], v[134:137], v[172:175], v[62:65]
	v_mfma_f32_16x16x32_bf16 v[58:61], v[142:145], v[172:175], v[58:61]
	v_mfma_f32_16x16x32_bf16 v[46:49], v[134:137], v[180:183], v[46:49]
	v_mfma_f32_16x16x32_bf16 v[42:45], v[142:145], v[180:183], v[42:45]
	v_mfma_f32_16x16x32_bf16 v[30:33], v[134:137], v[188:191], v[30:33]
	v_mfma_f32_16x16x32_bf16 v[26:29], v[142:145], v[188:191], v[26:29]
	v_mfma_f32_16x16x32_bf16 v[14:17], v[134:137], v[200:203], v[14:17]
	v_mfma_f32_16x16x32_bf16 v[10:13], v[142:145], v[200:203], v[10:13]
	v_mfma_f32_16x16x32_bf16 v[54:57], v[146:149], v[168:171], v[54:57]
	v_mfma_f32_16x16x32_bf16 v[50:53], v[154:157], v[168:171], v[50:53]
	v_mfma_f32_16x16x32_bf16 v[38:41], v[146:149], v[176:179], v[38:41]
	v_mfma_f32_16x16x32_bf16 v[34:37], v[154:157], v[176:179], v[34:37]
	v_mfma_f32_16x16x32_bf16 v[22:25], v[146:149], v[184:187], v[22:25]
	v_mfma_f32_16x16x32_bf16 v[18:21], v[154:157], v[184:187], v[18:21]
	v_mfma_f32_16x16x32_bf16 v[6:9], v[146:149], v[192:195], v[6:9]
	v_mfma_f32_16x16x32_bf16 v[2:5], v[154:157], v[192:195], v[2:5]
	v_mfma_f32_16x16x32_bf16 v[54:57], v[150:153], v[172:175], v[54:57]
	v_mfma_f32_16x16x32_bf16 v[50:53], v[164:167], v[172:175], v[50:53]
	v_mfma_f32_16x16x32_bf16 v[38:41], v[150:153], v[180:183], v[38:41]
	v_mfma_f32_16x16x32_bf16 v[34:37], v[164:167], v[180:183], v[34:37]
	v_mfma_f32_16x16x32_bf16 v[22:25], v[150:153], v[188:191], v[22:25]
	v_mfma_f32_16x16x32_bf16 v[18:21], v[164:167], v[188:191], v[18:21]
	v_mfma_f32_16x16x32_bf16 v[6:9], v[150:153], v[200:203], v[6:9]
	v_mfma_f32_16x16x32_bf16 v[2:5], v[164:167], v[200:203], v[2:5]
	s_barrier
; #define PG8_WAIT_V(n) asm volatile("s_waitcnt vmcnt(" #n ")" ::: "memory")
; template <class Epi, bool ALIGN_EPI, bool SP2, class Hook>
; __device__ __forceinline__ void gemm_phase(LAS unsigned char* lds, const Gemm g, const StaticOrder& S, const Epi& E, Acc& acc, const bool fresh, const Hook& H, const int wave_id) {
;     ...
;         for (int t = t0; t < nt; t += 2) {
;             const bool last = (t == nt - 2);
;             const Src a1 = cA + (size_t)(t + 1) * kstep;
;             const Src a2 = last ? nA : cA + (size_t)(t + 2) * kstep, b2 = last ? nB : cB + (size_t)(t + 2) * kstep;
;             const Src a3 = a2 + kstep, b3 = b2 + kstep;
;             if (last && has_next) H(nxt);
;             if constexpr (SP2) {
;             PG8_TRIP_SP2(PG8_WAIT_V(8));
	s_setprio 0
	v_add_u32_e32 v142, 0x18000, v161
	v_add_u32_e32 v163, 0x1c000, v161
	ds_read_b128 v[130:133], v142
	ds_read_b128 v[134:137], v142 offset:1024
	ds_read_b128 v[138:141], v142 offset:2048
	ds_read_b128 v[142:145], v142 offset:3072
	ds_read_b128 v[146:149], v163
	ds_read_b128 v[150:153], v163 offset:1024
	ds_read_b128 v[154:157], v163 offset:2048
	ds_read_b128 v[164:167], v163 offset:3072
	s_add_i32 s64, s64, 0xc0000
	s_mov_b32 m0, s37
	ds_read_b128 v[168:171], v162 offset:32768
	ds_read_b128 v[172:175], v162 offset:33792
	ds_read_b128 v[176:179], v162 offset:34816
	ds_read_b128 v[180:183], v162 offset:35840
	ds_read_b128 v[184:187], v162 offset:36864
	ds_read_b128 v[188:191], v162 offset:37888
	ds_read_b128 v[192:195], v162 offset:38912
	ds_read_b128 v[200:203], v162 offset:39936
	buffer_load_dwordx4 v0, s[20:23], s64 offen lds
	s_mov_b32 m0, s38
	s_nop 0
	buffer_load_dwordx4 v159, s[20:23], s64 offen lds
	s_waitcnt vmcnt(8)
	s_setprio 1
	s_barrier
	s_waitcnt lgkmcnt(0)
	v_mfma_f32_16x16x32_bf16 v[126:129], v[130:133], v[168:171], v[126:129]
	v_mfma_f32_16x16x32_bf16 v[122:125], v[138:141], v[168:171], v[122:125]
	v_mfma_f32_16x16x32_bf16 v[110:113], v[130:133], v[176:179], v[110:113]
	v_mfma_f32_16x16x32_bf16 v[106:109], v[138:141], v[176:179], v[106:109]
	v_mfma_f32_16x16x32_bf16 v[94:97], v[130:133], v[184:187], v[94:97]
	v_mfma_f32_16x16x32_bf16 v[90:93], v[138:141], v[184:187], v[90:93]
	v_mfma_f32_16x16x32_bf16 v[78:81], v[130:133], v[192:195], v[78:81]
	v_mfma_f32_16x16x32_bf16 v[74:77], v[138:141], v[192:195], v[74:77]
	v_mfma_f32_16x16x32_bf16 v[126:129], v[134:137], v[172:175], v[126:129]
	v_mfma_f32_16x16x32_bf16 v[122:125], v[142:145], v[172:175], v[122:125]
	v_mfma_f32_16x16x32_bf16 v[110:113], v[134:137], v[180:183], v[110:113]
	v_mfma_f32_16x16x32_bf16 v[106:109], v[142:145], v[180:183], v[106:109]
	v_mfma_f32_16x16x32_bf16 v[94:97], v[134:137], v[188:191], v[94:97]
	v_mfma_f32_16x16x32_bf16 v[90:93], v[142:145], v[188:191], v[90:93]
	v_mfma_f32_16x16x32_bf16 v[78:81], v[134:137], v[200:203], v[78:81]
	v_mfma_f32_16x16x32_bf16 v[74:77], v[142:145], v[200:203], v[74:77]
	v_mfma_f32_16x16x32_bf16 v[118:121], v[146:149], v[168:171], v[118:121]
	v_mfma_f32_16x16x32_bf16 v[114:117], v[154:157], v[168:171], v[114:117]
	v_mfma_f32_16x16x32_bf16 v[102:105], v[146:149], v[176:179], v[102:105]
	v_mfma_f32_16x16x32_bf16 v[98:101], v[154:157], v[176:179], v[98:101]
	v_mfma_f32_16x16x32_bf16 v[86:89], v[146:149], v[184:187], v[86:89]
	v_mfma_f32_16x16x32_bf16 v[82:85], v[154:157], v[184:187], v[82:85]
	v_mfma_f32_16x16x32_bf16 v[70:73], v[146:149], v[192:195], v[70:73]
	v_mfma_f32_16x16x32_bf16 v[66:69], v[154:157], v[192:195], v[66:69]
	v_mfma_f32_16x16x32_bf16 v[118:121], v[150:153], v[172:175], v[118:121]
	v_mfma_f32_16x16x32_bf16 v[114:117], v[164:167], v[172:175], v[114:117]
	v_mfma_f32_16x16x32_bf16 v[102:105], v[150:153], v[180:183], v[102:105]
	v_mfma_f32_16x16x32_bf16 v[98:101], v[164:167], v[180:183], v[98:101]
	v_mfma_f32_16x16x32_bf16 v[86:89], v[150:153], v[188:191], v[86:89]
	v_mfma_f32_16x16x32_bf16 v[82:85], v[164:167], v[188:191], v[82:85]
	v_mfma_f32_16x16x32_bf16 v[70:73], v[150:153], v[200:203], v[70:73]
	v_mfma_f32_16x16x32_bf16 v[66:69], v[164:167], v[200:203], v[66:69]
	s_barrier
	s_setprio 0
	s_mov_b32 m0, s39
	s_or_b32 s64, s62, 0x80
	ds_read_b128 v[168:171], v162 offset:49152
	ds_read_b128 v[172:175], v162 offset:50176
	ds_read_b128 v[176:179], v162 offset:51200
	ds_read_b128 v[180:183], v162 offset:52224
	ds_read_b128 v[184:187], v162 offset:53248
	ds_read_b128 v[188:191], v162 offset:54272
	ds_read_b128 v[192:195], v162 offset:55296
	ds_read_b128 v[200:203], v162 offset:56320
	buffer_load_dwordx4 v158, s[16:19], s64 offen lds
	s_mov_b32 m0, s40
	s_add_i32 s62, s62, 0xb0080
	buffer_load_dwordx4 v160, s[16:19], s64 offen lds
	s_mov_b32 m0, s43
	s_nop 0
	buffer_load_dwordx4 v158, s[16:19], s62 offen lds
	s_mov_b32 m0, s42
	s_nop 0
	buffer_load_dwordx4 v160, s[16:19], s62 offen lds
	s_mov_b32 m0, s41
	s_nop 0
	buffer_load_dwordx4 v0, s[20:23], s63 offen lds
	s_mov_b32 m0, s33
	s_nop 0
	buffer_load_dwordx4 v159, s[20:23], s63 offen lds
	s_waitcnt vmcnt(8)
	s_setprio 1
	s_barrier
	s_waitcnt lgkmcnt(0)
	v_mfma_f32_16x16x32_bf16 v[62:65], v[130:133], v[168:171], v[62:65]
	v_mfma_f32_16x16x32_bf16 v[58:61], v[138:141], v[168:171], v[58:61]
	v_mfma_f32_16x16x32_bf16 v[46:49], v[130:133], v[176:179], v[46:49]
	v_mfma_f32_16x16x32_bf16 v[42:45], v[138:141], v[176:179], v[42:45]
	v_mfma_f32_16x16x32_bf16 v[30:33], v[130:133], v[184:187], v[30:33]
	v_mfma_f32_16x16x32_bf16 v[26:29], v[138:141], v[184:187], v[26:29]
	v_mfma_f32_16x16x32_bf16 v[14:17], v[130:133], v[192:195], v[14:17]
	v_mfma_f32_16x16x32_bf16 v[10:13], v[138:141], v[192:195], v[10:13]
	v_mfma_f32_16x16x32_bf16 v[62:65], v[134:137], v[172:175], v[62:65]
	v_mfma_f32_16x16x32_bf16 v[58:61], v[142:145], v[172:175], v[58:61]
	v_mfma_f32_16x16x32_bf16 v[46:49], v[134:137], v[180:183], v[46:49]
	v_mfma_f32_16x16x32_bf16 v[42:45], v[142:145], v[180:183], v[42:45]
	v_mfma_f32_16x16x32_bf16 v[30:33], v[134:137], v[188:191], v[30:33]
	v_mfma_f32_16x16x32_bf16 v[26:29], v[142:145], v[188:191], v[26:29]
	v_mfma_f32_16x16x32_bf16 v[14:17], v[134:137], v[200:203], v[14:17]
	v_mfma_f32_16x16x32_bf16 v[10:13], v[142:145], v[200:203], v[10:13]
	v_mfma_f32_16x16x32_bf16 v[54:57], v[146:149], v[168:171], v[54:57]
	v_mfma_f32_16x16x32_bf16 v[50:53], v[154:157], v[168:171], v[50:53]
	v_mfma_f32_16x16x32_bf16 v[38:41], v[146:149], v[176:179], v[38:41]
	v_mfma_f32_16x16x32_bf16 v[34:37], v[154:157], v[176:179], v[34:37]
	v_mfma_f32_16x16x32_bf16 v[22:25], v[146:149], v[184:187], v[22:25]
	v_mfma_f32_16x16x32_bf16 v[18:21], v[154:157], v[184:187], v[18:21]
	v_mfma_f32_16x16x32_bf16 v[6:9], v[146:149], v[192:195], v[6:9]
	v_mfma_f32_16x16x32_bf16 v[2:5], v[154:157], v[192:195], v[2:5]
	v_mfma_f32_16x16x32_bf16 v[54:57], v[150:153], v[172:175], v[54:57]
	v_mfma_f32_16x16x32_bf16 v[50:53], v[164:167], v[172:175], v[50:53]
	v_mfma_f32_16x16x32_bf16 v[38:41], v[150:153], v[180:183], v[38:41]
	v_mfma_f32_16x16x32_bf16 v[34:37], v[164:167], v[180:183], v[34:37]
	v_mfma_f32_16x16x32_bf16 v[22:25], v[150:153], v[188:191], v[22:25]
	v_mfma_f32_16x16x32_bf16 v[18:21], v[164:167], v[188:191], v[18:21]
	v_mfma_f32_16x16x32_bf16 v[6:9], v[150:153], v[200:203], v[6:9]
	v_mfma_f32_16x16x32_bf16 v[2:5], v[164:167], v[200:203], v[2:5]
	s_barrier
	s_setprio 0
	s_add_i32 s61, s61, 2
	s_addk_i32 s2, 0x100
	s_addk_i32 s3, 0x100
	s_cmp_gt_u32 s61, 41
	s_cbranch_scc0 .LBB0_1572
	v_readlane_b32 s2, v251, 45
	v_readlane_b32 s3, v251, 46
	s_and_b64 vcc, exec, s[2:3]
	s_cbranch_vccz .LBB0_1575
	s_barrier

; template <class Epi, bool ALIGN_EPI, bool SP2, class Hook>
; __device__ __forceinline__ void gemm_phase(LAS unsigned char* lds, const Gemm g, const StaticOrder& S, const Epi& E, Acc& acc, const bool fresh, const Hook& H, const int wave_id) {
;     ...
;         for (int t = t0; t < nt; t += 2) {
;             const bool last = (t == nt - 2);
;             const Src a1 = cA + (size_t)(t + 1) * kstep;
;             const Src a2 = last ? nA : cA + (size_t)(t + 2) * kstep, b2 = last ? nB : cB + (size_t)(t + 2) * kstep;
;             const Src a3 = a2 + kstep, b3 = b2 + kstep;
;             if (last && has_next) H(nxt);
.LBB0_1614:
	v_add_u32_e32 v0, 0x10000, v172
	ds_read_b128 v[130:133], v0
	ds_read_b128 v[134:137], v0 offset:1024
	ds_read_b128 v[138:141], v0 offset:2048
	ds_read_b128 v[142:145], v0 offset:3072
	v_add_u32_e32 v0, 0x14000, v172
	ds_read_b128 v[146:149], v0
	ds_read_b128 v[150:153], v0 offset:1024
	ds_read_b128 v[154:157], v0 offset:2048
	ds_read_b128 v[158:161], v0 offset:3072
	s_add_i32 s12, s2, 0xfff40080
	s_cmp_eq_u32 s59, 40
	s_cselect_b32 s62, s55, s12
	s_cselect_b32 s13, s31, s77
	s_cselect_b32 s12, s30, s76
	s_cselect_b32 s15, s35, s51
	s_cselect_b32 s14, s34, s50
	s_cselect_b32 s60, s56, s3
	s_cselect_b32 s16, s20, s8
	s_cselect_b32 s17, s21, s9
	s_cselect_b32 s18, s22, s10
	s_cselect_b32 s19, s23, s11
	s_or_b32 s61, s62, 0x80
	s_mov_b32 m0, s45
	ds_read_b128 v[162:165], v173
	ds_read_b128 v[174:177], v173 offset:1024
	ds_read_b128 v[178:181], v173 offset:2048
	ds_read_b128 v[182:185], v173 offset:3072
	ds_read_b128 v[186:189], v173 offset:4096
	ds_read_b128 v[190:193], v173 offset:5120
	ds_read_b128 v[194:197], v173 offset:6144
	ds_read_b128 v[200:203], v173 offset:7168
	buffer_load_dwordx4 v168, s[8:11], s2 offen lds
	s_mov_b32 m0, s46
	s_nop 0
	buffer_load_dwordx4 v170, s[8:11], s2 offen lds
	s_waitcnt vmcnt(8)
	s_setprio 1
	s_barrier
	s_waitcnt lgkmcnt(0)
	v_mfma_f32_16x16x32_bf16 v[126:129], v[130:133], v[162:165], v[126:129]
	v_mfma_f32_16x16x32_bf16 v[122:125], v[138:141], v[162:165], v[122:125]
	v_mfma_f32_16x16x32_bf16 v[110:113], v[130:133], v[178:181], v[110:113]
	v_mfma_f32_16x16x32_bf16 v[106:109], v[138:141], v[178:181], v[106:109]
	v_mfma_f32_16x16x32_bf16 v[94:97], v[130:133], v[186:189], v[94:97]
	v_mfma_f32_16x16x32_bf16 v[90:93], v[138:141], v[186:189], v[90:93]
	v_mfma_f32_16x16x32_bf16 v[78:81], v[130:133], v[194:197], v[78:81]
	v_mfma_f32_16x16x32_bf16 v[74:77], v[138:141], v[194:197], v[74:77]
	v_mfma_f32_16x16x32_bf16 v[126:129], v[134:137], v[174:177], v[126:129]
	v_mfma_f32_16x16x32_bf16 v[122:125], v[142:145], v[174:177], v[122:125]
	v_mfma_f32_16x16x32_bf16 v[110:113], v[134:137], v[182:185], v[110:113]
	v_mfma_f32_16x16x32_bf16 v[106:109], v[142:145], v[182:185], v[106:109]
	v_mfma_f32_16x16x32_bf16 v[94:97], v[134:137], v[190:193], v[94:97]
	v_mfma_f32_16x16x32_bf16 v[90:93], v[142:145], v[190:193], v[90:93]
	v_mfma_f32_16x16x32_bf16 v[78:81], v[134:137], v[200:203], v[78:81]
	v_mfma_f32_16x16x32_bf16 v[74:77], v[142:145], v[200:203], v[74:77]
	v_mfma_f32_16x16x32_bf16 v[118:121], v[146:149], v[162:165], v[118:121]
	v_mfma_f32_16x16x32_bf16 v[114:117], v[154:157], v[162:165], v[114:117]
	v_mfma_f32_16x16x32_bf16 v[102:105], v[146:149], v[178:181], v[102:105]
	v_mfma_f32_16x16x32_bf16 v[98:101], v[154:157], v[178:181], v[98:101]
	v_mfma_f32_16x16x32_bf16 v[86:89], v[146:149], v[186:189], v[86:89]
	v_mfma_f32_16x16x32_bf16 v[82:85], v[154:157], v[186:189], v[82:85]
	v_mfma_f32_16x16x32_bf16 v[70:73], v[146:149], v[194:197], v[70:73]
	v_mfma_f32_16x16x32_bf16 v[66:69], v[154:157], v[194:197], v[66:69]
	v_mfma_f32_16x16x32_bf16 v[118:121], v[150:153], v[174:177], v[118:121]
	v_mfma_f32_16x16x32_bf16 v[114:117], v[158:161], v[174:177], v[114:117]
	v_mfma_f32_16x16x32_bf16 v[102:105], v[150:153], v[182:185], v[102:105]
	v_mfma_f32_16x16x32_bf16 v[98:101], v[158:161], v[182:185], v[98:101]
	v_mfma_f32_16x16x32_bf16 v[86:89], v[150:153], v[190:193], v[86:89]
	v_mfma_f32_16x16x32_bf16 v[82:85], v[158:161], v[190:193], v[82:85]
	v_mfma_f32_16x16x32_bf16 v[70:73], v[150:153], v[200:203], v[70:73]
	v_mfma_f32_16x16x32_bf16 v[66:69], v[158:161], v[200:203], v[66:69]
	s_barrier
	s_setprio 0
	s_mov_b32 m0, s92
	ds_read_b128 v[162:165], v173 offset:16384
	ds_read_b128 v[174:177], v173 offset:17408
	ds_read_b128 v[178:181], v173 offset:18432
	ds_read_b128 v[182:185], v173 offset:19456
	ds_read_b128 v[186:189], v173 offset:20480
	ds_read_b128 v[190:193], v173 offset:21504
	ds_read_b128 v[194:197], v173 offset:22528
	ds_read_b128 v[200:203], v173 offset:23552
	buffer_load_dwordx4 v169, s[12:15], s60 offen lds
	s_mov_b32 m0, s93
	s_add_i32 s63, s60, 0xb0000
	buffer_load_dwordx4 v171, s[12:15], s60 offen lds
	s_mov_b32 m0, s94
	s_nop 0
	buffer_load_dwordx4 v169, s[12:15], s63 offen lds
	s_mov_b32 m0, s95
	s_nop 0
	buffer_load_dwordx4 v171, s[12:15], s63 offen lds
	s_mov_b32 m0, s44
	s_nop 0
	buffer_load_dwordx4 v168, s[16:19], s62 offen lds
	s_mov_b32 m0, s36
	s_nop 0
	buffer_load_dwordx4 v170, s[16:19], s62 offen lds
	s_waitcnt vmcnt(8)
	s_setprio 1
	s_barrier
	s_waitcnt lgkmcnt(0)
	v_mfma_f32_16x16x32_bf16 v[62:65], v[130:133], v[162:165], v[62:65]
	v_mfma_f32_16x16x32_bf16 v[58:61], v[138:141], v[162:165], v[58:61]
	v_mfma_f32_16x16x32_bf16 v[46:49], v[130:133], v[178:181], v[46:49]
	v_mfma_f32_16x16x32_bf16 v[42:45], v[138:141], v[178:181], v[42:45]
	v_mfma_f32_16x16x32_bf16 v[30:33], v[130:133], v[186:189], v[30:33]
	v_mfma_f32_16x16x32_bf16 v[26:29], v[138:141], v[186:189], v[26:29]
	v_mfma_f32_16x16x32_bf16 v[14:17], v[130:133], v[194:197], v[14:17]
	v_mfma_f32_16x16x32_bf16 v[10:13], v[138:141], v[194:197], v[10:13]
	v_mfma_f32_16x16x32_bf16 v[62:65], v[134:137], v[174:177], v[62:65]
	v_mfma_f32_16x16x32_bf16 v[58:61], v[142:145], v[174:177], v[58:61]
	v_mfma_f32_16x16x32_bf16 v[46:49], v[134:137], v[182:185], v[46:49]
	v_mfma_f32_16x16x32_bf16 v[42:45], v[142:145], v[182:185], v[42:45]
	v_mfma_f32_16x16x32_bf16 v[30:33], v[134:137], v[190:193], v[30:33]
	v_mfma_f32_16x16x32_bf16 v[26:29], v[142:145], v[190:193], v[26:29]
	v_mfma_f32_16x16x32_bf16 v[14:17], v[134:137], v[200:203], v[14:17]
	v_mfma_f32_16x16x32_bf16 v[10:13], v[142:145], v[200:203], v[10:13]
	v_mfma_f32_16x16x32_bf16 v[54:57], v[146:149], v[162:165], v[54:57]
	v_mfma_f32_16x16x32_bf16 v[50:53], v[154:157], v[162:165], v[50:53]
	v_mfma_f32_16x16x32_bf16 v[38:41], v[146:149], v[178:181], v[38:41]
	v_mfma_f32_16x16x32_bf16 v[34:37], v[154:157], v[178:181], v[34:37]
	v_mfma_f32_16x16x32_bf16 v[22:25], v[146:149], v[186:189], v[22:25]
	v_mfma_f32_16x16x32_bf16 v[18:21], v[154:157], v[186:189], v[18:21]
	v_mfma_f32_16x16x32_bf16 v[6:9], v[146:149], v[194:197], v[6:9]
	v_mfma_f32_16x16x32_bf16 v[2:5], v[154:157], v[194:197], v[2:5]
	v_mfma_f32_16x16x32_bf16 v[54:57], v[150:153], v[174:177], v[54:57]
	v_mfma_f32_16x16x32_bf16 v[50:53], v[158:161], v[174:177], v[50:53]
	v_mfma_f32_16x16x32_bf16 v[38:41], v[150:153], v[182:185], v[38:41]
	v_mfma_f32_16x16x32_bf16 v[34:37], v[158:161], v[182:185], v[34:37]
	v_mfma_f32_16x16x32_bf16 v[22:25], v[150:153], v[190:193], v[22:25]
	v_mfma_f32_16x16x32_bf16 v[18:21], v[158:161], v[190:193], v[18:21]
	v_mfma_f32_16x16x32_bf16 v[6:9], v[150:153], v[200:203], v[6:9]
	v_mfma_f32_16x16x32_bf16 v[2:5], v[158:161], v[200:203], v[2:5]
	s_barrier
; #define PG8_WAIT_V(n) asm volatile("s_waitcnt vmcnt(" #n ")" ::: "memory")
; template <class Epi, bool ALIGN_EPI, bool SP2, class Hook>
; __device__ __forceinline__ void gemm_phase(LAS unsigned char* lds, const Gemm g, const StaticOrder& S, const Epi& E, Acc& acc, const bool fresh, const Hook& H, const int wave_id) {
;     ...
;         for (int t = t0; t < nt; t += 2) {
;             const bool last = (t == nt - 2);
;             const Src a1 = cA + (size_t)(t + 1) * kstep;
;             const Src a2 = last ? nA : cA + (size_t)(t + 2) * kstep, b2 = last ? nB : cB + (size_t)(t + 2) * kstep;
;             const Src a3 = a2 + kstep, b3 = b2 + kstep;
;             if (last && has_next) H(nxt);
;             if constexpr (SP2) {
;             PG8_TRIP_SP2(PG8_WAIT_V(8));
	s_setprio 0
	v_add_u32_e32 v0, 0x18000, v172
	ds_read_b128 v[130:133], v0
	ds_read_b128 v[134:137], v0 offset:1024
	ds_read_b128 v[138:141], v0 offset:2048
	ds_read_b128 v[142:145], v0 offset:3072
	v_add_u32_e32 v0, 0x1c000, v172
	ds_read_b128 v[146:149], v0
	ds_read_b128 v[150:153], v0 offset:1024
	ds_read_b128 v[154:157], v0 offset:2048
	ds_read_b128 v[158:161], v0 offset:3072
	s_add_i32 s62, s62, 0xc0000
	s_mov_b32 m0, s37
	ds_read_b128 v[162:165], v173 offset:32768
	ds_read_b128 v[174:177], v173 offset:33792
	ds_read_b128 v[178:181], v173 offset:34816
	ds_read_b128 v[182:185], v173 offset:35840
	ds_read_b128 v[186:189], v173 offset:36864
	ds_read_b128 v[190:193], v173 offset:37888
	ds_read_b128 v[194:197], v173 offset:38912
	ds_read_b128 v[200:203], v173 offset:39936
	buffer_load_dwordx4 v168, s[16:19], s62 offen lds
	s_mov_b32 m0, s38
	s_nop 0
	buffer_load_dwordx4 v170, s[16:19], s62 offen lds
	s_waitcnt vmcnt(8)
	s_setprio 1
	s_barrier
	s_waitcnt lgkmcnt(0)
	v_mfma_f32_16x16x32_bf16 v[126:129], v[130:133], v[162:165], v[126:129]
	v_mfma_f32_16x16x32_bf16 v[122:125], v[138:141], v[162:165], v[122:125]
	v_mfma_f32_16x16x32_bf16 v[110:113], v[130:133], v[178:181], v[110:113]
	v_mfma_f32_16x16x32_bf16 v[106:109], v[138:141], v[178:181], v[106:109]
	v_mfma_f32_16x16x32_bf16 v[94:97], v[130:133], v[186:189], v[94:97]
	v_mfma_f32_16x16x32_bf16 v[90:93], v[138:141], v[186:189], v[90:93]
	v_mfma_f32_16x16x32_bf16 v[78:81], v[130:133], v[194:197], v[78:81]
	v_mfma_f32_16x16x32_bf16 v[74:77], v[138:141], v[194:197], v[74:77]
	v_mfma_f32_16x16x32_bf16 v[126:129], v[134:137], v[174:177], v[126:129]
	v_mfma_f32_16x16x32_bf16 v[122:125], v[142:145], v[174:177], v[122:125]
	v_mfma_f32_16x16x32_bf16 v[110:113], v[134:137], v[182:185], v[110:113]
	v_mfma_f32_16x16x32_bf16 v[106:109], v[142:145], v[182:185], v[106:109]
	v_mfma_f32_16x16x32_bf16 v[94:97], v[134:137], v[190:193], v[94:97]
	v_mfma_f32_16x16x32_bf16 v[90:93], v[142:145], v[190:193], v[90:93]
	v_mfma_f32_16x16x32_bf16 v[78:81], v[134:137], v[200:203], v[78:81]
	v_mfma_f32_16x16x32_bf16 v[74:77], v[142:145], v[200:203], v[74:77]
	v_mfma_f32_16x16x32_bf16 v[118:121], v[146:149], v[162:165], v[118:121]
	v_mfma_f32_16x16x32_bf16 v[114:117], v[154:157], v[162:165], v[114:117]
	v_mfma_f32_16x16x32_bf16 v[102:105], v[146:149], v[178:181], v[102:105]
	v_mfma_f32_16x16x32_bf16 v[98:101], v[154:157], v[178:181], v[98:101]
	v_mfma_f32_16x16x32_bf16 v[86:89], v[146:149], v[186:189], v[86:89]
	v_mfma_f32_16x16x32_bf16 v[82:85], v[154:157], v[186:189], v[82:85]
	v_mfma_f32_16x16x32_bf16 v[70:73], v[146:149], v[194:197], v[70:73]
	v_mfma_f32_16x16x32_bf16 v[66:69], v[154:157], v[194:197], v[66:69]
	v_mfma_f32_16x16x32_bf16 v[118:121], v[150:153], v[174:177], v[118:121]
	v_mfma_f32_16x16x32_bf16 v[114:117], v[158:161], v[174:177], v[114:117]
	v_mfma_f32_16x16x32_bf16 v[102:105], v[150:153], v[182:185], v[102:105]
	v_mfma_f32_16x16x32_bf16 v[98:101], v[158:161], v[182:185], v[98:101]
	v_mfma_f32_16x16x32_bf16 v[86:89], v[150:153], v[190:193], v[86:89]
	v_mfma_f32_16x16x32_bf16 v[82:85], v[158:161], v[190:193], v[82:85]
	v_mfma_f32_16x16x32_bf16 v[70:73], v[150:153], v[200:203], v[70:73]
	v_mfma_f32_16x16x32_bf16 v[66:69], v[158:161], v[200:203], v[66:69]
	s_barrier
	s_setprio 0
	s_mov_b32 m0, s39
	s_or_b32 s62, s60, 0x80
	ds_read_b128 v[162:165], v173 offset:49152
	ds_read_b128 v[174:177], v173 offset:50176
	ds_read_b128 v[178:181], v173 offset:51200
	ds_read_b128 v[182:185], v173 offset:52224
	ds_read_b128 v[186:189], v173 offset:53248
	ds_read_b128 v[190:193], v173 offset:54272
	ds_read_b128 v[194:197], v173 offset:55296
	ds_read_b128 v[200:203], v173 offset:56320
	buffer_load_dwordx4 v169, s[12:15], s62 offen lds
	s_mov_b32 m0, s40
	s_add_i32 s60, s60, 0xb0080
	buffer_load_dwordx4 v171, s[12:15], s62 offen lds
	s_mov_b32 m0, s43
	s_nop 0
	buffer_load_dwordx4 v169, s[12:15], s60 offen lds
	s_mov_b32 m0, s42
	s_nop 0
	buffer_load_dwordx4 v171, s[12:15], s60 offen lds
	s_mov_b32 m0, s41
	s_nop 0
	buffer_load_dwordx4 v168, s[16:19], s61 offen lds
	s_mov_b32 m0, s33
	s_nop 0
	buffer_load_dwordx4 v170, s[16:19], s61 offen lds
	s_waitcnt vmcnt(8)
	s_setprio 1
	s_barrier
	s_waitcnt lgkmcnt(0)
	v_mfma_f32_16x16x32_bf16 v[62:65], v[130:133], v[162:165], v[62:65]
	v_mfma_f32_16x16x32_bf16 v[58:61], v[138:141], v[162:165], v[58:61]
	v_mfma_f32_16x16x32_bf16 v[46:49], v[130:133], v[178:181], v[46:49]
	v_mfma_f32_16x16x32_bf16 v[42:45], v[138:141], v[178:181], v[42:45]
	v_mfma_f32_16x16x32_bf16 v[30:33], v[130:133], v[186:189], v[30:33]
	v_mfma_f32_16x16x32_bf16 v[26:29], v[138:141], v[186:189], v[26:29]
	v_mfma_f32_16x16x32_bf16 v[14:17], v[130:133], v[194:197], v[14:17]
	v_mfma_f32_16x16x32_bf16 v[10:13], v[138:141], v[194:197], v[10:13]
	v_mfma_f32_16x16x32_bf16 v[62:65], v[134:137], v[174:177], v[62:65]
	v_mfma_f32_16x16x32_bf16 v[58:61], v[142:145], v[174:177], v[58:61]
	v_mfma_f32_16x16x32_bf16 v[46:49], v[134:137], v[182:185], v[46:49]
	v_mfma_f32_16x16x32_bf16 v[42:45], v[142:145], v[182:185], v[42:45]
	v_mfma_f32_16x16x32_bf16 v[30:33], v[134:137], v[190:193], v[30:33]
	v_mfma_f32_16x16x32_bf16 v[26:29], v[142:145], v[190:193], v[26:29]
	v_mfma_f32_16x16x32_bf16 v[14:17], v[134:137], v[200:203], v[14:17]
	v_mfma_f32_16x16x32_bf16 v[10:13], v[142:145], v[200:203], v[10:13]
	v_mfma_f32_16x16x32_bf16 v[54:57], v[146:149], v[162:165], v[54:57]
	v_mfma_f32_16x16x32_bf16 v[50:53], v[154:157], v[162:165], v[50:53]
	v_mfma_f32_16x16x32_bf16 v[38:41], v[146:149], v[178:181], v[38:41]
	v_mfma_f32_16x16x32_bf16 v[34:37], v[154:157], v[178:181], v[34:37]
	v_mfma_f32_16x16x32_bf16 v[22:25], v[146:149], v[186:189], v[22:25]
	v_mfma_f32_16x16x32_bf16 v[18:21], v[154:157], v[186:189], v[18:21]
	v_mfma_f32_16x16x32_bf16 v[6:9], v[146:149], v[194:197], v[6:9]
	v_mfma_f32_16x16x32_bf16 v[2:5], v[154:157], v[194:197], v[2:5]
	v_mfma_f32_16x16x32_bf16 v[54:57], v[150:153], v[174:177], v[54:57]
	v_mfma_f32_16x16x32_bf16 v[50:53], v[158:161], v[174:177], v[50:53]
	v_mfma_f32_16x16x32_bf16 v[38:41], v[150:153], v[182:185], v[38:41]
	v_mfma_f32_16x16x32_bf16 v[34:37], v[158:161], v[182:185], v[34:37]
	v_mfma_f32_16x16x32_bf16 v[22:25], v[150:153], v[190:193], v[22:25]
	v_mfma_f32_16x16x32_bf16 v[18:21], v[158:161], v[190:193], v[18:21]
	v_mfma_f32_16x16x32_bf16 v[6:9], v[150:153], v[200:203], v[6:9]
	v_mfma_f32_16x16x32_bf16 v[2:5], v[158:161], v[200:203], v[2:5]
	s_barrier
	s_setprio 0
	s_add_i32 s59, s59, 2
	s_addk_i32 s2, 0x100
	s_addk_i32 s3, 0x100
	s_cmp_gt_u32 s59, 41
	s_cbranch_scc0 .LBB0_1614
	v_readlane_b32 s2, v251, 45
	v_readlane_b32 s3, v251, 46
	s_and_b64 vcc, exec, s[2:3]
	s_cbranch_vccz .LBB0_1617
	s_barrier
